# v21: v18 + hyena conv_s2 base twiddles loaded once per phase into registers instead of 8 post-barrier global loads with immediate waits per item
# baseline (speedup 1.0000x reference)
; #define LAS __attribute__((address_space(3)))
; __device__ __forceinline__ kaptr ka_fresh() { kaptr p = (kaptr)__builtin_amdgcn_kernarg_segment_ptr(); asm volatile("" : "+s"(p)); return p; }
; #define KA_WS(ka) (*(unsigned char* const __attribute__((address_space(4)))*)((ka) + 216))
; #define PHASE_IDS() int vcu = vcu0, G = G0; asm volatile("" : "+s"(vcu), "+s"(G)); const int ngw = G * NWAVES; (void)ngw; int tid = tid0; asm volatile("" : "+v"(tid)); const int lane = tid & 63, wave = __builtin_amdgcn_readfirstlane(tid >> 6), gw = vcu * NWAVES + wave; (void)lane; (void)gw
; __device__ __forceinline__ void hyena_conv_s2(const float* HYT, float* ZOUT, const float* FILT, const cf2* TW, LAS unsigned char* lds, int vb, int nb, int tid_in) {
;     ldsc X = (ldsc)lds;
;     for (int u = vb; u < 1024; u += nb) {
;         int tid = tid_in; asm volatile("" : "+v"(tid));
;         __syncthreads();
;         const int c = u;
;         const float* hv = HYT + (size_t)c * MTOK + 16384; const float* hx1 = HYT + (size_t)(1024 + c) * MTOK + 16384; const float* hx2 = HYT + (size_t)(2048 + c) * MTOK + 16384;
;         float* zo = ZOUT + (size_t)c * MTOK + 16384;
;         const float* f0 = FILT + FILT_L1_OFF + (size_t)c * 16384; const float* f1 = FILT + FILT_L1_OFF + (size_t)(1024 + c) * 16384;
; __global__ void __launch_bounds__(NT, 2) fwd_kernel(Args args_unused) {
;     ...
;         if (IN(P + 2)) for (int rp2 = 0; rp2 < 1 + ((DBG_DOUBLE >> 11) & 1); ++rp2) {
;             PHASE_IDS(); kaptr ka = ka_fresh(); unsigned char* ws = KA_WS(ka); __syncthreads();
;     ...
;             if (PM(8)) { hyena_conv_s2(WSP(const float, WS_HYT), WSP(float, WS_ZOUT), WSP(const float, WS_FILT), WSP(const cf2, WS_TW), lds, vcu, G, tid); hyena_conv_p(WSP(const float, WS_HYT), WSP(float, WS_ZOUT), WSP(const float, WS_FILT), WSP(const unsigned char, WS_FMTAB), lds, vcu, G, tid); }
.LBB0_633:
	v_readlane_b32 s4, v252, 6
	v_readlane_b32 s6, v252, 8
	v_readlane_b32 s7, v252, 9
	s_mov_b64 s[10:11], s[6:7]
	v_readlane_b32 s5, v252, 7
	s_cmp_gt_i32 s10, s3
	s_cselect_b64 s[4:5], -1, 0
	s_xor_b64 s[6:7], s[8:9], -1
	s_add_i32 s68, s46, 5
	s_cmp_lt_i32 s68, s11
	s_cselect_b64 s[52:53], -1, 0
	s_or_b64 s[4:5], s[4:5], s[6:7]
	s_and_b64 vcc, exec, s[4:5]
	s_cbranch_vccnz .LBB0_821
	v_readlane_b32 s10, v252, 0
	v_readlane_b32 s69, v252, 4
	v_readlane_b32 s70, v252, 5
	v_mov_b32_e32 v1, v0
	v_readlane_b32 s11, v252, 1
	s_load_dwordx2 s[8:9], s[10:11], 0xd8
	s_waitcnt vmcnt(0) lgkmcnt(0)
	s_barrier
	s_add_u32 s64, s8, 0x66200000
	s_addc_u32 s65, s9, 0
	s_add_u32 s56, s8, 0x90200000
	s_addc_u32 s57, s9, 0
	s_cmpk_lt_i32 s70, 0x400
	s_cselect_b64 s[6:7], -1, 0
	s_cmpk_gt_i32 s70, 0x3ff
	s_cbranch_scc1 .LBB0_687
	s_add_u32 s36, s8, 0xf00000
	s_addc_u32 s37, s9, 0
	v_lshlrev_b32_e32 v200, 7, v1
	v_lshlrev_b32_e32 v201, 11, v1
	v_and_b32_e32 v200, 0x1f80, v200
	v_and_b32_e32 v201, 0x3800, v201
	global_load_dwordx2 v[202:203], v200, s[36:37]
	global_load_dwordx2 v[204:205], v201, s[36:37]
	s_waitcnt vmcnt(0)
	s_add_u32 s58, s8, 0x28200000
	s_addc_u32 s59, s9, 0
	s_mov_b32 s14, s70

; template <int R> FFT_HD inline void reg_fwd(cf2 (&v)[1 << R], cf2 th) { dft_fwd_reg<R>(v); tw_apply<R, 1, false>(v, th, th); }
; template <int R> FFT_HD inline void dft_fwd_reg(cf2 (&v)[1 << R]) {
;     ...
;         for (int m = 0; m < n; ++m) {
;             if ((m & half) == 0) {
;                 const int ml = m & (half - 1), tk = ml * (16 / half);
;                 const cf2 a = v[m], b = v[m + half];
;                 v[m].x = a.x + b.x; v[m].y = a.y + b.y;
;                 const cf2 d = {a.x - b.x, a.y - b.y};
;                 if (tk == 0) v[m + half] = d;
;                 else if (tk == 8) { v[m + half].x = d.y; v[m + half].y = -d.x; }
;                 else { const cf2 w = {fc32(tk), -fs32(tk)}; v[m + half] = cmulf(d, w); }
;             }
; __device__ __forceinline__ void hyena_conv_s2(const float* HYT, float* ZOUT, const float* FILT, const cf2* TW, LAS unsigned char* lds, int vb, int nb, int tid_in) {
;     ...
; #pragma unroll 1
;         for (int q = 0; q < 2; ++q) { const int grp = tid + 512 * q; cf2 v[16];
; #pragma unroll
;             for (int m = 0; m < 16; ++m) { v[m].x = m < 8 ? hv[grp + 1024 * m] : 0.f; v[m].y = f0[grp + 1024 * m]; }
;             reg_fwd<4>(v, TW[grp]); grp_store<4, 1024>(X, grp, v); }
.LBB0_637:
	v_cndmask_b32_e64 v2, 0, 1, s[54:55]
	v_cmp_ne_u32_e64 s[4:5], 1, v2
	v_add_u32_e32 v2, s3, v172
	v_ashrrev_i32_e32 v3, 31, v2
	v_lshlrev_b64 v[6:7], 2, v[2:3]
	v_lshl_add_u64 v[14:15], s[42:43], 0, v[6:7]
	v_add_co_u32_e32 v8, vcc, 0x1000, v14
	v_lshl_add_u64 v[6:7], s[50:51], 0, v[6:7]
	s_nop 0
	v_addc_co_u32_e32 v9, vcc, 0, v15, vcc
	global_load_dword v4, v[14:15], off
	global_load_dword v29, v[6:7], off
	global_load_dword v10, v[8:9], off
	v_add_co_u32_e32 v8, vcc, 0x1000, v6
	s_mov_b32 s26, s61
	s_nop 0
	v_addc_co_u32_e32 v9, vcc, 0, v7, vcc
	global_load_dword v32, v[8:9], off
	v_add_co_u32_e32 v8, vcc, s48, v14
	s_mov_b32 s27, s60
	s_nop 0
	v_addc_co_u32_e32 v9, vcc, 0, v15, vcc
	global_load_dword v30, v[8:9], off
	v_add_co_u32_e32 v8, vcc, s48, v6
	s_mov_b32 s79, s61
	s_nop 0
	v_addc_co_u32_e32 v9, vcc, 0, v7, vcc
	global_load_dword v35, v[8:9], off
	v_add_co_u32_e32 v8, vcc, 0x3000, v14
	s_mov_b32 s30, s80
	s_nop 0
	v_addc_co_u32_e32 v9, vcc, 0, v15, vcc
	global_load_dword v31, v[8:9], off
	v_add_co_u32_e32 v8, vcc, 0x3000, v6
	s_mov_b32 s31, s60
	s_nop 0
	v_addc_co_u32_e32 v9, vcc, 0, v7, vcc
	v_add_co_u32_e32 v12, vcc, s40, v14
	global_load_dword v34, v[8:9], off
	s_nop 0
	v_addc_co_u32_e32 v13, vcc, 0, v15, vcc
	v_add_co_u32_e32 v16, vcc, s40, v6
	global_load_dword v8, v[12:13], off offset:-4096
	s_nop 0
	v_addc_co_u32_e32 v17, vcc, 0, v7, vcc
	v_add_co_u32_e32 v14, vcc, s33, v14
	global_load_dword v19, v[16:17], off offset:-4096
	s_nop 0
	global_load_dword v13, v[12:13], off
	s_nop 0
	global_load_dword v18, v[16:17], off
	v_addc_co_u32_e32 v15, vcc, 0, v15, vcc
	v_add_co_u32_e32 v22, vcc, s33, v6
	global_load_dword v16, v[14:15], off offset:-4096
	s_nop 0
	v_addc_co_u32_e32 v23, vcc, 0, v7, vcc
	global_load_dword v21, v[22:23], off offset:-4096
	global_load_dword v17, v[14:15], off
	global_load_dword v20, v[22:23], off
	v_add_co_u32_e32 v14, vcc, s1, v6
	s_mov_b32 s28, s80
	s_nop 0
	v_addc_co_u32_e32 v15, vcc, 0, v7, vcc
	global_load_dword v33, v[14:15], off offset:-4096
	global_load_dword v28, v[14:15], off
	v_add_co_u32_e32 v14, vcc, s92, v6
	s_mov_b32 s29, s61
	s_nop 0
	v_addc_co_u32_e32 v15, vcc, 0, v7, vcc
	global_load_dword v45, v[14:15], off offset:-4096
	global_load_dword v44, v[14:15], off
	v_add_co_u32_e32 v14, vcc, s0, v6
	s_mov_b32 s44, s61
	s_nop 0
	v_addc_co_u32_e32 v15, vcc, 0, v7, vcc
	v_add_co_u32_e32 v6, vcc, s18, v6
	global_load_dword v25, v[14:15], off offset:-4096
	global_load_dword v24, v[14:15], off
	v_addc_co_u32_e32 v7, vcc, 0, v7, vcc
	global_load_dword v23, v[6:7], off offset:-4096
	global_load_dword v22, v[6:7], off
	v_lshl_add_u64 v[6:7], v[2:3], 3, s[36:37]
	global_load_dwordx2 v[6:7], v[6:7], off
	s_mov_b32 s45, s80
	s_mov_b32 s83, s84
	s_mov_b32 s81, s82
	s_waitcnt vmcnt(23)
	v_mov_b32_e32 v69, v29
	s_waitcnt vmcnt(22)
	v_mov_b32_e32 v5, v10
	v_pk_add_f32 v[40:41], v[4:5], 0 op_sel_hi:[1,0]
	v_mul_f32_e32 v70, 0x3ec3ef15, v10
	v_lshrrev_b32_e32 v3, 22, v3
	v_add_lshl_u32 v3, v2, v3, 4
	v_and_b32_e32 v3, 0xffffc000, v3
	v_and_b32_e32 v2, 0x3ff, v2
	s_movk_i32 s3, 0x200
	s_mov_b64 s[54:55], 0
	s_and_b64 vcc, exec, s[4:5]
	s_waitcnt vmcnt(18)
	v_pk_add_f32 v[54:55], v[30:31], 0 op_sel_hi:[1,0]
	s_waitcnt vmcnt(15)
	v_mov_b32_e32 v66, v19
	s_waitcnt vmcnt(14)
	v_mov_b32_e32 v9, v13
	v_mul_f32_e32 v14, 0x3f6c835e, v13
	v_pk_add_f32 v[74:75], v[8:9], 0 op_sel_hi:[1,0]
	v_mul_f32_e32 v65, 0x3ec3ef15, v13
	v_sub_f32_e32 v5, v41, v75
	v_mul_f32_e32 v5, 0x3f3504f3, v5
	s_waitcnt vmcnt(10)
	v_pk_add_f32 v[84:85], v[16:17], 0 op_sel_hi:[1,0]
	s_nop 0
	v_pk_add_f32 v[82:83], v[54:55], v[84:85]
	s_waitcnt vmcnt(8)
	v_mov_b32_e32 v71, v33
	s_waitcnt vmcnt(7)
	v_sub_f32_e32 v11, v32, v28
	v_mul_f32_e32 v12, 0x3ec3ef15, v11
	v_pk_fma_f32 v[26:27], v[10:11], s[26:27], v[12:13] op_sel_hi:[1,1,0]
	v_pk_add_f32 v[46:47], v[28:29], v[32:33]
	v_sub_f32_e32 v10, v55, v85
	v_mul_f32_e32 v68, 0x3f6c835e, v11
	s_waitcnt vmcnt(5)
	v_pk_add_f32 v[72:73], v[34:35], v[44:45]
	v_mov_b32_e32 v32, v35
	v_mov_b32_e32 v33, v34
	v_mov_b32_e32 v34, v45
	v_mov_b32_e32 v35, v44
	v_pk_add_f32 v[32:33], v[32:33], v[34:35] neg_lo:[0,1] neg_hi:[0,1]
	v_mov_b32_e32 v34, v31
	v_mov_b32_e32 v35, v30
	s_waitcnt vmcnt(3)
	v_sub_f32_e32 v12, v18, v24
	v_pk_add_f32 v[78:79], v[18:19], v[24:25]
	v_mul_f32_e32 v67, 0x3f6c835e, v12
	s_waitcnt vmcnt(1)
	v_pk_add_f32 v[86:87], v[20:21], v[22:23]
	v_pk_fma_f32 v[36:37], v[12:13], s[78:79], v[14:15] op_sel_hi:[1,1,0] neg_lo:[0,0,1] neg_hi:[0,0,1]
	s_waitcnt vmcnt(0)
; #define FFT_HD __device__ __attribute__((always_inline))
; template <int R> FFT_HD inline void dft_fwd_reg(cf2 (&v)[1 << R]) {
;     constexpr int n = 1 << R;
; #pragma unroll
;     for (int s = 0; s < R; ++s) {
;         const int half = n >> (s + 1);
; #pragma unroll
;         for (int m = 0; m < n; ++m) {
;             if ((m & half) == 0) {
;                 const int ml = m & (half - 1), tk = ml * (16 / half);
;                 const cf2 a = v[m], b = v[m + half];
;                 v[m].x = a.x + b.x; v[m].y = a.y + b.y;
;                 const cf2 d = {a.x - b.x, a.y - b.y};
;                 if (tk == 0) v[m + half] = d;
;                 else if (tk == 8) { v[m + half].x = d.y; v[m + half].y = -d.x; }
;                 else { const cf2 w = {fc32(tk), -fs32(tk)}; v[m + half] = cmulf(d, w); }
;             }
;         }
;     }
; }
; template <int R, int F, bool CONJ> FFT_HD inline void tw_apply(cf2 (&v)[1 << R], cf2 pf, cf2 th) {
;     constexpr int j = fbrev(F, R);
;     v[j] = CONJ ? cmulcf(v[j], pf) : cmulf(v[j], pf);
;     if constexpr (2 * F < (1 << R)) {
;         const cf2 p2 = cmulf(pf, pf);
;         tw_apply<R, 2 * F, CONJ>(v, p2, th);
;         const cf2 p3 = cmulf(p2, th);
;         tw_apply<R, 2 * F + 1, CONJ>(v, p3, th);
;     }
; }
	v_pk_mul_f32 v[38:39], v[6:7], v[6:7] op_sel:[1,1] op_sel_hi:[0,1]
	v_pk_fma_f32 v[42:43], v[6:7], v[6:7], v[38:39] op_sel_hi:[0,1,1] neg_lo:[0,0,1] neg_hi:[0,0,1]
	v_pk_fma_f32 v[50:51], v[6:7], v[6:7], v[38:39] op_sel_hi:[0,1,1]
	v_pk_mov_b32 v[38:39], v[50:51], v[42:43] op_sel:[1,0]
	v_pk_add_f32 v[12:13], v[40:41], v[74:75]
	v_pk_add_f32 v[14:15], v[46:47], v[78:79]
	v_pk_add_f32 v[88:89], v[72:73], v[86:87]
	v_mov_b32_e32 v52, v42
	v_mov_b32_e32 v53, v51
	v_pk_mul_f32 v[58:59], v[50:51], v[38:39] op_sel:[1,0]
	v_mul_f32_e32 v18, 0x3f3504f3, v10
	v_pk_add_f32 v[10:11], v[12:13], v[82:83] neg_lo:[0,1] neg_hi:[0,1]
	v_pk_add_f32 v[90:91], v[14:15], v[88:89] neg_lo:[0,1] neg_hi:[0,1]
	v_pk_fma_f32 v[56:57], v[42:43], v[52:53], v[58:59] op_sel_hi:[0,1,1] neg_lo:[0,0,1] neg_hi:[0,0,1]
	v_pk_fma_f32 v[58:59], v[42:43], v[52:53], v[58:59] op_sel_hi:[0,1,1]
	v_pk_add_f32 v[80:81], v[10:11], v[90:91]
	v_pk_add_f32 v[48:49], v[10:11], v[90:91] neg_lo:[0,1] neg_hi:[0,1]
	v_sub_f32_e32 v10, v91, v11
	v_pk_mov_b32 v[90:91], v[58:59], v[56:57] op_sel:[1,0]
	v_mov_b32_e32 v92, v56
	v_mov_b32_e32 v93, v59
	v_pk_mul_f32 v[90:91], v[10:11], v[90:91] op_sel_hi:[0,1]
	v_pk_mul_f32 v[60:61], v[56:57], v[92:93] op_sel_hi:[0,1]
	v_pk_fma_f32 v[10:11], v[80:81], v[56:57], v[90:91] neg_lo:[0,0,1] neg_hi:[0,0,1]
	v_pk_fma_f32 v[90:91], v[80:81], v[92:93], v[90:91] op_sel_hi:[0,1,1]
	v_pk_fma_f32 v[94:95], v[92:93], v[58:59], v[60:61] op_sel:[0,1,1] op_sel_hi:[1,1,0] neg_lo:[1,0,0] neg_hi:[1,0,0]
	v_pk_fma_f32 v[96:97], v[92:93], v[58:59], v[60:61] op_sel:[0,1,1] op_sel_hi:[1,1,0]
	v_mov_b32_e32 v11, v91
	v_mov_b32_e32 v90, v12
	v_mov_b32_e32 v91, v15
	v_mov_b32_e32 v92, v82
	v_mov_b32_e32 v93, v89
	v_pk_mov_b32 v[12:13], v[12:13], v[14:15] op_sel:[1,0]
	v_pk_mov_b32 v[14:15], v[82:83], v[88:89] op_sel:[1,0]
	v_pk_add_f32 v[90:91], v[90:91], v[92:93]
	v_pk_add_f32 v[14:15], v[12:13], v[14:15]
	s_mov_b32 s26, s60
	s_mov_b32 s27, s80
	v_pk_add_f32 v[82:83], v[90:91], v[14:15] neg_lo:[0,1] neg_hi:[0,1]
	v_pk_mul_f32 v[30:31], v[34:35], s[26:27]
	v_pk_mul_f32 v[44:45], v[32:33], s[30:31]
	v_sub_f32_e32 v9, v46, v78
	v_pk_mul_f32 v[88:89], v[82:83], v[96:97] op_sel:[1,0] op_sel_hi:[0,0]
	v_pk_fma_f32 v[30:31], v[32:33], s[28:29], v[30:31] op_sel:[0,0,1] op_sel_hi:[1,1,0]
	v_pk_fma_f32 v[32:33], v[34:35], s[44:45], v[44:45] op_sel:[0,0,1] op_sel_hi:[1,1,0] neg_lo:[1,0,0] neg_hi:[1,0,0]
	v_mov_b32_e32 v34, v21
	v_mov_b32_e32 v35, v20
	v_mov_b32_e32 v20, v23
	v_mov_b32_e32 v21, v22
	v_mov_b32_e32 v22, v17
	v_mov_b32_e32 v23, v16
	v_mul_f32_e32 v24, 0x3f3504f3, v9
	v_pk_add_f32 v[12:13], v[90:91], v[14:15]
	v_pk_fma_f32 v[14:15], v[82:83], v[94:95], v[88:89] op_sel:[0,1,0] neg_lo:[0,0,1] neg_hi:[0,0,1]
	v_pk_fma_f32 v[82:83], v[82:83], v[94:95], v[88:89] op_sel:[0,1,0]
	v_mov_b32_e32 v41, v47
	v_mov_b32_e32 v75, v79
	v_pk_add_f32 v[20:21], v[34:35], v[20:21] neg_lo:[0,1] neg_hi:[0,1]
	v_pk_mul_f32 v[16:17], v[22:23], s[44:45]
	v_pk_add_f32 v[46:47], v[40:41], v[74:75] neg_lo:[0,1] neg_hi:[0,1]
	v_add_f32_e32 v82, v24, v5
	v_pk_mov_b32 v[40:41], v[72:73], v[54:55] op_sel:[1,0]
	v_pk_mov_b32 v[54:55], v[86:87], v[84:85] op_sel:[1,0]
	v_sub_f32_e32 v24, v72, v86
	v_pk_add_f32 v[28:29], v[68:69], v[70:71] neg_lo:[0,1] neg_hi:[0,1]
	v_mov_b32_e32 v64, v25
	v_pk_fma_f32 v[16:17], v[20:21], s[30:31], v[16:17] op_sel:[0,0,1] op_sel_hi:[1,1,0] neg_lo:[0,0,1] neg_hi:[0,0,1]
	v_pk_mul_f32 v[20:21], v[20:21], s[82:83]
	v_mov_b32_e32 v37, v8
	v_mov_b32_e32 v15, v83
	v_fma_f32 v83, v9, s80, -v5
	v_pk_add_f32 v[54:55], v[40:41], v[54:55] neg_lo:[0,1] neg_hi:[0,1]
	v_pk_fma_f32 v[84:85], v[24:25], s[80:81], v[18:19] op_sel_hi:[0,1,0] neg_lo:[0,0,1] neg_hi:[0,0,1]
	v_pk_add_f32 v[24:25], v[66:67], v[64:65] neg_lo:[0,1] neg_hi:[0,1]
	v_pk_fma_f32 v[20:21], v[22:23], s[26:27], v[20:21] op_sel:[0,0,1] op_sel_hi:[1,1,0] neg_lo:[1,0,0] neg_hi:[1,0,0]
	v_mov_b32_e32 v5, v26
	v_pk_add_f32 v[66:67], v[28:29], v[36:37]
	v_pk_add_f32 v[68:69], v[28:29], v[36:37] neg_lo:[0,1] neg_hi:[0,1]
	v_pk_add_f32 v[40:41], v[46:47], v[54:55]
	v_pk_add_f32 v[72:73], v[46:47], v[54:55] neg_lo:[0,1] neg_hi:[0,1]
	v_pk_add_f32 v[22:23], v[4:5], v[24:25]
	v_mov_b32_e32 v68, v66
	v_pk_add_f32 v[34:35], v[30:31], v[16:17] neg_lo:[0,1] neg_hi:[0,1]
	v_pk_add_f32 v[44:45], v[32:33], v[20:21] neg_lo:[0,1] neg_hi:[0,1]
	v_pk_add_f32 v[16:17], v[30:31], v[16:17]
	v_pk_add_f32 v[20:21], v[32:33], v[20:21]
	v_mov_b32_e32 v72, v40
	v_pk_add_f32 v[74:75], v[82:83], v[84:85]
	v_mov_b32_e32 v47, v83
	v_mov_b32_e32 v55, v85
	v_pk_add_f32 v[32:33], v[22:23], v[16:17] neg_lo:[0,1] neg_hi:[0,1]
	v_pk_add_f32 v[70:71], v[68:69], v[20:21] neg_lo:[0,1] neg_hi:[0,1]
	v_mov_b32_e32 v68, v22
	v_mov_b32_e32 v30, v16
	v_mov_b32_e32 v31, v21
	v_pk_mov_b32 v[22:23], v[22:23], v[66:67] op_sel:[1,0]
	v_pk_mov_b32 v[16:17], v[16:17], v[20:21] op_sel:[1,0]
	v_pk_add_f32 v[46:47], v[46:47], v[54:55] neg_lo:[0,1] neg_hi:[0,1]
	v_pk_add_f32 v[54:55], v[72:73], v[74:75]
	v_pk_add_f32 v[30:31], v[68:69], v[30:31]
	v_pk_add_f32 v[16:17], v[22:23], v[16:17]
	v_pk_add_f32 v[78:79], v[72:73], v[74:75] neg_lo:[0,1] neg_hi:[0,1]
	v_pk_mul_f32 v[72:73], v[38:39], v[54:55] op_sel:[0,1]
	v_pk_add_f32 v[20:21], v[30:31], v[16:17]
	v_mov_b32_e32 v62, v96
	v_mov_b32_e32 v63, v95
	v_pk_fma_f32 v[38:39], v[42:43], v[54:55], v[72:73] neg_lo:[0,0,1] neg_hi:[0,0,1]
	v_pk_fma_f32 v[52:53], v[52:53], v[54:55], v[72:73] op_sel_hi:[1,0,1]
	v_pk_add_f32 v[22:23], v[30:31], v[16:17] neg_lo:[0,1] neg_hi:[0,1]
	v_pk_mul_f32 v[30:31], v[6:7], v[20:21] op_sel:[1,1] op_sel_hi:[0,1]
	v_pk_mov_b32 v[60:61], v[94:95], v[96:97] op_sel:[1,0]
	v_pk_mul_f32 v[62:63], v[6:7], v[62:63]
; #define FFT_HD __device__ __attribute__((always_inline))
; template <int R> FFT_HD inline void dft_fwd_reg(cf2 (&v)[1 << R]) {
;     constexpr int n = 1 << R;
; #pragma unroll
;     for (int s = 0; s < R; ++s) {
;         const int half = n >> (s + 1);
; #pragma unroll
;         for (int m = 0; m < n; ++m) {
;             if ((m & half) == 0) {
;                 const int ml = m & (half - 1), tk = ml * (16 / half);
;                 const cf2 a = v[m], b = v[m + half];
;                 v[m].x = a.x + b.x; v[m].y = a.y + b.y;
;                 const cf2 d = {a.x - b.x, a.y - b.y};
;                 if (tk == 0) v[m + half] = d;
;                 else if (tk == 8) { v[m + half].x = d.y; v[m + half].y = -d.x; }
;                 else { const cf2 w = {fc32(tk), -fs32(tk)}; v[m + half] = cmulf(d, w); }
;             }
;         }
;     }
; }
; template <int R, int F, bool CONJ> FFT_HD inline void tw_apply(cf2 (&v)[1 << R], cf2 pf, cf2 th) {
;     constexpr int j = fbrev(F, R);
;     v[j] = CONJ ? cmulcf(v[j], pf) : cmulf(v[j], pf);
;     if constexpr (2 * F < (1 << R)) {
;         const cf2 p2 = cmulf(pf, pf);
;         tw_apply<R, 2 * F, CONJ>(v, p2, th);
;         const cf2 p3 = cmulf(p2, th);
;         tw_apply<R, 2 * F + 1, CONJ>(v, p3, th);
;     }
; }
	v_mov_b32_e32 v39, v53
	v_pk_mul_f32 v[52:53], v[6:7], v[50:51] op_sel:[1,1] op_sel_hi:[0,1]
	v_pk_fma_f32 v[16:17], v[6:7], v[20:21], v[30:31] neg_lo:[0,0,1] neg_hi:[0,0,1]
	v_pk_fma_f32 v[20:21], v[6:7], v[20:21], v[30:31] op_sel_hi:[1,0,1]
	v_pk_mul_f32 v[60:61], v[6:7], v[60:61]
	v_pk_fma_f32 v[50:51], v[6:7], v[42:43], v[52:53] op_sel_hi:[1,0,1] neg_lo:[0,0,1] neg_hi:[0,0,1]
	v_pk_fma_f32 v[42:43], v[6:7], v[42:43], v[52:53] op_sel_hi:[1,0,1]
	v_mov_b32_e32 v17, v21
	v_pk_add_f32 v[20:21], v[62:63], v[62:63] op_sel:[1,0] op_sel_hi:[1,0]
	v_pk_mov_b32 v[54:55], v[42:43], v[50:51] op_sel:[1,0]
	v_pk_mul_f32 v[30:31], v[22:23], v[20:21] op_sel:[1,0] op_sel_hi:[0,1]
	v_pk_add_f32 v[60:61], v[60:61], v[60:61] op_sel:[0,1] op_sel_hi:[0,1] neg_lo:[0,1] neg_hi:[0,1]
	v_mov_b32_e32 v52, v50
	v_mov_b32_e32 v53, v43
	v_pk_mul_f32 v[42:43], v[42:43], v[54:55] op_sel:[1,0]
	v_pk_fma_f32 v[20:21], v[22:23], v[60:61], v[30:31] neg_lo:[0,0,1] neg_hi:[0,0,1]
	v_pk_fma_f32 v[22:23], v[22:23], v[60:61], v[30:31]
	v_pk_fma_f32 v[86:87], v[50:51], v[52:53], v[42:43] op_sel_hi:[0,1,1] neg_lo:[0,0,1] neg_hi:[0,0,1]
	v_pk_fma_f32 v[72:73], v[50:51], v[52:53], v[42:43] op_sel_hi:[0,1,1]
	v_sub_f32_e32 v18, v82, v84
	v_mov_b32_e32 v21, v23
	v_pk_mul_f32 v[22:23], v[6:7], v[58:59] op_sel:[1,1] op_sel_hi:[0,1]
	v_pk_add_f32 v[42:43], v[40:41], v[18:19] op_sel:[1,0] op_sel_hi:[1,0] neg_lo:[0,1] neg_hi:[0,1]
	v_pk_mov_b32 v[82:83], v[72:73], v[86:87] op_sel:[1,0]
	v_pk_fma_f32 v[60:61], v[6:7], v[56:57], v[22:23] op_sel_hi:[1,0,1] neg_lo:[0,0,1] neg_hi:[0,0,1]
	v_pk_fma_f32 v[22:23], v[6:7], v[56:57], v[22:23] op_sel_hi:[1,0,1]
	v_mov_b32_e32 v74, v86
	v_mov_b32_e32 v75, v73
	v_pk_add_f32 v[88:89], v[46:47], v[46:47] op_sel:[0,1] op_sel_hi:[0,1]
	v_pk_mul_f32 v[84:85], v[42:43], v[82:83]
	v_mov_b32_e32 v62, v60
	v_mov_b32_e32 v63, v23
	v_pk_fma_f32 v[42:43], v[88:89], v[86:87], v[84:85] neg_lo:[0,0,1] neg_hi:[0,0,1]
	v_pk_fma_f32 v[84:85], v[88:89], v[74:75], v[84:85]
	v_pk_mov_b32 v[66:67], v[22:23], v[60:61] op_sel:[1,0]
	v_pk_mul_f32 v[22:23], v[62:63], v[22:23] op_sel:[0,1]
	v_mov_b32_e32 v43, v85
	v_pk_mul_f32 v[84:85], v[74:75], v[72:73] op_sel:[0,1]
	v_pk_fma_f32 v[68:69], v[60:61], v[66:67], v[22:23] op_sel_hi:[0,1,1] neg_lo:[0,0,1] neg_hi:[0,0,1]
	v_pk_fma_f32 v[22:23], v[60:61], v[66:67], v[22:23] op_sel_hi:[0,1,1]
	v_mov_b32_e32 v77, v81
	v_pk_mov_b32 v[80:81], v[80:81], v[48:49] op_sel:[1,0]
	v_pk_fma_f32 v[88:89], v[86:87], v[82:83], v[84:85] op_sel_hi:[0,1,1] neg_lo:[0,0,1] neg_hi:[0,0,1]
	v_pk_fma_f32 v[82:83], v[86:87], v[82:83], v[84:85] op_sel_hi:[0,1,1]
	v_mov_b32_e32 v30, v22
	v_mov_b32_e32 v31, v69
	v_pk_mov_b32 v[56:57], v[68:69], v[22:23] op_sel:[1,0]
	v_pk_mul_f32 v[22:23], v[78:79], v[22:23] op_sel:[1,0] op_sel_hi:[0,0]
	v_mov_b32_e32 v76, v48
	v_pk_mul_f32 v[80:81], v[80:81], v[82:83] op_sel_hi:[1,0]
	v_pk_mul_f32 v[58:59], v[6:7], v[30:31]
	v_pk_fma_f32 v[30:31], v[78:79], v[68:69], v[22:23] op_sel:[0,1,0] neg_lo:[0,0,1] neg_hi:[0,0,1]
	v_pk_fma_f32 v[22:23], v[78:79], v[68:69], v[22:23] op_sel:[0,1,0]
	v_mov_b32_e32 v84, v82
	v_mov_b32_e32 v85, v89
	v_pk_mov_b32 v[82:83], v[88:89], v[82:83] op_sel:[1,0]
	v_pk_fma_f32 v[48:49], v[48:49], v[88:89], v[80:81] op_sel:[0,1,0] neg_lo:[0,0,1] neg_hi:[0,0,1]
	v_pk_fma_f32 v[76:77], v[76:77], v[88:89], v[80:81] op_sel:[0,1,0]
	v_sub_f32_e32 v22, v71, v33
	v_mov_b32_e32 v49, v77
	v_pk_mul_f32 v[76:77], v[6:7], v[82:83]
	v_pk_mul_f32 v[80:81], v[6:7], v[84:85]
	v_pk_add_f32 v[82:83], v[32:33], v[70:71]
	v_pk_add_f32 v[84:85], v[32:33], v[70:71] neg_lo:[0,1] neg_hi:[0,1]
	v_pk_mul_f32 v[32:33], v[22:23], v[66:67] op_sel_hi:[0,1]
	v_mov_b32_e32 v31, v23
	v_pk_fma_f32 v[22:23], v[82:83], v[60:61], v[32:33] neg_lo:[0,0,1] neg_hi:[0,0,1]
	v_pk_fma_f32 v[32:33], v[82:83], v[62:63], v[32:33] op_sel_hi:[0,1,1]
	v_mov_b32_e32 v23, v33
	v_pk_mov_b32 v[32:33], v[82:83], v[84:85] op_sel:[1,0]
	v_pk_add_f32 v[60:61], v[80:81], v[80:81] op_sel:[1,0] op_sel_hi:[1,0]
	v_mov_b32_e32 v86, v84
	v_mov_b32_e32 v87, v83
	v_pk_mul_f32 v[60:61], v[32:33], v[60:61]
	v_pk_add_f32 v[62:63], v[76:77], v[76:77] op_sel:[0,1] op_sel_hi:[0,1] neg_lo:[0,1] neg_hi:[0,1]
	v_pk_fma_f32 v[32:33], v[84:85], v[62:63], v[60:61] neg_lo:[0,0,1] neg_hi:[0,0,1]
	v_pk_fma_f32 v[60:61], v[86:87], v[62:63], v[60:61]
	v_pk_mul_f32 v[66:67], v[6:7], v[74:75]
	v_mul_f32_e32 v60, v6, v73
	v_mov_b32_e32 v68, v28
	v_mov_b32_e32 v69, v66
	v_mov_b32_e32 v37, v67
	v_mov_b32_e32 v33, v61
	v_pk_fma_f32 v[60:61], v[6:7], v[74:75], v[60:61] op_sel:[1,0,0] op_sel_hi:[0,1,0]
	v_pk_add_f32 v[36:37], v[68:69], v[36:37] neg_lo:[0,1] neg_hi:[0,1]
	v_mov_b32_e32 v27, v66
	v_mov_b32_e32 v66, v25
	v_pk_mul_f32 v[62:63], v[60:61], v[60:61]
	v_pk_add_f32 v[26:27], v[26:27], v[66:67] neg_lo:[0,1] neg_hi:[0,1]
	v_mov_b32_e32 v66, v187
	v_mov_b32_e32 v67, v60
	v_pk_mul_f32 v[70:71], v[36:37], v[36:37]
	v_pk_mul_f32 v[68:69], v[36:37], s[80:81]
	v_pk_mul_f32 v[26:27], v[26:27], v[66:67]
	v_mov_b32_e32 v5, v71
	v_mov_b32_e32 v25, v62
	v_pk_add_f32 v[4:5], v[4:5], v[24:25] neg_lo:[0,1] neg_hi:[0,1]
	v_pk_fma_f32 v[24:25], v[36:37], v[66:67], v[26:27] neg_lo:[0,0,1] neg_hi:[0,0,1]
	v_pk_fma_f32 v[62:63], v[36:37], v[66:67], v[26:27]
	v_mov_b32_e32 v9, v26
	v_pk_mov_b32 v[26:27], v[28:29], v[68:69] op_sel:[1,0]
	v_mul_f32_e32 v64, 0x3f3504f3, v35
	v_pk_add_f32 v[8:9], v[8:9], v[26:27]
	v_pk_fma_f32 v[64:65], v[44:45], s[80:81], v[64:65] op_sel_hi:[0,1,0] neg_lo:[0,0,1] neg_hi:[0,0,1]
	v_pk_mov_b32 v[26:27], v[44:45], v[8:9] op_sel:[1,0]
	v_pk_mul_f32 v[56:57], v[6:7], v[56:57]
	v_pk_add_f32 v[28:29], v[26:27], v[4:5]
	v_pk_add_f32 v[26:27], v[26:27], v[34:35] op_sel_hi:[1,0] neg_lo:[0,1] neg_hi:[0,1]
; #define FFT_HD __device__ __attribute__((always_inline))
; template <int R> FFT_HD inline void reg_fwd(cf2 (&v)[1 << R], cf2 th) { dft_fwd_reg<R>(v); tw_apply<R, 1, false>(v, th, th); }
; template <int R, int F, bool CONJ> FFT_HD inline void tw_apply(cf2 (&v)[1 << R], cf2 pf, cf2 th) {
;     constexpr int j = fbrev(F, R);
;     v[j] = CONJ ? cmulcf(v[j], pf) : cmulf(v[j], pf);
;     if constexpr (2 * F < (1 << R)) {
;         const cf2 p2 = cmulf(pf, pf);
;         tw_apply<R, 2 * F, CONJ>(v, p2, th);
;         const cf2 p3 = cmulf(p2, th);
;         tw_apply<R, 2 * F + 1, CONJ>(v, p3, th);
;     }
; }
; __device__ __forceinline__ void hyena_conv_s2(const float* HYT, float* ZOUT, const float* FILT, const cf2* TW, LAS unsigned char* lds, int vb, int nb, int tid_in) {
;     ...
;         for (int q = 0; q < 2; ++q) { const int grp = tid + 512 * q; cf2 v[16];
; #pragma unroll
;             for (int m = 0; m < 16; ++m) { v[m].x = m < 8 ? hv[grp + 1024 * m] : 0.f; v[m].y = f0[grp + 1024 * m]; }
;             reg_fwd<4>(v, TW[grp]); grp_store<4, 1024>(X, grp, v); }
	v_pk_add_f32 v[58:59], v[58:59], v[58:59] op_sel:[1,0] op_sel_hi:[1,0]
	v_mov_b32_e32 v29, v27
	v_pk_mov_b32 v[26:27], v[8:9], v[24:25] op_sel:[1,0]
	v_pk_add_f32 v[56:57], v[56:57], v[56:57] op_sel:[0,1] op_sel_hi:[0,1] neg_lo:[0,1] neg_hi:[0,1]
	v_pk_add_f32 v[26:27], v[26:27], v[64:65]
	v_mov_b32_e32 v35, v64
	v_pk_add_f32 v[68:69], v[28:29], v[26:27]
	v_pk_add_f32 v[26:27], v[28:29], v[26:27] neg_lo:[0,1] neg_hi:[0,1]
	v_pk_add_f32 v[24:25], v[24:25], v[64:65] op_sel:[0,1] op_sel_hi:[1,0] neg_lo:[0,1] neg_hi:[0,1]
	v_pk_mul_f32 v[58:59], v[26:27], v[58:59] op_sel:[1,0] op_sel_hi:[0,1]
	v_pk_fma_f32 v[64:65], v[26:27], v[56:57], v[58:59] neg_lo:[0,0,1] neg_hi:[0,0,1]
	v_pk_fma_f32 v[26:27], v[26:27], v[56:57], v[58:59]
	v_pk_mov_b32 v[66:67], v[44:45], v[6:7] op_sel:[1,0]
	v_pk_add_f32 v[44:45], v[8:9], v[34:35]
	v_pk_add_f32 v[8:9], v[8:9], v[34:35] neg_lo:[0,1] neg_hi:[0,1]
	v_mov_b32_e32 v65, v27
	v_pk_mul_f32 v[26:27], v[54:55], v[68:69] op_sel:[0,1]
	v_mov_b32_e32 v34, v44
	v_mov_b32_e32 v35, v9
	v_pk_fma_f32 v[50:51], v[50:51], v[68:69], v[26:27] neg_lo:[0,0,1] neg_hi:[0,0,1]
	v_pk_fma_f32 v[26:27], v[52:53], v[68:69], v[26:27] op_sel_hi:[1,0,1]
	v_pk_add_f32 v[70:71], v[4:5], v[66:67] neg_lo:[0,1] neg_hi:[0,1]
	v_pk_mul_f32 v[28:29], v[62:63], v[6:7]
	v_pk_add_f32 v[34:35], v[34:35], v[8:9] op_sel:[0,1] op_sel_hi:[1,0]
	v_mov_b32_e32 v51, v27
	v_pk_mov_b32 v[26:27], v[36:37], v[60:61] op_sel:[1,0]
	v_pk_add_f32 v[8:9], v[44:45], v[8:9] op_sel:[0,1] op_sel_hi:[0,1] neg_lo:[0,1] neg_hi:[0,1]
	v_mov_b32_e32 v61, v37
	v_mov_b32_e32 v28, v24
	v_pk_add_f32 v[24:25], v[70:71], v[24:25]
	v_pk_mul_f32 v[8:9], v[8:9], v[60:61]
	v_pk_mul_f32 v[66:67], v[4:5], v[66:67]
	v_pk_fma_f32 v[36:37], v[24:25], v[26:27], v[8:9] neg_lo:[0,0,1] neg_hi:[0,0,1]
	v_pk_fma_f32 v[8:9], v[24:25], v[26:27], v[8:9] op_sel_hi:[0,1,1]
	v_pk_add_f32 v[18:19], v[40:41], v[18:19] op_sel:[1,0] op_sel_hi:[1,0]
	v_mov_b32_e32 v4, v63
	v_mov_b32_e32 v37, v9
	v_pk_add_f32 v[8:9], v[46:47], v[46:47] op_sel:[0,1] op_sel_hi:[0,1] neg_lo:[0,1] neg_hi:[0,1]
	v_mov_b32_e32 v62, v5
	v_pk_mul_f32 v[18:19], v[18:19], v[4:5]
	v_mov_b32_e32 v66, v70
	v_pk_fma_f32 v[24:25], v[8:9], v[62:63], v[18:19] neg_lo:[0,0,1] neg_hi:[0,0,1]
	v_pk_fma_f32 v[8:9], v[8:9], v[62:63], v[18:19]
	v_pk_mul_f32 v[4:5], v[6:7], v[4:5]
	v_mov_b32_e32 v25, v9
	v_pk_add_f32 v[8:9], v[66:67], v[28:29] neg_lo:[0,1] neg_hi:[0,1]
	v_mov_b32_e32 v6, v34
	v_mov_b32_e32 v7, v8
	v_pk_add_f32 v[4:5], v[4:5], v[4:5] op_sel:[1,0] op_sel_hi:[1,0]
	s_nop 0
	v_pk_mul_f32 v[4:5], v[6:7], v[4:5]
	v_pk_mov_b32 v[6:7], v[8:9], v[34:35] op_sel:[1,0]
	s_nop 0
	v_pk_fma_f32 v[18:19], v[8:9], v[6:7], v[4:5] neg_lo:[0,0,1] neg_hi:[0,0,1]
	v_pk_fma_f32 v[4:5], v[8:9], v[6:7], v[4:5]
	s_nop 0
	v_or_b32_e32 v4, v3, v2
	v_bitop3_b32 v2, v3, s19, v2 bitop3:0xc8
	v_lshlrev_b32_e32 v3, 3, v4
	v_add3_u32 v2, 0, v2, v3
	v_add_u32_e32 v3, 0x12000, v2
	ds_write2st64_b64 v2, v[12:13], v[14:15] offset1:18
	ds_write2st64_b64 v2, v[10:11], v[48:49] offset0:36 offset1:54
	ds_write2st64_b64 v2, v[38:39], v[30:31] offset0:72 offset1:90
	ds_write2st64_b64 v2, v[42:43], v[24:25] offset0:108 offset1:126
	ds_write_b64 v3, v[16:17]
	v_add_u32_e32 v3, 0x14400, v2
	ds_write_b64 v3, v[20:21]
	v_add_u32_e32 v3, 0x16800, v2
	ds_write_b64 v3, v[22:23]
	v_add_u32_e32 v3, 0x18c00, v2
	ds_write_b64 v3, v[32:33]
	v_add_u32_e32 v3, 0x1b000, v2
	ds_write_b64 v3, v[50:51]
	v_add_u32_e32 v3, 0x1d400, v2
	v_mov_b32_e32 v19, v5
	ds_write_b64 v3, v[64:65]
	v_add_u32_e32 v3, 0x1f800, v2
	v_add_u32_e32 v2, 0x21c00, v2
	ds_write_b64 v3, v[36:37]
	ds_write_b64 v2, v[18:19]
	s_cbranch_vccz .LBB0_637
	v_lshlrev_b32_e32 v2, 7, v172
	v_and_b32_e32 v182, 0x1f80, v2
	s_waitcnt lgkmcnt(0)
	s_barrier
	v_mov_b32_e32 v36, v202
	v_mov_b32_e32 v37, v203
	v_and_b32_e32 v173, 63, v172
	s_mov_b32 s3, 0
	v_lshl_add_u64 v[34:35], s[36:37], 0, v[182:183]
	s_mov_b64 s[4:5], -1
	v_pk_mul_f32 v[2:3], v[36:37], v[36:37] op_sel:[1,1] op_sel_hi:[0,1]
	v_pk_fma_f32 v[4:5], v[36:37], v[36:37], v[2:3] op_sel_hi:[0,1,1] neg_lo:[0,0,1] neg_hi:[0,0,1]
	v_pk_fma_f32 v[2:3], v[36:37], v[36:37], v[2:3] op_sel_hi:[0,1,1]
	v_pk_mov_b32 v[42:43], v[2:3], v[4:5] op_sel:[1,0]
	v_pk_mul_f32 v[6:7], v[36:37], v[2:3] op_sel:[1,1] op_sel_hi:[0,1]
	v_mov_b32_e32 v40, v4
	v_mov_b32_e32 v41, v3
	v_pk_mul_f32 v[2:3], v[2:3], v[42:43] op_sel:[1,0]
	v_pk_fma_f32 v[8:9], v[36:37], v[4:5], v[6:7] op_sel_hi:[1,0,1] neg_lo:[0,0,1] neg_hi:[0,0,1]
	v_pk_fma_f32 v[6:7], v[36:37], v[4:5], v[6:7] op_sel_hi:[1,0,1]
	v_pk_fma_f32 v[10:11], v[4:5], v[40:41], v[2:3] op_sel_hi:[0,1,1] neg_lo:[0,0,1] neg_hi:[0,0,1]
	v_pk_fma_f32 v[2:3], v[4:5], v[40:41], v[2:3] op_sel_hi:[0,1,1]
	v_pk_mov_b32 v[46:47], v[6:7], v[8:9] op_sel:[1,0]
	v_mov_b32_e32 v44, v8
	v_mov_b32_e32 v45, v7
	v_pk_mov_b32 v[50:51], v[2:3], v[10:11] op_sel:[1,0]
	v_pk_mul_f32 v[4:5], v[36:37], v[10:11] op_sel_hi:[1,0]
	v_pk_mul_f32 v[6:7], v[6:7], v[46:47] op_sel:[1,0]
	v_mov_b32_e32 v48, v10
	v_mov_b32_e32 v49, v3
	v_pk_mul_f32 v[12:13], v[2:3], v[50:51] op_sel:[1,0]
	v_pk_fma_f32 v[14:15], v[36:37], v[2:3], v[4:5] op_sel:[0,1,1] op_sel_hi:[1,1,0] neg_lo:[1,0,0] neg_hi:[1,0,0]
	v_pk_fma_f32 v[2:3], v[36:37], v[2:3], v[4:5] op_sel:[0,1,1] op_sel_hi:[1,1,0]
	v_pk_fma_f32 v[4:5], v[8:9], v[44:45], v[6:7] op_sel_hi:[0,1,1] neg_lo:[0,0,1] neg_hi:[0,0,1]
	v_pk_fma_f32 v[6:7], v[8:9], v[44:45], v[6:7] op_sel_hi:[0,1,1]
	v_pk_fma_f32 v[8:9], v[10:11], v[48:49], v[12:13] op_sel_hi:[0,1,1] neg_lo:[0,0,1] neg_hi:[0,0,1]
	v_pk_fma_f32 v[10:11], v[10:11], v[48:49], v[12:13] op_sel_hi:[0,1,1]
	v_pk_mov_b32 v[12:13], v[14:15], v[2:3] op_sel:[1,0]
	v_pk_mov_b32 v[56:57], v[6:7], v[4:5] op_sel:[1,0]
; #define FFT_HD __device__ __attribute__((always_inline))
; template <int R> FFT_HD inline void reg_fwd(cf2 (&v)[1 << R], cf2 th) { dft_fwd_reg<R>(v); tw_apply<R, 1, false>(v, th, th); }
; template <int R> FFT_HD inline void dft_fwd_reg(cf2 (&v)[1 << R]) {
;     constexpr int n = 1 << R;
; #pragma unroll
;     for (int s = 0; s < R; ++s) {
;         const int half = n >> (s + 1);
; #pragma unroll
;         for (int m = 0; m < n; ++m) {
;             if ((m & half) == 0) {
;                 const int ml = m & (half - 1), tk = ml * (16 / half);
;                 const cf2 a = v[m], b = v[m + half];
;                 v[m].x = a.x + b.x; v[m].y = a.y + b.y;
;                 const cf2 d = {a.x - b.x, a.y - b.y};
;                 if (tk == 0) v[m + half] = d;
;                 else if (tk == 8) { v[m + half].x = d.y; v[m + half].y = -d.x; }
;                 else { const cf2 w = {fc32(tk), -fs32(tk)}; v[m + half] = cmulf(d, w); }
;             }
;         }
;     }
; }
; __device__ __forceinline__ void s_mid2(ldsc X, const cf2* TW, int tid) {
; #pragma unroll 1
;     for (int q = 0; q < 2; ++q) { const int grp = tid + 512 * q; cf2 v[16]; grp_load<4, 64>(X, grp, v); reg_fwd<4>(v, TW[(grp & 63) * 16]); grp_store<4, 64>(X, grp, v); }
	v_pk_mul_f32 v[16:17], v[36:37], v[6:7] op_sel:[1,1] op_sel_hi:[0,1]
	v_mov_b32_e32 v52, v2
	v_mov_b32_e32 v53, v15
	v_mov_b32_e32 v54, v4
	v_mov_b32_e32 v55, v7
	v_mov_b32_e32 v59, v11
	v_pk_mov_b32 v[60:61], v[10:11], v[8:9] op_sel:[1,0]
	v_pk_mul_f32 v[10:11], v[36:37], v[10:11] op_sel:[1,1] op_sel_hi:[0,1]
	v_pk_mul_f32 v[2:3], v[2:3], v[12:13] op_sel_hi:[0,1]
	v_pk_mul_f32 v[6:7], v[6:7], v[56:57] op_sel:[1,0]
	v_pk_fma_f32 v[12:13], v[36:37], v[4:5], v[16:17] op_sel_hi:[1,0,1] neg_lo:[0,0,1] neg_hi:[0,0,1]
	v_pk_fma_f32 v[16:17], v[36:37], v[4:5], v[16:17] op_sel_hi:[1,0,1]
	v_mov_b32_e32 v58, v8
	v_pk_fma_f32 v[18:19], v[36:37], v[8:9], v[10:11] op_sel_hi:[1,0,1] neg_lo:[0,0,1] neg_hi:[0,0,1]
	v_pk_fma_f32 v[8:9], v[36:37], v[8:9], v[10:11] op_sel_hi:[1,0,1]
	v_pk_fma_f32 v[10:11], v[14:15], v[52:53], v[2:3] op_sel:[1,0,0] neg_lo:[0,0,1] neg_hi:[0,0,1]
	v_pk_fma_f32 v[2:3], v[14:15], v[52:53], v[2:3] op_sel:[1,0,0]
	v_pk_fma_f32 v[14:15], v[4:5], v[54:55], v[6:7] op_sel_hi:[0,1,1] neg_lo:[0,0,1] neg_hi:[0,0,1]
	v_pk_fma_f32 v[4:5], v[4:5], v[54:55], v[6:7] op_sel_hi:[0,1,1]
	v_pk_mov_b32 v[64:65], v[16:17], v[12:13] op_sel:[1,0]
	v_mov_b32_e32 v62, v12
	v_mov_b32_e32 v63, v17
	v_mov_b32_e32 v68, v2
	v_pk_mul_f32 v[2:3], v[36:37], v[2:3] op_sel:[1,0] op_sel_hi:[0,0]
	v_mov_b32_e32 v71, v5
	v_pk_mov_b32 v[72:73], v[4:5], v[14:15] op_sel:[1,0]
	v_pk_mul_f32 v[4:5], v[36:37], v[4:5] op_sel:[1,1] op_sel_hi:[0,1]
	v_pk_mul_f32 v[6:7], v[16:17], v[64:65] op_sel:[1,0]
	v_mov_b32_e32 v67, v9
	v_mov_b32_e32 v69, v11
	v_mov_b32_e32 v70, v14
	v_pk_mov_b32 v[74:75], v[8:9], v[18:19] op_sel:[1,0]
	v_pk_fma_f32 v[8:9], v[36:37], v[10:11], v[2:3] op_sel:[0,1,0] neg_lo:[0,0,1] neg_hi:[0,0,1]
	v_pk_fma_f32 v[2:3], v[36:37], v[10:11], v[2:3] op_sel:[0,1,0]
	v_pk_fma_f32 v[10:11], v[36:37], v[14:15], v[4:5] op_sel_hi:[1,0,1] neg_lo:[0,0,1] neg_hi:[0,0,1]
	v_pk_fma_f32 v[4:5], v[36:37], v[14:15], v[4:5] op_sel_hi:[1,0,1]
	v_pk_fma_f32 v[14:15], v[12:13], v[62:63], v[6:7] op_sel_hi:[0,1,1] neg_lo:[0,0,1] neg_hi:[0,0,1]
	v_pk_fma_f32 v[6:7], v[12:13], v[62:63], v[6:7] op_sel_hi:[0,1,1]
	v_mov_b32_e32 v81, v7
	v_pk_mov_b32 v[82:83], v[6:7], v[14:15] op_sel:[1,0]
	v_pk_mul_f32 v[6:7], v[36:37], v[6:7] op_sel:[1,1] op_sel_hi:[0,1]
	v_mov_b32_e32 v77, v3
	v_mov_b32_e32 v79, v5
	v_pk_mov_b32 v[84:85], v[4:5], v[10:11] op_sel:[1,0]
	v_pk_mov_b32 v[86:87], v[2:3], v[8:9] op_sel:[1,0]
	v_pk_fma_f32 v[2:3], v[36:37], v[14:15], v[6:7] op_sel_hi:[1,0,1] neg_lo:[0,0,1] neg_hi:[0,0,1]
	v_pk_fma_f32 v[4:5], v[36:37], v[14:15], v[6:7] op_sel_hi:[1,0,1]
	v_pk_mov_b32 v[38:39], v[36:37], v[36:37] op_sel:[1,0]
	v_mov_b32_e32 v66, v18
	v_mov_b32_e32 v76, v8
	v_mov_b32_e32 v78, v10
	v_mov_b32_e32 v80, v14
	v_mov_b32_e32 v88, v2
	v_mov_b32_e32 v89, v5
	v_pk_mov_b32 v[90:91], v[4:5], v[2:3] op_sel:[1,0]
.LBB0_639:
	v_cndmask_b32_e64 v2, 0, 1, s[4:5]
	v_cmp_ne_u32_e32 vcc, 1, v2
	v_add_u32_e32 v2, s3, v172
	v_ashrrev_i32_e32 v3, 31, v2
	v_lshrrev_b32_e32 v3, 26, v3
	v_add_lshl_u32 v2, v2, v3, 4
	v_and_b32_e32 v2, 0xfffffc00, v2
	v_or_b32_e32 v3, v2, v173
	v_bitop3_b32 v2, v2, s24, v173 bitop3:0xc8
	v_lshlrev_b32_e32 v3, 3, v3
	v_add3_u32 v127, 0, v2, v3
	v_add_u32_e32 v125, 0x800, v127
	v_add_u32_e32 v124, 0x1400, v127
	ds_read2_b64 v[18:21], v127 offset1:72
	ds_read2_b64 v[2:5], v127 offset0:144 offset1:216
	ds_read2_b64 v[14:17], v125 offset0:32 offset1:104
	ds_read2_b64 v[10:13], v125 offset0:176 offset1:248
	ds_read2_b64 v[6:9], v124 offset0:80 offset1:152
	v_add_u32_e32 v126, 0x1000, v127
	v_add_u32_e32 v123, 0x1800, v127
	ds_read2_b64 v[22:25], v126 offset0:64 offset1:136
	ds_read2_b64 v[26:29], v123 offset0:96 offset1:168
	s_waitcnt lgkmcnt(2)
	v_pk_add_f32 v[92:93], v[4:5], v[8:9] neg_lo:[0,1] neg_hi:[0,1]
	v_add_u32_e32 v122, 0x1c00, v127
	v_mul_f32_e32 v94, 0x3f6c835e, v93
	ds_read2_b64 v[30:33], v122 offset0:112 offset1:184
	v_pk_fma_f32 v[96:97], v[92:93], s[60:61], v[94:95] op_sel_hi:[1,1,0]
	v_mul_f32_e32 v99, 0x3ec3ef15, v93
	v_mul_f32_e32 v128, 0x3f6c835e, v92
	v_pk_mov_b32 v[92:93], v[18:19], v[14:15] op_sel:[1,0]
	s_waitcnt lgkmcnt(1)
	v_pk_mov_b32 v[94:95], v[22:23], v[26:27] op_sel:[1,0]
	v_mov_b32_e32 v100, v22
	v_pk_add_f32 v[92:93], v[92:93], v[94:95] neg_lo:[0,1] neg_hi:[0,1]
	v_mov_b32_e32 v94, v18
	v_mov_b32_e32 v95, v15
	v_mov_b32_e32 v101, v27
	v_pk_add_f32 v[94:95], v[94:95], v[100:101] neg_lo:[0,1] neg_hi:[0,1]
	v_mov_b32_e32 v100, v21
	v_mov_b32_e32 v101, v17
	v_mov_b32_e32 v102, v25
	v_mov_b32_e32 v103, v29
	v_pk_add_f32 v[104:105], v[100:101], v[102:103] neg_lo:[0,1] neg_hi:[0,1]
	v_mov_b32_e32 v100, v20
	v_mov_b32_e32 v101, v16
	v_mov_b32_e32 v102, v24
	v_mov_b32_e32 v103, v28
	v_pk_add_f32 v[106:107], v[100:101], v[102:103] neg_lo:[0,1] neg_hi:[0,1]
	s_mov_b32 s4, s61
	s_mov_b32 s5, s60
	v_pk_mul_f32 v[100:101], v[106:107], s[4:5]
	s_waitcnt lgkmcnt(0)
; #define FFT_HD __device__ __attribute__((always_inline))
; template <int R> FFT_HD inline void dft_fwd_reg(cf2 (&v)[1 << R]) {
;     constexpr int n = 1 << R;
; #pragma unroll
;     for (int s = 0; s < R; ++s) {
;         const int half = n >> (s + 1);
; #pragma unroll
;         for (int m = 0; m < n; ++m) {
;             if ((m & half) == 0) {
;                 const int ml = m & (half - 1), tk = ml * (16 / half);
;                 const cf2 a = v[m], b = v[m + half];
;                 v[m].x = a.x + b.x; v[m].y = a.y + b.y;
;                 const cf2 d = {a.x - b.x, a.y - b.y};
;                 if (tk == 0) v[m + half] = d;
;                 else if (tk == 8) { v[m + half].x = d.y; v[m + half].y = -d.x; }
;                 else { const cf2 w = {fc32(tk), -fs32(tk)}; v[m + half] = cmulf(d, w); }
;             }
;         }
;     }
; }
	v_pk_add_f32 v[112:113], v[10:11], v[30:31] neg_lo:[0,1] neg_hi:[0,1]
	v_pk_add_f32 v[118:119], v[18:19], v[22:23]
	v_pk_add_f32 v[18:19], v[20:21], v[24:25]
	v_pk_add_f32 v[130:131], v[2:3], v[6:7]
	v_pk_add_f32 v[4:5], v[4:5], v[8:9]
	v_pk_add_f32 v[26:27], v[14:15], v[26:27]
	v_pk_add_f32 v[8:9], v[16:17], v[28:29]
	v_pk_add_f32 v[28:29], v[10:11], v[30:31]
	v_pk_add_f32 v[10:11], v[12:13], v[32:33]
	v_mul_f32_e32 v114, 0x3f6c835e, v104
	v_mul_f32_e32 v116, 0x3ec3ef15, v106
	v_pk_fma_f32 v[102:103], v[104:105], s[60:61], v[100:101]
	v_pk_fma_f32 v[100:101], v[104:105], s[60:61], v[100:101] neg_lo:[0,0,1] neg_hi:[0,0,1]
	v_mov_b32_e32 v106, v105
	v_pk_add_f32 v[104:105], v[12:13], v[32:33] neg_lo:[0,1] neg_hi:[0,1]
	v_pk_add_f32 v[12:13], v[118:119], v[26:27]
	v_pk_add_f32 v[14:15], v[18:19], v[8:9]
	v_pk_add_f32 v[24:25], v[18:19], v[8:9] neg_lo:[0,1] neg_hi:[0,1]
	v_pk_add_f32 v[16:17], v[130:131], v[28:29]
	v_pk_add_f32 v[18:19], v[4:5], v[10:11]
	v_pk_add_f32 v[22:23], v[4:5], v[10:11] neg_lo:[0,1] neg_hi:[0,1]
	v_pk_add_f32 v[8:9], v[12:13], v[16:17]
	v_pk_add_f32 v[10:11], v[14:15], v[18:19]
	v_mul_f32_e32 v21, 0x3f3504f3, v24
	v_pk_add_f32 v[4:5], v[8:9], v[10:11]
	v_pk_add_f32 v[10:11], v[8:9], v[10:11] neg_lo:[0,1] neg_hi:[0,1]
	v_pk_add_f32 v[12:13], v[12:13], v[16:17] neg_lo:[0,1] neg_hi:[0,1]
	v_mul_f32_e32 v8, v11, v59
	v_mul_f32_e32 v20, v10, v60
	v_pk_add_f32 v[14:15], v[14:15], v[18:19] neg_lo:[0,1] neg_hi:[0,1]
	v_pk_fma_f32 v[8:9], v[10:11], v[58:59], v[8:9] op_sel_hi:[1,1,0] neg_lo:[0,0,1] neg_hi:[0,0,1]
	v_pk_fma_f32 v[10:11], v[10:11], v[60:61], v[20:21] op_sel_hi:[1,1,0]
	v_pk_add_f32 v[18:19], v[12:13], v[14:15] op_sel:[0,1] op_sel_hi:[1,0] neg_lo:[0,1] neg_hi:[0,1]
	v_pk_add_f32 v[16:17], v[12:13], v[14:15] op_sel:[0,1] op_sel_hi:[1,0]
	v_mov_b32_e32 v15, v19
	v_mov_b32_e32 v14, v16
	v_mul_f32_e32 v10, v19, v49
	v_pk_fma_f32 v[12:13], v[14:15], v[48:49], v[10:11] op_sel_hi:[1,1,0] neg_lo:[0,0,1] neg_hi:[0,0,1]
	v_mul_f32_e32 v10, v16, v50
	v_mul_f32_e32 v32, 0x3f3504f3, v25
	v_mul_f32_e32 v24, 0x3f3504f3, v22
	v_mov_b32_e32 v30, v18
	v_mov_b32_e32 v31, v17
	v_pk_fma_f32 v[14:15], v[14:15], v[50:51], v[10:11] op_sel_hi:[1,1,0]
	v_mul_f32_e32 v10, v17, v71
	v_pk_add_f32 v[26:27], v[118:119], v[26:27] neg_lo:[0,1] neg_hi:[0,1]
	v_pk_add_f32 v[28:29], v[130:131], v[28:29] neg_lo:[0,1] neg_hi:[0,1]
	s_mov_b32 s83, s80
	v_pk_fma_f32 v[16:17], v[30:31], v[70:71], v[10:11] op_sel_hi:[1,1,0] neg_lo:[0,0,1] neg_hi:[0,0,1]
	v_mul_f32_e32 v10, v18, v72
	v_sub_f32_e32 v20, v32, v21
	v_fmac_f32_e32 v21, 0x3f3504f3, v25
	v_pk_fma_f32 v[22:23], v[22:23], s[82:83], v[24:25] op_sel:[1,0,0] op_sel_hi:[1,1,0] neg_lo:[0,0,1] neg_hi:[0,0,1]
	v_pk_add_f32 v[24:25], v[26:27], v[28:29] op_sel:[0,1] op_sel_hi:[1,0] neg_lo:[0,1] neg_hi:[0,1]
	v_pk_add_f32 v[26:27], v[26:27], v[28:29] op_sel:[0,1] op_sel_hi:[1,0]
	v_pk_fma_f32 v[18:19], v[30:31], v[72:73], v[10:11] op_sel_hi:[1,1,0]
	v_mov_b32_e32 v28, v24
	v_pk_add_f32 v[30:31], v[20:21], v[22:23] neg_lo:[0,1] neg_hi:[0,1]
	v_pk_mov_b32 v[24:25], v[24:25], v[26:27] op_sel:[1,0]
	v_pk_add_f32 v[20:21], v[20:21], v[22:23]
	v_mov_b32_e32 v29, v27
	v_pk_add_f32 v[22:23], v[24:25], v[20:21]
	v_pk_add_f32 v[26:27], v[24:25], v[20:21] neg_lo:[0,1] neg_hi:[0,1]
	v_mul_f32_e32 v10, v43, v23
	v_pk_fma_f32 v[20:21], v[42:43], v[22:23], v[10:11] op_sel_hi:[1,1,0] neg_lo:[1,0,0] neg_hi:[1,0,0]
	v_mul_f32_e32 v10, v40, v22
	s_mov_b32 s79, s61
	v_mul_f32_e32 v98, 0x3f6c835e, v107
	v_pk_fma_f32 v[22:23], v[40:41], v[22:23], v[10:11] op_sel_hi:[1,1,0]
	v_mul_f32_e32 v10, v27, v69
	v_pk_mov_b32 v[2:3], v[2:3], v[2:3] op_sel:[1,0]
	v_pk_mov_b32 v[6:7], v[6:7], v[6:7] op_sel:[1,0]
	v_pk_fma_f32 v[120:121], v[106:107], s[78:79], v[98:99] op_sel_hi:[1,1,0] neg_lo:[0,0,1] neg_hi:[0,0,1]
	v_mul_f32_e32 v98, 0xbf6c835e, v105
	v_pk_add_f32 v[118:119], v[28:29], v[30:31] neg_lo:[0,1] neg_hi:[0,1]
	v_pk_add_f32 v[32:33], v[28:29], v[30:31]
	v_pk_fma_f32 v[24:25], v[26:27], v[68:69], v[10:11] op_sel_hi:[1,1,0] neg_lo:[1,0,0] neg_hi:[1,0,0]
	v_mul_f32_e32 v10, v27, v68
	v_mov_b32_e32 v115, v3
	v_mov_b32_e32 v117, v7
	v_pk_fma_f32 v[106:107], v[104:105], s[78:79], v[98:99] op_sel_hi:[1,1,0]
	v_pk_fma_f32 v[26:27], v[26:27], v[68:69], v[10:11] op_sel:[1,0,0] op_sel_hi:[0,1,0]
	v_mov_b32_e32 v30, v32
	v_mov_b32_e32 v31, v119
	v_mul_f32_e32 v10, v119, v55
	v_pk_add_f32 v[114:115], v[114:115], v[116:117] neg_lo:[0,1] neg_hi:[0,1]
	v_mov_b32_e32 v3, v99
	v_mov_b32_e32 v7, v128
	v_pk_fma_f32 v[28:29], v[30:31], v[54:55], v[10:11] op_sel_hi:[1,1,0] neg_lo:[0,0,1] neg_hi:[0,0,1]
	v_mul_f32_e32 v10, v32, v56
	v_pk_add_f32 v[6:7], v[2:3], v[6:7] neg_lo:[0,1] neg_hi:[0,1]
	v_pk_add_f32 v[2:3], v[114:115], v[120:121]
	v_mov_b32_e32 v186, v120
	v_pk_add_f32 v[116:117], v[114:115], v[120:121] neg_lo:[0,1] neg_hi:[0,1]
	v_mov_b32_e32 v120, v187
	v_mov_b32_e32 v121, v106
	v_mov_b32_e32 v130, v118
	v_mov_b32_e32 v131, v33
	v_pk_fma_f32 v[30:31], v[30:31], v[56:57], v[10:11] op_sel_hi:[1,1,0]
	v_mul_f32_e32 v10, v33, v81
	v_pk_mul_f32 v[114:115], v[114:115], v[186:187]
	v_pk_mul_f32 v[128:129], v[6:7], v[120:121]
	v_pk_add_f32 v[120:121], v[6:7], v[120:121] neg_lo:[0,1] neg_hi:[0,1]
	v_pk_mul_f32 v[108:109], v[112:113], s[80:81] op_sel_hi:[1,0]
	v_pk_mul_f32 v[110:111], v[104:105], s[4:5]
	v_pk_fma_f32 v[32:33], v[130:131], v[80:81], v[10:11] op_sel_hi:[1,1,0] neg_lo:[0,0,1] neg_hi:[0,0,1]
	v_mul_f32_e32 v10, v118, v82
	v_mov_b32_e32 v117, v115
	v_mov_b32_e32 v129, v121
	s_mov_b32 s3, s80
	v_mov_b32_e32 v114, v115
	v_mov_b32_e32 v115, v187
	v_pk_fma_f32 v[118:119], v[130:131], v[82:83], v[10:11] op_sel_hi:[1,1,0]
	v_mov_b32_e32 v131, v128
; #define FFT_HD __device__ __attribute__((always_inline))
; template <int R> FFT_HD inline void dft_fwd_reg(cf2 (&v)[1 << R]) {
;     constexpr int n = 1 << R;
; #pragma unroll
;     for (int s = 0; s < R; ++s) {
;         const int half = n >> (s + 1);
; #pragma unroll
;         for (int m = 0; m < n; ++m) {
;             if ((m & half) == 0) {
;                 const int ml = m & (half - 1), tk = ml * (16 / half);
;                 const cf2 a = v[m], b = v[m + half];
;                 v[m].x = a.x + b.x; v[m].y = a.y + b.y;
;                 const cf2 d = {a.x - b.x, a.y - b.y};
;                 if (tk == 0) v[m + half] = d;
;                 else if (tk == 8) { v[m + half].x = d.y; v[m + half].y = -d.x; }
;                 else { const cf2 w = {fc32(tk), -fs32(tk)}; v[m + half] = cmulf(d, w); }
;             }
;         }
;     }
; }
; template <int R, int F, bool CONJ> FFT_HD inline void tw_apply(cf2 (&v)[1 << R], cf2 pf, cf2 th) {
;     constexpr int j = fbrev(F, R);
;     v[j] = CONJ ? cmulcf(v[j], pf) : cmulf(v[j], pf);
;     if constexpr (2 * F < (1 << R)) {
;         const cf2 p2 = cmulf(pf, pf);
;         tw_apply<R, 2 * F, CONJ>(v, p2, th);
;         const cf2 p3 = cmulf(p2, th);
;         tw_apply<R, 2 * F + 1, CONJ>(v, p3, th);
;     }
; }
	v_pk_add_f32 v[114:115], v[128:129], v[114:115] neg_lo:[0,1] neg_hi:[0,1]
	v_pk_mul_f32 v[128:129], v[120:121], s[2:3]
	v_mul_f32_e32 v103, 0xbf3504f3, v121
	v_mov_b32_e32 v120, v109
	v_mov_b32_e32 v121, v111
	v_mov_b32_e32 v109, v110
	v_mov_b32_e32 v186, v108
	v_pk_add_f32 v[108:109], v[120:121], v[108:109] neg_lo:[0,1] neg_hi:[0,1]
	v_pk_mov_b32 v[112:113], v[112:113], v[96:97] op_sel:[1,0]
	v_mov_b32_e32 v110, v94
	v_mov_b32_e32 v111, v102
	v_mov_b32_e32 v100, v95
	v_mov_b32_e32 v189, v109
	v_sub_f32_e32 v98, v102, v101
	v_pk_add_f32 v[100:101], v[110:111], v[100:101]
	v_pk_mul_f32 v[110:111], v[112:113], v[188:189]
	v_pk_add_f32 v[112:113], v[112:113], v[108:109] neg_lo:[0,1] neg_hi:[0,1]
	v_mov_b32_e32 v130, v187
	v_mov_b32_e32 v111, v113
	v_pk_mul_f32 v[132:133], v[116:117], v[130:131]
	v_pk_add_f32 v[116:117], v[116:117], v[130:131]
	v_pk_add_f32 v[112:113], v[110:111], v[186:187] neg_lo:[0,1] neg_hi:[0,1]
	v_pk_add_f32 v[104:105], v[92:93], v[92:93] op_sel:[0,1] op_sel_hi:[1,0] neg_lo:[0,1] neg_hi:[0,1]
	v_pk_mov_b32 v[96:97], v[116:117], v[96:97] op_sel:[1,0]
	v_pk_mul_f32 v[110:111], v[110:111], v[186:187]
	v_pk_mov_b32 v[6:7], v[6:7], v[114:115] op_sel:[1,0]
	v_mov_b32_e32 v107, v112
	v_mov_b32_e32 v128, v114
	v_pk_add_f32 v[96:97], v[96:97], v[108:109]
	v_mov_b32_e32 v113, v111
	v_pk_add_f32 v[6:7], v[6:7], v[106:107]
	v_mov_b32_e32 v114, v2
	v_mov_b32_e32 v115, v104
	v_pk_add_f32 v[106:107], v[128:129], v[112:113] neg_lo:[0,1] neg_hi:[0,1]
	v_pk_add_f32 v[114:115], v[114:115], v[6:7] neg_lo:[0,1] neg_hi:[0,1]
	v_mov_b32_e32 v128, v100
	v_mov_b32_e32 v129, v104
	v_mov_b32_e32 v104, v96
	v_mov_b32_e32 v105, v7
	v_pk_mov_b32 v[2:3], v[100:101], v[2:3] op_sel:[1,0]
	v_pk_mov_b32 v[6:7], v[96:97], v[6:7] op_sel:[1,0]
	v_pk_add_f32 v[104:105], v[128:129], v[104:105]
	v_pk_add_f32 v[2:3], v[2:3], v[6:7]
	v_mul_f32_e32 v98, 0x3f3504f3, v98
	v_pk_add_f32 v[6:7], v[104:105], v[2:3] neg_lo:[0,1] neg_hi:[0,1]
	v_pk_add_f32 v[2:3], v[104:105], v[2:3]
	v_mov_b32_e32 v133, v117
	v_mov_b32_e32 v99, v108
	v_mul_f32_e32 v10, v37, v3
	v_pk_add_f32 v[108:109], v[132:133], v[98:99] neg_lo:[0,1] neg_hi:[0,1]
	v_pk_add_f32 v[112:113], v[100:101], v[96:97] neg_lo:[0,1] neg_hi:[0,1]
	v_pk_fma_f32 v[96:97], v[36:37], v[2:3], v[10:11] op_sel_hi:[1,1,0] neg_lo:[0,0,1] neg_hi:[0,0,1]
	v_mul_f32_e32 v10, v38, v2
	v_mov_b32_e32 v99, v92
	v_mov_b32_e32 v133, v93
	v_mov_b32_e32 v102, v94
	v_mov_b32_e32 v110, v95
	v_pk_fma_f32 v[2:3], v[38:39], v[2:3], v[10:11] op_sel_hi:[1,1,0]
	v_pk_add_f32 v[92:93], v[98:99], v[132:133]
	v_pk_add_f32 v[94:95], v[102:103], v[110:111] neg_lo:[0,1] neg_hi:[0,1]
	v_mov_b32_e32 v102, v107
	v_mov_b32_e32 v103, v109
	v_pk_add_f32 v[116:117], v[112:113], v[114:115] neg_lo:[0,1] neg_hi:[0,1]
	v_pk_add_f32 v[120:121], v[112:113], v[114:115]
	v_mul_f32_e32 v2, v7, v67
	v_pk_add_f32 v[104:105], v[114:115], v[112:113] neg_lo:[0,1] neg_hi:[0,1]
	v_pk_add_f32 v[110:111], v[92:93], v[102:103]
	v_pk_add_f32 v[102:103], v[92:93], v[102:103] neg_lo:[0,1] neg_hi:[0,1]
	v_mov_b32_e32 v114, v106
	v_mov_b32_e32 v115, v108
	v_pk_fma_f32 v[100:101], v[6:7], v[66:67], v[2:3] op_sel_hi:[1,1,0] neg_lo:[0,0,1] neg_hi:[0,0,1]
	v_mul_f32_e32 v2, v6, v74
	v_mov_b32_e32 v99, v92
	v_mov_b32_e32 v111, v103
	v_pk_add_f32 v[114:115], v[94:95], v[114:115]
	v_mov_b32_e32 v92, v95
	v_pk_fma_f32 v[6:7], v[6:7], v[74:75], v[2:3] op_sel_hi:[1,1,0]
	v_pk_mov_b32 v[112:113], v[104:105], v[120:121] op_sel:[1,0]
	v_mul_f32_e32 v2, v120, v53
	v_mov_b32_e32 v98, v94
	v_pk_add_f32 v[94:95], v[108:109], v[92:93] neg_lo:[0,1] neg_hi:[0,1]
	v_pk_add_f32 v[92:93], v[108:109], v[92:93]
	v_pk_add_f32 v[108:109], v[114:115], v[110:111]
	v_mov_b32_e32 v102, v114
	v_mov_b32_e32 v111, v115
	v_pk_fma_f32 v[112:113], v[112:113], v[52:53], v[2:3] op_sel_hi:[1,1,0] neg_lo:[1,0,0] neg_hi:[1,0,0]
	v_mov_b32_e32 v104, v120
	v_mul_f32_e32 v2, v120, v52
	v_pk_add_f32 v[102:103], v[102:103], v[110:111] neg_lo:[0,1] neg_hi:[0,1]
	v_pk_fma_f32 v[104:105], v[104:105], v[52:53], v[2:3] op_sel_hi:[1,1,0]
	v_mul_f32_e32 v2, v103, v77
	v_pk_fma_f32 v[110:111], v[102:103], v[76:77], v[2:3] op_sel_hi:[1,1,0] neg_lo:[0,0,1] neg_hi:[0,0,1]
	v_mul_f32_e32 v2, v102, v86
	v_pk_fma_f32 v[102:103], v[102:103], v[86:87], v[2:3] op_sel_hi:[1,1,0]
	v_mul_f32_e32 v2, v45, v109
	v_pk_fma_f32 v[114:115], v[44:45], v[108:109], v[2:3] op_sel_hi:[1,1,0] neg_lo:[0,0,1] neg_hi:[0,0,1]
	v_mul_f32_e32 v2, v46, v108
	v_mov_b32_e32 v117, v121
	v_pk_add_f32 v[98:99], v[98:99], v[106:107] neg_lo:[0,1] neg_hi:[0,1]
	v_mov_b32_e32 v106, v94
	v_mov_b32_e32 v107, v93
	v_pk_fma_f32 v[108:109], v[46:47], v[108:109], v[2:3] op_sel_hi:[1,1,0]
	v_mul_f32_e32 v2, v121, v79
	v_pk_add_f32 v[106:107], v[98:99], v[106:107]
	v_pk_fma_f32 v[120:121], v[116:117], v[78:79], v[2:3] op_sel_hi:[1,1,0] neg_lo:[0,0,1] neg_hi:[0,0,1]
	v_mul_f32_e32 v2, v116, v84
	v_pk_add_f32 v[92:93], v[92:93], v[98:99] neg_lo:[0,1] neg_hi:[0,1]
	v_pk_fma_f32 v[116:117], v[116:117], v[84:85], v[2:3] op_sel_hi:[1,1,0]
	v_mov_b32_e32 v92, v106
	v_mul_f32_e32 v2, v93, v63
	v_pk_add_f32 v[94:95], v[98:99], v[94:95] neg_lo:[0,1] neg_hi:[0,1]
	v_pk_fma_f32 v[98:99], v[92:93], v[62:63], v[2:3] op_sel_hi:[1,1,0] neg_lo:[0,0,1] neg_hi:[0,0,1]
	v_mul_f32_e32 v2, v106, v64
	v_mov_b32_e32 v95, v107
	v_pk_fma_f32 v[92:93], v[92:93], v[64:65], v[2:3] op_sel_hi:[1,1,0]
	v_mul_f32_e32 v2, v107, v89
	v_pk_fma_f32 v[106:107], v[94:95], v[88:89], v[2:3] op_sel_hi:[1,1,0] neg_lo:[0,0,1] neg_hi:[0,0,1]
	v_mul_f32_e32 v2, v94, v90
	v_pk_fma_f32 v[94:95], v[94:95], v[90:91], v[2:3] op_sel_hi:[1,1,0]
	v_mov_b32_e32 v9, v11
	v_mov_b32_e32 v13, v15
	v_mov_b32_e32 v17, v19
	v_mov_b32_e32 v21, v23
	v_mov_b32_e32 v25, v27
	v_mov_b32_e32 v29, v31
	v_mov_b32_e32 v33, v119
	v_mov_b32_e32 v97, v3
	v_mov_b32_e32 v101, v7
	v_mov_b32_e32 v113, v105
	v_mov_b32_e32 v121, v117
	v_mov_b32_e32 v115, v109
	v_mov_b32_e32 v111, v103
	v_mov_b32_e32 v99, v93
	v_mov_b32_e32 v107, v95
	s_movk_i32 s3, 0x200
	s_mov_b64 s[4:5], 0
	s_and_b64 vcc, exec, vcc
	ds_write2_b64 v127, v[4:5], v[8:9] offset1:72
	ds_write2_b64 v127, v[12:13], v[16:17] offset0:144 offset1:216
	ds_write2_b64 v125, v[20:21], v[24:25] offset0:32 offset1:104
	ds_write2_b64 v125, v[28:29], v[32:33] offset0:176 offset1:248
	ds_write2_b64 v126, v[96:97], v[100:101] offset0:64 offset1:136
	ds_write2_b64 v124, v[112:113], v[120:121] offset0:80 offset1:152
	ds_write2_b64 v123, v[114:115], v[110:111] offset0:96 offset1:168
	ds_write2_b64 v122, v[98:99], v[106:107] offset0:112 offset1:184
	s_cbranch_vccz .LBB0_639
; #define FFT_HD __device__ __attribute__((always_inline))
; template <int R> FFT_HD inline void reg_fwd(cf2 (&v)[1 << R], cf2 th) { dft_fwd_reg<R>(v); tw_apply<R, 1, false>(v, th, th); }
; template <int R, int F, bool CONJ> FFT_HD inline void tw_apply(cf2 (&v)[1 << R], cf2 pf, cf2 th) {
;     constexpr int j = fbrev(F, R);
;     v[j] = CONJ ? cmulcf(v[j], pf) : cmulf(v[j], pf);
;     if constexpr (2 * F < (1 << R)) {
;         const cf2 p2 = cmulf(pf, pf);
;         tw_apply<R, 2 * F, CONJ>(v, p2, th);
;         const cf2 p3 = cmulf(p2, th);
;         tw_apply<R, 2 * F + 1, CONJ>(v, p3, th);
;     }
; }
; __device__ __forceinline__ void s_mid2(ldsc X, const cf2* TW, int tid) {
;     ...
; #pragma unroll 1
;     for (int q = 0; q < 4; ++q) { const int grp = tid + 512 * q; cf2 v[8]; grp_load<3, 8>(X, grp, v); reg_fwd<3>(v, TW[(grp & 7) * 256]); grp_store<3, 8>(X, grp, v); }
	v_lshlrev_b32_e32 v2, 11, v172
	v_and_b32_e32 v182, 0x3800, v2
	s_waitcnt lgkmcnt(0)
	s_barrier
	v_mov_b32_e32 v2, v204
	v_mov_b32_e32 v3, v205
	v_and_b32_e32 v30, 7, v172
	v_lshl_add_u64 v[36:37], s[36:37], 0, v[182:183]
	s_mov_b32 s3, 0
	v_lshlrev_b32_e32 v174, 3, v30
	v_pk_mul_f32 v[6:7], v[2:3], v[2:3] op_sel:[1,1] op_sel_hi:[0,1]
	v_pk_fma_f32 v[14:15], v[2:3], v[2:3], v[6:7] op_sel_hi:[0,1,1] neg_lo:[0,0,1] neg_hi:[0,0,1]
	v_pk_fma_f32 v[16:17], v[2:3], v[2:3], v[6:7] op_sel_hi:[0,1,1]
	v_mov_b32_e32 v6, v14
	v_mov_b32_e32 v7, v17
	v_mul_f32_e32 v8, v17, v17
	v_pk_mul_f32 v[10:11], v[6:7], v[16:17] op_sel:[0,1] op_sel_hi:[1,0]
	v_pk_mov_b32 v[12:13], v[16:17], v[14:15] op_sel:[1,0]
	v_pk_mul_f32 v[16:17], v[2:3], v[16:17] op_sel:[1,1] op_sel_hi:[0,1]
	v_pk_fma_f32 v[18:19], v[2:3], v[14:15], v[16:17] op_sel_hi:[1,0,1] neg_lo:[0,0,1] neg_hi:[0,0,1]
	v_pk_fma_f32 v[20:21], v[2:3], v[14:15], v[16:17] op_sel_hi:[1,0,1]
	v_mov_b32_e32 v14, v18
	v_pk_mov_b32 v[16:17], v[20:21], v[18:19] op_sel:[1,0]
	v_mov_b32_e32 v15, v21
	v_pk_mul_f32 v[20:21], v[20:21], v[16:17] op_sel:[1,0]
	v_pk_fma_f32 v[8:9], v[6:7], v[6:7], v[8:9] op_sel_hi:[1,1,0] neg_lo:[0,0,1] neg_hi:[0,0,1]
	v_pk_fma_f32 v[22:23], v[18:19], v[14:15], v[20:21] op_sel_hi:[0,1,1] neg_lo:[0,0,1] neg_hi:[0,0,1]
	v_pk_fma_f32 v[24:25], v[18:19], v[14:15], v[20:21] op_sel_hi:[0,1,1]
	v_mov_b32_e32 v19, v25
	v_pk_mov_b32 v[20:21], v[24:25], v[22:23] op_sel:[1,0]
	v_pk_mul_f32 v[24:25], v[2:3], v[24:25] op_sel:[1,1] op_sel_hi:[0,1]
	v_pk_add_f32 v[10:11], v[10:11], v[10:11]
	v_pk_fma_f32 v[26:27], v[2:3], v[22:23], v[24:25] op_sel_hi:[1,0,1] neg_lo:[0,0,1] neg_hi:[0,0,1]
	v_pk_fma_f32 v[24:25], v[2:3], v[22:23], v[24:25] op_sel_hi:[1,0,1]
	v_mul_f32_e32 v9, v2, v8
	v_mul_f32_e32 v28, v3, v8
	v_mov_b32_e32 v18, v22
	v_mov_b32_e32 v22, v26
	v_mov_b32_e32 v23, v25
	v_pk_mov_b32 v[24:25], v[24:25], v[26:27] op_sel:[1,0]
	v_fma_f32 v26, -v3, v10, v9
	v_fmac_f32_e32 v28, v2, v10
	v_pk_mov_b32 v[4:5], v[2:3], v[2:3] op_sel:[1,0]
	v_mov_b32_e32 v27, v26
	v_mov_b32_e32 v9, v8
	v_mov_b32_e32 v11, v10
	v_mov_b32_e32 v29, v28

; #define FFT_HD __device__ __attribute__((always_inline))
; template <int R> FFT_HD inline void reg_inv(cf2 (&v)[1 << R], cf2 th) { tw_apply<R, 1, true>(v, th, th); dft_inv_reg<R>(v); }
; template <int R> FFT_HD inline void dft_inv_reg(cf2 (&v)[1 << R]) {
;     constexpr int n = 1 << R;
; #pragma unroll
;     for (int s = R - 1; s >= 0; --s) {
;         const int half = n >> (s + 1);
; #pragma unroll
;         for (int m = 0; m < n; ++m) {
;             if ((m & half) == 0) {
;                 const int ml = m & (half - 1), tk = ml * (16 / half);
;                 const cf2 a = v[m], bb = v[m + half]; cf2 b;
;                 if (tk == 0) b = bb;
;                 else if (tk == 8) { b.x = -bb.y; b.y = bb.x; }
;                 else { const cf2 w = {fc32(tk), -fs32(tk)}; b = cmulcf(bb, w); }
;                 v[m].x = a.x + b.x; v[m].y = a.y + b.y; v[m + half].x = a.x - b.x; v[m + half].y = a.y - b.y;
;             }
;         }
;     }
; }
; __device__ __forceinline__ void s_mid2(ldsc X, const cf2* TW, int tid) {
;     ...
;     for (int q = 0; q < 4; ++q) { const int grp = tid + 512 * q; cf2 v[8]; grp_load<3, 1>(X, grp, v); dft_inv_reg<3>(v); grp_store<3, 1>(X, grp, v); }
;     __syncthreads();
; #pragma unroll 1
;     for (int q = 0; q < 4; ++q) { const int grp = tid + 512 * q; cf2 v[8]; grp_load<3, 8>(X, grp, v); reg_inv<3>(v, TW[(grp & 7) * 256]); grp_store<3, 8>(X, grp, v); }
.LBB0_655:
	v_add_u32_e32 v26, s3, v175
	ds_read2_b64 v[2:5], v26 offset1:1
	ds_read2_b64 v[6:9], v26 offset0:2 offset1:3
	ds_read2_b64 v[10:13], v26 offset0:4 offset1:5
	ds_read2_b64 v[14:17], v26 offset0:6 offset1:7
	s_mov_b32 s83, s80
	s_add_i32 s3, s3, 0x9000
	s_waitcnt lgkmcnt(2)
	v_pk_add_f32 v[24:25], v[6:7], v[8:9]
	s_waitcnt lgkmcnt(1)
	v_mov_b32_e32 v22, v12
	s_waitcnt lgkmcnt(0)
	v_pk_mov_b32 v[18:19], v[10:11], v[14:15] op_sel:[1,0]
	v_pk_mov_b32 v[20:21], v[12:13], v[16:17] op_sel:[1,0]
	v_mov_b32_e32 v23, v17
	v_pk_add_f32 v[18:19], v[18:19], v[20:21] neg_lo:[0,1] neg_hi:[0,1]
	v_mov_b32_e32 v20, v10
	v_mov_b32_e32 v21, v15
	v_pk_add_f32 v[20:21], v[20:21], v[22:23] neg_lo:[0,1] neg_hi:[0,1]
	v_add_f32_e32 v22, v18, v19
	v_sub_f32_e32 v27, v20, v21
	v_sub_f32_e32 v18, v18, v19
	v_mul_f32_e32 v19, 0x3f3504f3, v22
	v_pk_add_f32 v[22:23], v[2:3], v[4:5]
	v_pk_add_f32 v[10:11], v[10:11], v[12:13]
	v_pk_add_f32 v[12:13], v[14:15], v[16:17]
	v_pk_add_f32 v[2:3], v[2:3], v[4:5] neg_lo:[0,1] neg_hi:[0,1]
	v_pk_add_f32 v[4:5], v[6:7], v[8:9] neg_lo:[0,1] neg_hi:[0,1]
	v_mul_f32_e32 v28, 0x3f3504f3, v27
	v_pk_add_f32 v[14:15], v[22:23], v[24:25] neg_lo:[0,1] neg_hi:[0,1]
	v_pk_add_f32 v[16:17], v[10:11], v[12:13] neg_lo:[0,1] neg_hi:[0,1]
	v_pk_add_f32 v[22:23], v[22:23], v[24:25]
	v_pk_add_f32 v[10:11], v[10:11], v[12:13]
	v_pk_add_f32 v[6:7], v[2:3], v[4:5] op_sel:[0,1] op_sel_hi:[1,0]
	v_pk_add_f32 v[2:3], v[2:3], v[4:5] op_sel:[0,1] op_sel_hi:[1,0] neg_lo:[0,1] neg_hi:[0,1]
	v_pk_add_f32 v[12:13], v[22:23], v[10:11]
	v_pk_add_f32 v[10:11], v[22:23], v[10:11] neg_lo:[0,1] neg_hi:[0,1]
	v_pk_add_f32 v[22:23], v[14:15], v[16:17] op_sel:[0,1] op_sel_hi:[1,0] neg_lo:[0,1] neg_hi:[0,1]
	v_pk_add_f32 v[14:15], v[14:15], v[16:17] op_sel:[0,1] op_sel_hi:[1,0]
	v_mul_f32_e32 v16, 0x3f3504f3, v18
	v_mov_b32_e32 v5, v3
	v_sub_f32_e32 v18, v28, v19
	v_fmac_f32_e32 v19, 0x3f3504f3, v27
	v_mov_b32_e32 v3, v7
	v_pk_add_f32 v[8:9], v[20:21], v[20:21] op_sel:[0,1] op_sel_hi:[0,1]
	v_mov_b32_e32 v4, v6
	v_pk_add_f32 v[6:7], v[2:3], v[18:19]
	v_pk_fma_f32 v[8:9], v[8:9], s[82:83], v[16:17] op_sel_hi:[1,1,0] neg_lo:[0,0,1] neg_hi:[0,0,1]
	ds_write2_b64 v26, v[12:13], v[6:7] offset1:1
	v_pk_add_f32 v[16:17], v[4:5], v[8:9]
	v_pk_add_f32 v[4:5], v[4:5], v[8:9] neg_lo:[0,1] neg_hi:[0,1]
	v_mov_b32_e32 v6, v22
	v_mov_b32_e32 v7, v15
	v_mov_b32_e32 v15, v23
	s_cmp_eq_u32 s3, 0x24000
	v_pk_add_f32 v[2:3], v[2:3], v[18:19] neg_lo:[0,1] neg_hi:[0,1]
	ds_write2_b64 v26, v[6:7], v[16:17] offset0:2 offset1:3
	ds_write2_b64 v26, v[10:11], v[2:3] offset0:4 offset1:5
	ds_write2_b64 v26, v[14:15], v[4:5] offset0:6 offset1:7
	s_cbranch_scc0 .LBB0_655
	s_waitcnt lgkmcnt(0)
	s_barrier
	v_mov_b32_e32 v2, v204
	v_mov_b32_e32 v3, v205
	s_mov_b32 s3, 0
	v_pk_mul_f32 v[8:9], v[2:3], v[2:3] op_sel:[0,1] op_sel_hi:[1,0]
	v_mul_f32_e32 v6, v3, v3
	v_pk_add_f32 v[8:9], v[8:9], v[8:9]
	v_pk_fma_f32 v[6:7], v[2:3], v[2:3], v[6:7] op_sel_hi:[1,1,0] neg_lo:[0,0,1] neg_hi:[0,0,1]
	v_pk_mul_f32 v[16:17], v[2:3], v[8:9]
	v_pk_mul_f32 v[14:15], v[2:3], v[8:9] op_sel:[1,0] op_sel_hi:[0,1]
	v_pk_fma_f32 v[16:17], v[2:3], v[6:7], v[16:17] op_sel:[1,0,0] op_sel_hi:[0,1,1]
	v_pk_mul_f32 v[10:11], v[8:9], v[8:9]
	v_pk_fma_f32 v[14:15], v[2:3], v[6:7], v[14:15] neg_lo:[0,0,1] neg_hi:[0,0,1]
	v_pk_mul_f32 v[20:21], v[16:17], v[16:17]
	v_pk_mul_f32 v[12:13], v[6:7], v[8:9]
	v_pk_fma_f32 v[10:11], v[6:7], v[6:7], v[10:11] neg_lo:[0,0,1] neg_hi:[0,0,1]
	v_pk_mul_f32 v[22:23], v[14:15], v[16:17]
	v_pk_fma_f32 v[20:21], v[14:15], v[14:15], v[20:21] neg_lo:[0,0,1] neg_hi:[0,0,1]
	v_pk_add_f32 v[12:13], v[12:13], v[12:13]
	v_mul_f32_e32 v18, v3, v10
	v_mul_f32_e32 v19, v2, v10
	v_pk_add_f32 v[22:23], v[22:23], v[22:23]
	v_mul_f32_e32 v26, v3, v20
	v_mul_f32_e32 v27, v2, v20
	v_fmac_f32_e32 v18, v2, v12
	v_fma_f32 v24, -v3, v12, v19
	v_fmac_f32_e32 v26, v2, v22
	v_fma_f32 v28, -v3, v22, v27
	v_pk_mov_b32 v[4:5], v[2:3], v[2:3] op_sel:[1,0]
	v_mov_b32_e32 v9, v8
	v_mov_b32_e32 v7, v6
	v_mov_b32_e32 v11, v10
	v_mov_b32_e32 v17, v16
	v_mov_b32_e32 v13, v12
	v_mov_b32_e32 v15, v14
	v_mov_b32_e32 v23, v22
	v_mov_b32_e32 v19, v18
	v_mov_b32_e32 v21, v20
	v_mov_b32_e32 v25, v24
	v_mov_b32_e32 v27, v26
	v_mov_b32_e32 v29, v28
; #define FFT_HD __device__ __attribute__((always_inline))
; template <int R> FFT_HD inline void reg_inv(cf2 (&v)[1 << R], cf2 th) { tw_apply<R, 1, true>(v, th, th); dft_inv_reg<R>(v); }
; template <int R> FFT_HD inline void dft_inv_reg(cf2 (&v)[1 << R]) {
;     constexpr int n = 1 << R;
; #pragma unroll
;     for (int s = R - 1; s >= 0; --s) {
;         const int half = n >> (s + 1);
; #pragma unroll
;         for (int m = 0; m < n; ++m) {
;             if ((m & half) == 0) {
;                 const int ml = m & (half - 1), tk = ml * (16 / half);
;                 const cf2 a = v[m], bb = v[m + half]; cf2 b;
;                 if (tk == 0) b = bb;
;                 else if (tk == 8) { b.x = -bb.y; b.y = bb.x; }
;                 else { const cf2 w = {fc32(tk), -fs32(tk)}; b = cmulcf(bb, w); }
;                 v[m].x = a.x + b.x; v[m].y = a.y + b.y; v[m + half].x = a.x - b.x; v[m + half].y = a.y - b.y;
;             }
;         }
;     }
; }
; template <int R, int F, bool CONJ> FFT_HD inline void tw_apply(cf2 (&v)[1 << R], cf2 pf, cf2 th) {
;     constexpr int j = fbrev(F, R);
;     v[j] = CONJ ? cmulcf(v[j], pf) : cmulf(v[j], pf);
;     if constexpr (2 * F < (1 << R)) {
;         const cf2 p2 = cmulf(pf, pf);
;         tw_apply<R, 2 * F, CONJ>(v, p2, th);
;         const cf2 p3 = cmulf(p2, th);
;         tw_apply<R, 2 * F + 1, CONJ>(v, p3, th);
;     }
; }
; __device__ __forceinline__ void s_mid2(ldsc X, const cf2* TW, int tid) {
;     ...
; #pragma unroll 1
;     for (int q = 0; q < 4; ++q) { const int grp = tid + 512 * q; cf2 v[8]; grp_load<3, 8>(X, grp, v); reg_inv<3>(v, TW[(grp & 7) * 256]); grp_store<3, 8>(X, grp, v); }
.LBB0_657:
	v_add_u32_e32 v30, s3, v172
	v_ashrrev_i32_e32 v31, 31, v30
	v_lshrrev_b32_e32 v31, 29, v31
	v_add_u32_e32 v30, v30, v31
	v_ashrrev_i32_e32 v30, 3, v30
	v_lshl_add_u32 v31, v30, 6, 0
	v_lshlrev_b32_e32 v30, 9, v30
	v_add3_u32 v68, v31, v30, v174
	ds_read2_b64 v[38:41], v68 offset1:9
	ds_read2_b64 v[30:33], v68 offset0:18 offset1:27
	ds_read2_b64 v[42:45], v68 offset0:36 offset1:45
	ds_read2_b64 v[46:49], v68 offset0:54 offset1:63
	s_mov_b32 s83, s80
	s_addk_i32 s3, 0x200
	s_waitcnt lgkmcnt(2)
	v_pk_mul_f32 v[50:51], v[30:31], v[8:9]
	s_cmpk_eq_i32 s3, 0x800
	v_pk_fma_f32 v[52:53], v[30:31], v[6:7], v[50:51] op_sel:[1,0,0] op_sel_hi:[0,1,1] neg_lo:[0,0,1] neg_hi:[0,0,1]
	v_pk_fma_f32 v[30:31], v[30:31], v[6:7], v[50:51] op_sel:[1,0,0] op_sel_hi:[0,1,1]
	v_mov_b32_e32 v53, v31
	v_pk_mul_f32 v[30:31], v[40:41], v[12:13] op_sel:[1,0] op_sel_hi:[0,1]
	v_pk_fma_f32 v[50:51], v[40:41], v[10:11], v[30:31]
	v_pk_fma_f32 v[30:31], v[40:41], v[10:11], v[30:31] neg_lo:[0,0,1] neg_hi:[0,0,1]
	s_nop 0
	v_mov_b32_e32 v51, v31
	v_pk_mul_f32 v[30:31], v[32:33], v[22:23]
	s_nop 0
	v_pk_fma_f32 v[40:41], v[32:33], v[20:21], v[30:31] op_sel:[1,0,0] op_sel_hi:[0,1,1] neg_lo:[0,0,1] neg_hi:[0,0,1]
	v_pk_fma_f32 v[30:31], v[32:33], v[20:21], v[30:31] op_sel:[1,0,0] op_sel_hi:[0,1,1]
	v_mov_b32_e32 v41, v31
	v_pk_add_f32 v[30:31], v[38:39], v[50:51] neg_lo:[0,1] neg_hi:[0,1]
	v_pk_add_f32 v[32:33], v[52:53], v[40:41] neg_lo:[0,1] neg_hi:[0,1]
	v_pk_add_f32 v[38:39], v[38:39], v[50:51]
	v_pk_add_f32 v[54:55], v[30:31], v[32:33]
	v_pk_add_f32 v[56:57], v[30:31], v[32:33] neg_lo:[0,1] neg_hi:[0,1]
	s_waitcnt lgkmcnt(1)
	v_pk_mul_f32 v[32:33], v[42:43], v[4:5] op_sel_hi:[0,1]
	v_pk_fma_f32 v[58:59], v[42:43], v[2:3], v[32:33] op_sel:[1,0,0] neg_lo:[0,0,1] neg_hi:[0,0,1]
	v_pk_fma_f32 v[32:33], v[42:43], v[2:3], v[32:33] op_sel:[1,0,0]
	v_pk_mul_f32 v[42:43], v[44:45], v[18:19]
	v_mov_b32_e32 v59, v33
	v_pk_fma_f32 v[60:61], v[44:45], v[24:25], v[42:43] op_sel:[1,0,0] op_sel_hi:[0,1,1] neg_lo:[0,0,1] neg_hi:[0,0,1]
	v_pk_fma_f32 v[42:43], v[44:45], v[24:25], v[42:43] op_sel:[1,0,0] op_sel_hi:[0,1,1]
	s_waitcnt lgkmcnt(0)
	v_pk_mul_f32 v[44:45], v[46:47], v[16:17]
	v_mov_b32_e32 v61, v43
	v_pk_fma_f32 v[62:63], v[46:47], v[14:15], v[44:45] op_sel:[1,0,0] op_sel_hi:[0,1,1] neg_lo:[0,0,1] neg_hi:[0,0,1]
	v_pk_fma_f32 v[44:45], v[46:47], v[14:15], v[44:45] op_sel:[1,0,0] op_sel_hi:[0,1,1]
	v_pk_mul_f32 v[46:47], v[48:49], v[26:27]
	v_mov_b32_e32 v44, v62
	v_pk_fma_f32 v[64:65], v[48:49], v[28:29], v[46:47] op_sel:[1,0,0] op_sel_hi:[0,1,1] neg_lo:[0,0,1] neg_hi:[0,0,1]
	v_pk_fma_f32 v[46:47], v[48:49], v[28:29], v[46:47] op_sel:[1,0,0] op_sel_hi:[0,1,1]
	v_mov_b32_e32 v46, v64
	v_pk_add_f32 v[48:49], v[58:59], v[60:61]
	v_mov_b32_e32 v59, v45
	v_mov_b32_e32 v61, v47
	v_pk_mov_b32 v[32:33], v[32:33], v[62:63] op_sel:[1,0]
	v_pk_mov_b32 v[42:43], v[42:43], v[64:65] op_sel:[1,0]
	v_pk_add_f32 v[66:67], v[44:45], v[46:47]
	v_pk_add_f32 v[44:45], v[58:59], v[60:61] neg_lo:[0,1] neg_hi:[0,1]
	v_pk_add_f32 v[58:59], v[32:33], v[42:43] neg_lo:[0,1] neg_hi:[0,1]
	v_add_f32_e32 v32, v44, v45
	v_sub_f32_e32 v33, v58, v59
	v_pk_add_f32 v[40:41], v[52:53], v[40:41]
	v_mov_b32_e32 v30, v54
	v_pk_add_f32 v[46:47], v[48:49], v[66:67] neg_lo:[0,1] neg_hi:[0,1]
	v_sub_f32_e32 v42, v44, v45
	v_mul_f32_e32 v54, 0x3f3504f3, v33
	v_mul_f32_e32 v43, 0x3f3504f3, v32
	v_pk_add_f32 v[50:51], v[38:39], v[40:41] op_sel:[0,1] op_sel_hi:[1,0] neg_lo:[0,1] neg_hi:[0,1]
	v_mov_b32_e32 v31, v57
	v_mul_f32_e32 v32, 0x3f3504f3, v42
	v_pk_add_f32 v[44:45], v[48:49], v[66:67]
	v_pk_add_f32 v[38:39], v[38:39], v[40:41] op_sel:[0,1] op_sel_hi:[1,0]
	v_mov_b32_e32 v57, v55
	v_sub_f32_e32 v42, v54, v43
	v_fmac_f32_e32 v43, 0x3f3504f3, v33
	v_pk_add_f32 v[52:53], v[50:51], v[46:47] neg_lo:[0,1] neg_hi:[0,1]
	v_pk_add_f32 v[46:47], v[50:51], v[46:47]
	v_pk_add_f32 v[50:51], v[58:59], v[58:59] op_sel:[0,1] op_sel_hi:[0,1]
	v_pk_add_f32 v[40:41], v[38:39], v[44:45] op_sel:[0,1] op_sel_hi:[1,0]
	v_pk_add_f32 v[38:39], v[38:39], v[44:45] op_sel:[0,1] op_sel_hi:[1,0] neg_lo:[0,1] neg_hi:[0,1]
	v_pk_add_f32 v[44:45], v[56:57], v[42:43]
	v_pk_fma_f32 v[32:33], v[50:51], s[82:83], v[32:33] op_sel_hi:[1,1,0] neg_lo:[0,0,1] neg_hi:[0,0,1]
	v_pk_add_f32 v[42:43], v[56:57], v[42:43] neg_lo:[0,1] neg_hi:[0,1]
	v_mov_b32_e32 v48, v52
	v_mov_b32_e32 v49, v47
	v_mov_b32_e32 v47, v53
	v_pk_add_f32 v[50:51], v[30:31], v[32:33]
	v_pk_add_f32 v[30:31], v[30:31], v[32:33] neg_lo:[0,1] neg_hi:[0,1]
	ds_write2_b64 v68, v[40:41], v[44:45] offset1:9
	ds_write2_b64 v68, v[48:49], v[50:51] offset0:18 offset1:27
	ds_write2_b64 v68, v[38:39], v[42:43] offset0:36 offset1:45
	ds_write2_b64 v68, v[46:47], v[30:31] offset0:54 offset1:63
	s_cbranch_scc0 .LBB0_657
; #define FFT_HD __device__ __attribute__((always_inline))
; template <int R> FFT_HD inline void reg_inv(cf2 (&v)[1 << R], cf2 th) { tw_apply<R, 1, true>(v, th, th); dft_inv_reg<R>(v); }
; template <int R, int F, bool CONJ> FFT_HD inline void tw_apply(cf2 (&v)[1 << R], cf2 pf, cf2 th) {
;     constexpr int j = fbrev(F, R);
;     v[j] = CONJ ? cmulcf(v[j], pf) : cmulf(v[j], pf);
;     if constexpr (2 * F < (1 << R)) {
;         const cf2 p2 = cmulf(pf, pf);
;         tw_apply<R, 2 * F, CONJ>(v, p2, th);
;         const cf2 p3 = cmulf(p2, th);
;         tw_apply<R, 2 * F + 1, CONJ>(v, p3, th);
;     }
; }
; __device__ __forceinline__ void s_mid2(ldsc X, const cf2* TW, int tid) {
;     ...
; #pragma unroll 1
;     for (int q = 0; q < 2; ++q) { const int grp = tid + 512 * q; cf2 v[16]; grp_load<4, 64>(X, grp, v); reg_inv<4>(v, TW[(grp & 63) * 16]); grp_store<4, 64>(X, grp, v); }
	s_waitcnt lgkmcnt(0)
	s_barrier
	v_mov_b32_e32 v18, v202
	v_mov_b32_e32 v19, v203
	s_mov_b32 s3, 0
	s_mov_b64 s[4:5], -1
	v_pk_mul_f32 v[4:5], v[18:19], v[18:19] op_sel:[0,1] op_sel_hi:[1,0]
	v_mul_f32_e32 v2, v19, v19
	v_pk_add_f32 v[24:25], v[4:5], v[4:5]
	v_pk_fma_f32 v[22:23], v[18:19], v[18:19], v[2:3] op_sel_hi:[1,1,0] neg_lo:[0,0,1] neg_hi:[0,0,1]
	v_pk_mul_f32 v[6:7], v[18:19], v[24:25] op_sel:[1,0] op_sel_hi:[0,1]
	v_pk_mul_f32 v[8:9], v[18:19], v[24:25]
	v_pk_mul_f32 v[4:5], v[22:23], v[24:25]
	v_pk_fma_f32 v[30:31], v[18:19], v[22:23], v[6:7] neg_lo:[0,0,1] neg_hi:[0,0,1]
	v_pk_fma_f32 v[32:33], v[18:19], v[22:23], v[8:9] op_sel:[1,0,0] op_sel_hi:[0,1,1]
	v_pk_mul_f32 v[2:3], v[24:25], v[24:25]
	v_pk_add_f32 v[28:29], v[4:5], v[4:5]
	v_pk_mul_f32 v[12:13], v[30:31], v[32:33]
	v_pk_fma_f32 v[26:27], v[22:23], v[22:23], v[2:3] neg_lo:[0,0,1] neg_hi:[0,0,1]
	v_pk_mul_f32 v[8:9], v[18:19], v[28:29]
	v_pk_mul_f32 v[10:11], v[32:33], v[32:33]
	v_pk_add_f32 v[48:49], v[12:13], v[12:13]
	v_pk_mul_f32 v[2:3], v[28:29], v[28:29]
	v_pk_mul_f32 v[6:7], v[18:19], v[28:29] op_sel:[1,0] op_sel_hi:[0,1]
	v_pk_fma_f32 v[44:45], v[18:19], v[26:27], v[8:9] op_sel:[1,0,0] op_sel_hi:[0,1,1]
	v_pk_fma_f32 v[46:47], v[30:31], v[30:31], v[10:11] neg_lo:[0,0,1] neg_hi:[0,0,1]
	v_pk_mul_f32 v[12:13], v[18:19], v[48:49]
	v_pk_mul_f32 v[4:5], v[26:27], v[28:29]
	v_pk_fma_f32 v[38:39], v[26:27], v[26:27], v[2:3] neg_lo:[0,0,1] neg_hi:[0,0,1]
	v_pk_fma_f32 v[42:43], v[18:19], v[26:27], v[6:7] neg_lo:[0,0,1] neg_hi:[0,0,1]
	v_pk_mul_f32 v[2:3], v[44:45], v[44:45]
	v_pk_mul_f32 v[10:11], v[18:19], v[48:49] op_sel:[1,0] op_sel_hi:[0,1]
	v_pk_fma_f32 v[62:63], v[18:19], v[46:47], v[12:13] op_sel:[1,0,0] op_sel_hi:[0,1,1]
	v_pk_add_f32 v[40:41], v[4:5], v[4:5]
	v_pk_mul_f32 v[4:5], v[42:43], v[44:45]
	v_pk_mul_f32 v[6:7], v[48:49], v[48:49]
	v_pk_fma_f32 v[52:53], v[42:43], v[42:43], v[2:3] neg_lo:[0,0,1] neg_hi:[0,0,1]
	v_pk_fma_f32 v[60:61], v[18:19], v[46:47], v[10:11] neg_lo:[0,0,1] neg_hi:[0,0,1]
	v_pk_mul_f32 v[2:3], v[62:63], v[62:63]
	v_pk_mul_f32 v[8:9], v[46:47], v[48:49]
	v_pk_add_f32 v[54:55], v[4:5], v[4:5]
	v_pk_fma_f32 v[56:57], v[46:47], v[46:47], v[6:7] neg_lo:[0,0,1] neg_hi:[0,0,1]
	v_pk_mul_f32 v[4:5], v[60:61], v[62:63]
	v_pk_fma_f32 v[70:71], v[60:61], v[60:61], v[2:3] neg_lo:[0,0,1] neg_hi:[0,0,1]
	v_mul_f32_e32 v50, v19, v38
	v_mul_f32_e32 v14, v18, v38
	v_pk_add_f32 v[58:59], v[8:9], v[8:9]
	v_mul_f32_e32 v66, v19, v56
	v_mul_f32_e32 v68, v19, v52
	v_mul_f32_e32 v6, v18, v52
	v_mul_f32_e32 v7, v18, v56
	v_pk_add_f32 v[72:73], v[4:5], v[4:5]
	v_mul_f32_e32 v78, v19, v70
	v_mul_f32_e32 v2, v18, v70
	v_fmac_f32_e32 v50, v18, v40
	v_fma_f32 v64, -v19, v40, v14
	v_fmac_f32_e32 v66, v18, v58
	v_fmac_f32_e32 v68, v18, v54
	v_fma_f32 v74, -v19, v54, v6
	v_fma_f32 v76, -v19, v58, v7
	v_fmac_f32_e32 v78, v18, v72
	v_fma_f32 v80, -v19, v72, v2
	v_pk_mov_b32 v[20:21], v[18:19], v[18:19] op_sel:[1,0]
	v_mov_b32_e32 v25, v24
	v_mov_b32_e32 v23, v22
	v_mov_b32_e32 v29, v28
	v_mov_b32_e32 v33, v32
	v_mov_b32_e32 v27, v26
	v_mov_b32_e32 v31, v30
	v_mov_b32_e32 v39, v38
	v_mov_b32_e32 v49, v48
	v_mov_b32_e32 v45, v44
	v_mov_b32_e32 v41, v40
	v_mov_b32_e32 v47, v46
	v_mov_b32_e32 v43, v42
	v_mov_b32_e32 v59, v58
	v_mov_b32_e32 v55, v54
	v_mov_b32_e32 v51, v50
	v_mov_b32_e32 v63, v62
	v_mov_b32_e32 v57, v56
	v_mov_b32_e32 v53, v52
	v_mov_b32_e32 v65, v64
	v_mov_b32_e32 v61, v60
	v_mov_b32_e32 v73, v72
	v_mov_b32_e32 v67, v66
	v_mov_b32_e32 v69, v68
	v_mov_b32_e32 v71, v70
	v_mov_b32_e32 v75, v74
	v_mov_b32_e32 v77, v76
	v_mov_b32_e32 v79, v78
	v_mov_b32_e32 v81, v80

; #define FFT_HD __device__ __attribute__((always_inline))
; template <int R> FFT_HD inline void reg_fwd(cf2 (&v)[1 << R], cf2 th) { dft_fwd_reg<R>(v); tw_apply<R, 1, false>(v, th, th); }
; template <int R> FFT_HD inline void reg_inv(cf2 (&v)[1 << R], cf2 th) { tw_apply<R, 1, true>(v, th, th); dft_inv_reg<R>(v); }
; __device__ __forceinline__ cf2 tw_fresh(cf2 th) { asm volatile("" : "+v"(th.x), "+v"(th.y)); return th; }
; template <int R, int F, bool CONJ> FFT_HD inline void tw_apply(cf2 (&v)[1 << R], cf2 pf, cf2 th) {
;     constexpr int j = fbrev(F, R);
;     v[j] = CONJ ? cmulcf(v[j], pf) : cmulf(v[j], pf);
;     if constexpr (2 * F < (1 << R)) {
;         const cf2 p2 = cmulf(pf, pf);
;         tw_apply<R, 2 * F, CONJ>(v, p2, th);
;         const cf2 p3 = cmulf(p2, th);
;         tw_apply<R, 2 * F + 1, CONJ>(v, p3, th);
;     }
; }
; __device__ __forceinline__ void hyena_conv_s2(const float* HYT, float* ZOUT, const float* FILT, const cf2* TW, LAS unsigned char* lds, int vb, int nb, int tid_in) {
;     ...
;         for (int q = 0; q < 2; ++q) { const int grp = tid + 512 * q; cf2 v[16]; float g1[8], fl[16];
; #pragma unroll
;             for (int m = 0; m < 16; ++m) { if (m < 8) g1[m] = hx1[grp + 1024 * m]; fl[m] = f1[grp + 1024 * m]; }
;             const cf2 th = TW[grp];
;             grp_load<4, 1024>(X, grp, v); reg_inv<4>(v, th);
; #pragma unroll
;             for (int m = 0; m < 16; ++m) { v[m].x = m < 8 ? v[m].x * g1[m] : 0.f; v[m].y = fl[m]; }
;             reg_fwd<4>(v, tw_fresh(th)); grp_store<4, 1024>(X, grp, v); }
.LBB0_661:
	v_cndmask_b32_e64 v2, 0, 1, s[54:55]
	v_cmp_ne_u32_e64 s[4:5], 1, v2
	v_add_u32_e32 v2, s3, v172
	v_ashrrev_i32_e32 v3, 31, v2
	v_lshlrev_b64 v[4:5], 2, v[2:3]
	v_lshl_add_u64 v[6:7], s[42:43], 0, v[4:5]
	v_add_co_u32_e32 v8, vcc, 0x1000, v6
	v_lshl_add_u64 v[4:5], s[50:51], 0, v[4:5]
	s_nop 0
	v_addc_co_u32_e32 v9, vcc, 0, v7, vcc
	global_load_dword v10, v[8:9], off
	v_add_co_u32_e32 v8, vcc, 0x1000, v4
	global_load_dword v42, v[6:7], off
	s_nop 0
	v_addc_co_u32_e32 v9, vcc, 0, v5, vcc
	global_load_dword v11, v[8:9], off
	v_add_co_u32_e32 v8, vcc, s48, v6
	s_mov_b32 s83, s78
	s_nop 0
	v_addc_co_u32_e32 v9, vcc, 0, v7, vcc
	global_load_dword v13, v[8:9], off
	v_add_co_u32_e32 v8, vcc, s48, v4
	s_mov_b32 s15, s60
	s_nop 0
	v_addc_co_u32_e32 v9, vcc, 0, v5, vcc
	global_load_dword v12, v[8:9], off
	v_add_co_u32_e32 v8, vcc, 0x3000, v6
	s_mov_b32 s26, s61
	s_nop 0
	v_addc_co_u32_e32 v9, vcc, 0, v7, vcc
	global_load_dword v15, v[8:9], off
	v_add_co_u32_e32 v8, vcc, 0x3000, v4
	s_mov_b32 s27, s60
	s_nop 0
	v_addc_co_u32_e32 v9, vcc, 0, v5, vcc
	global_load_dword v14, v[8:9], off
	v_add_co_u32_e32 v8, vcc, s40, v6
	s_mov_b32 s85, s60
	s_nop 0
	v_addc_co_u32_e32 v9, vcc, 0, v7, vcc
	v_add_co_u32_e32 v18, vcc, s40, v4
	global_load_dword v45, v[8:9], off offset:-4096
	global_load_dword v16, v[4:5], off
	v_addc_co_u32_e32 v19, vcc, 0, v5, vcc
	v_add_co_u32_e32 v6, vcc, s33, v6
	global_load_dword v199, v[18:19], off offset:-4096
	global_load_dword v43, v[8:9], off
	global_load_dword v17, v[18:19], off
	v_addc_co_u32_e32 v7, vcc, 0, v7, vcc
	v_add_co_u32_e32 v8, vcc, s33, v4
	global_load_dword v19, v[6:7], off offset:-4096
	s_nop 0
	v_addc_co_u32_e32 v9, vcc, 0, v5, vcc
	global_load_dword v18, v[8:9], off offset:-4096
	global_load_dword v21, v[6:7], off
	global_load_dword v20, v[8:9], off
	v_add_co_u32_e32 v6, vcc, s1, v4
	v_mov_b32_e32 v30, v183
	s_nop 0
	v_addc_co_u32_e32 v7, vcc, 0, v5, vcc
	global_load_dword v29, v[6:7], off offset:-4096
	global_load_dword v27, v[6:7], off
	v_add_co_u32_e32 v6, vcc, s92, v4
	v_mov_b32_e32 v28, v183
	s_nop 0
	v_addc_co_u32_e32 v7, vcc, 0, v5, vcc
	global_load_dword v41, v[6:7], off offset:-4096
	global_load_dword v25, v[6:7], off
	v_add_co_u32_e32 v6, vcc, s0, v4
	v_mov_b32_e32 v26, v183
	s_nop 0
	v_addc_co_u32_e32 v7, vcc, 0, v5, vcc
	v_add_co_u32_e32 v4, vcc, s18, v4
	global_load_dword v39, v[6:7], off offset:-4096
	global_load_dword v31, v[6:7], off
	v_addc_co_u32_e32 v5, vcc, 0, v5, vcc
	global_load_dword v33, v[4:5], off offset:-4096
	global_load_dword v23, v[4:5], off
	v_lshl_add_u64 v[4:5], v[2:3], 3, s[36:37]
	global_load_dwordx2 v[6:7], v[4:5], off
	v_lshrrev_b32_e32 v3, 22, v3
	v_add_lshl_u32 v3, v2, v3, 4
	v_and_b32_e32 v3, 0xffffc000, v3
	v_and_b32_e32 v2, 0x3ff, v2
	v_or_b32_e32 v4, v3, v2
	v_bitop3_b32 v2, v3, s19, v2 bitop3:0xc8
	v_lshlrev_b32_e32 v3, 3, v4
	v_add3_u32 v177, 0, v2, v3
	ds_read2st64_b64 v[46:49], v177 offset1:18
	ds_read2st64_b64 v[2:5], v177 offset0:36 offset1:54
	ds_read2st64_b64 v[50:53], v177 offset0:72 offset1:90
	ds_read2st64_b64 v[54:57], v177 offset0:108 offset1:126
	v_add_u32_e32 v182, 0x1b000, v177
	s_waitcnt lgkmcnt(3)
	v_mov_b32_e32 v60, v49
	s_waitcnt lgkmcnt(2)
	v_mov_b32_e32 v61, v5
	v_add_u32_e32 v185, 0x1d400, v177
	ds_read_b64 v[138:139], v182
	ds_read_b64 v[140:141], v185
	v_add_u32_e32 v189, 0x1f800, v177
	v_add_u32_e32 v198, 0x21c00, v177
	ds_read_b64 v[62:63], v189
	ds_read_b64 v[76:77], v198
	s_waitcnt lgkmcnt(3)
	v_mov_b32_e32 v98, v139
	s_waitcnt lgkmcnt(2)
	v_mov_b32_e32 v99, v141
	v_add_u32_e32 v178, 0x12000, v177
	v_add_u32_e32 v179, 0x14400, v177
	v_add_u32_e32 v180, 0x16800, v177
	v_add_u32_e32 v181, 0x18c00, v177
	ds_read_b64 v[8:9], v178
	ds_read_b64 v[72:73], v179
	ds_read_b64 v[78:79], v180
	ds_read_b64 v[80:81], v181
	v_mov_b32_e32 v40, v183
	v_mov_b32_e32 v24, v183
	v_mov_b32_e32 v38, v183
	v_mov_b32_e32 v32, v183
	s_mov_b32 s3, s80
	s_mov_b64 s[54:55], 0
	s_and_b64 vcc, exec, s[4:5]
	s_waitcnt vmcnt(0)
	v_pk_mul_f32 v[58:59], v[6:7], v[6:7] op_sel:[0,1] op_sel_hi:[1,0]
	v_mul_f32_e32 v22, v7, v7
	v_pk_add_f32 v[82:83], v[58:59], v[58:59]
	v_pk_fma_f32 v[74:75], v[6:7], v[6:7], v[22:23] op_sel_hi:[1,1,0] neg_lo:[0,0,1] neg_hi:[0,0,1]
	v_mov_b32_e32 v58, v48
	v_pk_mul_f32 v[48:49], v[6:7], v[82:83] op_sel:[1,0] op_sel_hi:[0,0]
	v_pk_fma_f32 v[84:85], v[6:7], v[74:75], v[48:49] op_sel_hi:[1,0,1]
	v_pk_mul_f32 v[136:137], v[82:83], v[50:51]
	v_pk_fma_f32 v[142:143], v[6:7], v[74:75], v[48:49] op_sel_hi:[1,0,1] neg_lo:[0,0,1] neg_hi:[0,0,1]
	v_mov_b32_e32 v83, v85
	v_pk_mul_f32 v[134:135], v[74:75], v[50:51] op_sel:[0,1] op_sel_hi:[1,0]
	v_mov_b32_e32 v75, v142
	v_pk_mul_f32 v[48:49], v[82:83], v[82:83]
	v_mov_b32_e32 v59, v4
	v_pk_fma_f32 v[66:67], v[74:75], v[74:75], v[48:49] neg_lo:[0,0,1] neg_hi:[0,0,1]
	v_pk_mul_f32 v[48:49], v[74:75], v[82:83]
	v_mul_f32_e32 v22, v2, v66
	v_pk_add_f32 v[86:87], v[48:49], v[48:49]
	v_mov_b32_e32 v48, v66
	v_mov_b32_e32 v49, v86
	v_pk_mul_f32 v[64:65], v[66:67], v[86:87]
	v_pk_fma_f32 v[88:89], v[2:3], v[48:49], v[22:23] op_sel_hi:[1,1,0]
	v_pk_mul_f32 v[48:49], v[86:87], v[86:87]
	v_pk_add_f32 v[64:65], v[64:65], v[64:65]
	v_pk_fma_f32 v[48:49], v[66:67], v[66:67], v[48:49] neg_lo:[0,0,1] neg_hi:[0,0,1]
	v_pk_mul_f32 v[60:61], v[60:61], v[64:65]
	v_mov_b32_e32 v143, v85
	v_pk_fma_f32 v[58:59], v[58:59], v[48:49], v[60:61]
	v_mov_b32_e32 v84, v138
	v_pk_add_f32 v[60:61], v[46:47], v[58:59] neg_lo:[0,1] neg_hi:[0,1]
	v_mov_b32_e32 v47, v89
	v_pk_add_f32 v[58:59], v[46:47], v[58:59]
	v_pk_mul_f32 v[46:47], v[6:7], v[86:87] op_sel:[1,0]
	v_pk_mul_f32 v[88:89], v[6:7], v[86:87] op_sel_hi:[0,1]
	v_pk_fma_f32 v[46:47], v[6:7], v[66:67], v[46:47] op_sel_hi:[0,1,1] neg_lo:[0,0,1] neg_hi:[0,0,1]
	v_pk_fma_f32 v[88:89], v[6:7], v[66:67], v[88:89] op_sel:[1,0,0]
	v_mov_b32_e32 v90, v87
	v_pk_mul_f32 v[94:95], v[46:47], v[88:89]
	v_pk_mul_f32 v[92:93], v[88:89], v[88:89]
	v_pk_add_f32 v[94:95], v[94:95], v[94:95]
	v_pk_fma_f32 v[92:93], v[46:47], v[46:47], v[92:93] neg_lo:[0,0,1] neg_hi:[0,0,1]
	v_pk_mul_f32 v[96:97], v[6:7], v[94:95] op_sel:[1,0] op_sel_hi:[0,0]
	v_pk_fma_f32 v[158:159], v[6:7], v[92:93], v[96:97] op_sel_hi:[1,0,1]
	v_pk_fma_f32 v[154:155], v[6:7], v[92:93], v[96:97] op_sel_hi:[1,0,1] neg_lo:[0,0,1] neg_hi:[0,0,1]
	v_mov_b32_e32 v158, v85
	v_mov_b32_e32 v85, v140
	v_mov_b32_e32 v91, v67
	v_mov_b32_e32 v96, v142
	v_mov_b32_e32 v97, v154
	v_pk_mul_f32 v[84:85], v[158:159], v[84:85]
	v_pk_mul_f32 v[90:91], v[90:91], v[54:55]
	v_pk_fma_f32 v[84:85], v[96:97], v[98:99], v[84:85] neg_lo:[0,0,1] neg_hi:[0,0,1]
	v_mov_b32_e32 v97, v54
	v_mov_b32_e32 v83, v87
	v_mov_b32_e32 v54, v51
	v_mov_b32_e32 v75, v67
	v_mov_b32_e32 v96, v50
	v_pk_mul_f32 v[50:51], v[82:83], v[54:55]
	v_pk_mul_f32 v[146:147], v[52:53], v[92:93] op_sel:[1,0] op_sel_hi:[0,1]
	v_pk_fma_f32 v[144:145], v[74:75], v[96:97], v[50:51]
	v_mov_b32_e32 v50, v89
	v_mov_b32_e32 v51, v47
	v_pk_mul_f32 v[150:151], v[52:53], v[94:95]
	s_waitcnt lgkmcnt(5)
; #define FFT_HD __device__ __attribute__((always_inline))
; template <int R> FFT_HD inline void dft_inv_reg(cf2 (&v)[1 << R]) {
;     constexpr int n = 1 << R;
; #pragma unroll
;     for (int s = R - 1; s >= 0; --s) {
;         const int half = n >> (s + 1);
; #pragma unroll
;         for (int m = 0; m < n; ++m) {
;             if ((m & half) == 0) {
;                 const int ml = m & (half - 1), tk = ml * (16 / half);
;                 const cf2 a = v[m], bb = v[m + half]; cf2 b;
;                 if (tk == 0) b = bb;
;                 else if (tk == 8) { b.x = -bb.y; b.y = bb.x; }
;                 else { const cf2 w = {fc32(tk), -fs32(tk)}; b = cmulcf(bb, w); }
;                 v[m].x = a.x + b.x; v[m].y = a.y + b.y; v[m + half].x = a.x - b.x; v[m + half].y = a.y - b.y;
;             }
;         }
;     }
; }
; template <int R, int F, bool CONJ> FFT_HD inline void tw_apply(cf2 (&v)[1 << R], cf2 pf, cf2 th) {
;     constexpr int j = fbrev(F, R);
;     v[j] = CONJ ? cmulcf(v[j], pf) : cmulf(v[j], pf);
;     if constexpr (2 * F < (1 << R)) {
;         const cf2 p2 = cmulf(pf, pf);
;         tw_apply<R, 2 * F, CONJ>(v, p2, th);
;         const cf2 p3 = cmulf(p2, th);
;         tw_apply<R, 2 * F + 1, CONJ>(v, p3, th);
;     }
; }
	v_pk_mul_f32 v[160:161], v[50:51], v[62:63]
	v_mov_b32_e32 v50, v52
	v_mov_b32_e32 v52, v53
	v_mov_b32_e32 v53, v57
	v_mov_b32_e32 v51, v56
	v_pk_mul_f32 v[52:53], v[52:53], v[94:95]
	v_pk_mul_f32 v[54:55], v[6:7], v[94:95] op_sel:[0,1]
	v_pk_fma_f32 v[152:153], v[50:51], v[92:93], v[52:53]
	v_mov_b32_e32 v50, v95
	v_mov_b32_e32 v51, v93
	v_pk_mul_f32 v[50:51], v[56:57], v[50:51]
	v_mov_b32_e32 v52, v91
	v_mov_b32_e32 v53, v51
	v_mov_b32_e32 v91, v50
	v_pk_fma_f32 v[56:57], v[6:7], v[92:93], v[54:55] op_sel:[1,1,0] op_sel_hi:[0,1,1] neg_lo:[0,0,1] neg_hi:[0,0,1]
	v_pk_fma_f32 v[54:55], v[6:7], v[92:93], v[54:55] op_sel:[1,1,0] op_sel_hi:[0,1,1]
	v_pk_add_f32 v[156:157], v[52:53], v[90:91] neg_lo:[0,1] neg_hi:[0,1]
	v_mov_b32_e32 v52, v63
	s_waitcnt lgkmcnt(4)
	v_mov_b32_e32 v53, v77
	v_mov_b32_e32 v56, v54
	v_pk_mov_b32 v[54:55], v[88:89], v[54:55] op_sel:[1,0]
	v_pk_mul_f32 v[70:71], v[2:3], v[86:87]
	v_mov_b32_e32 v50, v62
	v_mov_b32_e32 v51, v76
	v_mov_b32_e32 v62, v47
	v_mov_b32_e32 v63, v57
	v_pk_mul_f32 v[52:53], v[54:55], v[52:53]
	v_mul_f32_e32 v22, v57, v77
	s_waitcnt lgkmcnt(0)
	v_mov_b32_e32 v83, v80
	v_mov_b32_e32 v80, v73
	v_mov_b32_e32 v73, v78
	v_pk_mov_b32 v[86:87], v[6:7], v[88:89] op_sel:[1,0]
	v_mov_b32_e32 v78, v9
	v_pk_mul_f32 v[148:149], v[142:143], v[138:139]
	v_mov_b32_e32 v155, v159
	v_pk_fma_f32 v[74:75], v[62:63], v[50:51], v[52:53]
	v_pk_fma_f32 v[76:77], v[56:57], v[76:77], v[22:23] op_sel_hi:[1,1,0] neg_lo:[1,0,0] neg_hi:[1,0,0]
	v_pk_mul_f32 v[52:53], v[6:7], v[64:65] op_sel_hi:[0,1]
	v_mov_b32_e32 v82, v72
	v_mov_b32_e32 v56, v6
	v_mov_b32_e32 v57, v46
	v_mov_b32_e32 v72, v8
	v_pk_mul_f32 v[8:9], v[86:87], v[78:79]
	v_mul_f32_e32 v44, v159, v141
	v_pk_mul_f32 v[50:51], v[6:7], v[64:65] op_sel:[1,0]
	v_pk_fma_f32 v[54:55], v[6:7], v[48:49], v[52:53] op_sel:[1,0,0]
	v_pk_fma_f32 v[166:167], v[56:57], v[72:73], v[8:9]
	v_pk_mul_f32 v[8:9], v[86:87], v[72:73]
	v_pk_fma_f32 v[140:141], v[154:155], v[140:141], v[44:45] op_sel_hi:[1,1,0]
	v_mov_b32_e32 v154, v148
	v_mov_b32_e32 v155, v161
	v_pk_mov_b32 v[148:149], v[148:149], v[160:161] op_sel:[1,0]
	v_pk_fma_f32 v[50:51], v[6:7], v[48:49], v[50:51] op_sel_hi:[0,1,1] neg_lo:[0,0,1] neg_hi:[0,0,1]
	v_pk_mul_f32 v[52:53], v[54:55], v[80:81]
	v_pk_fma_f32 v[56:57], v[56:57], v[78:79], v[8:9] neg_lo:[0,0,1] neg_hi:[0,0,1]
	v_pk_mul_f32 v[8:9], v[54:55], v[82:83]
	v_pk_fma_f32 v[138:139], v[142:143], v[138:139], v[148:149]
	v_pk_add_f32 v[158:159], v[154:155], v[148:149] neg_lo:[0,1] neg_hi:[0,1]
	v_pk_fma_f32 v[164:165], v[50:51], v[82:83], v[52:53]
	v_pk_fma_f32 v[168:169], v[50:51], v[80:81], v[8:9] neg_lo:[0,0,1] neg_hi:[0,0,1]
	v_mov_b32_e32 v8, v84
	v_mov_b32_e32 v9, v74
	v_mov_b32_e32 v50, v85
	v_mov_b32_e32 v51, v75
	v_mov_b32_e32 v139, v159
	v_mov_b32_e32 v141, v76
	v_pk_add_f32 v[170:171], v[8:9], v[50:51] neg_lo:[0,1] neg_hi:[0,1]
	v_pk_add_f32 v[142:143], v[138:139], v[140:141] neg_lo:[0,1] neg_hi:[0,1]
	v_pk_add_f32 v[148:149], v[170:171], v[170:171] op_sel:[0,1] op_sel_hi:[1,0]
	v_pk_add_f32 v[154:155], v[142:143], v[142:143] op_sel_hi:[0,1] neg_lo:[0,1] neg_hi:[0,1]
	v_pk_add_f32 v[46:47], v[166:167], v[164:165] neg_lo:[0,1] neg_hi:[0,1]
	v_pk_add_f32 v[78:79], v[56:57], v[168:169] neg_lo:[0,1] neg_hi:[0,1]
	v_mov_b32_e32 v149, v155
	v_mov_b32_e32 v135, v56
	v_mov_b32_e32 v137, v168
	v_pk_add_f32 v[80:81], v[56:57], v[168:169]
	v_pk_mul_f32 v[154:155], v[148:149], s[80:81] op_sel_hi:[1,0]
	v_pk_add_f32 v[168:169], v[134:135], v[136:137] neg_lo:[0,1] neg_hi:[0,1]
	v_mov_b32_e32 v147, v167
	v_mov_b32_e32 v151, v165
	v_mov_b32_e32 v136, v144
	v_mov_b32_e32 v137, v46
	v_mov_b32_e32 v78, v152
	v_pk_mul_f32 v[68:69], v[2:3], v[66:67] op_sel:[1,0] op_sel_hi:[0,1]
	v_pk_add_f32 v[52:53], v[166:167], v[164:165]
	v_pk_add_f32 v[72:73], v[170:171], v[170:171] op_sel_hi:[0,1] neg_lo:[0,1] neg_hi:[0,1]
	v_pk_fma_f32 v[170:171], v[148:149], s[80:81], v[154:155] op_sel:[0,0,1] op_sel_hi:[1,0,0]
	v_pk_add_f32 v[164:165], v[146:147], v[150:151] neg_lo:[0,1] neg_hi:[0,1]
	v_pk_add_f32 v[146:147], v[136:137], v[78:79] neg_lo:[0,1] neg_hi:[0,1]
	v_mov_b32_e32 v136, v156
	v_mov_b32_e32 v137, v155
	v_pk_mov_b32 v[148:149], v[156:157], v[154:155] op_sel:[1,0]
	v_pk_add_f32 v[142:143], v[142:143], v[142:143] op_sel:[0,1] op_sel_hi:[1,0]
	v_pk_add_f32 v[166:167], v[168:169], v[164:165]
	v_pk_add_f32 v[150:151], v[136:137], v[148:149] neg_lo:[0,1] neg_hi:[0,1]
	v_pk_add_f32 v[148:149], v[168:169], v[164:165] neg_lo:[0,1] neg_hi:[0,1]
	v_mov_b32_e32 v168, v145
	v_mov_b32_e32 v164, v153
	v_mov_b32_e32 v69, v46
	v_mov_b32_e32 v78, v70
	v_mov_b32_e32 v72, v4
	v_mov_b32_e32 v186, v65
	v_pk_add_f32 v[62:63], v[144:145], v[152:153]
	v_pk_add_f32 v[144:145], v[168:169], v[164:165] neg_lo:[0,1] neg_hi:[0,1]
	v_pk_fma_f32 v[2:3], v[2:3], v[66:67], v[70:71] op_sel:[1,0,0] op_sel_hi:[0,1,1] neg_lo:[0,0,1] neg_hi:[0,0,1]
	v_pk_add_f32 v[66:67], v[68:69], v[78:79]
	v_pk_mul_f32 v[68:69], v[72:73], v[186:187]
	v_pk_mov_b32 v[4:5], v[4:5], v[142:143] op_sel:[1,0]
	v_mov_b32_e32 v70, v49
	v_mov_b32_e32 v71, v188
	v_mov_b32_e32 v135, v166
	v_mov_b32_e32 v166, v148
	v_mov_b32_e32 v152, v144
	v_mov_b32_e32 v153, v170
	v_mov_b32_e32 v3, v67
	v_pk_fma_f32 v[4:5], v[4:5], v[70:71], v[68:69] neg_lo:[0,0,1] neg_hi:[0,0,1]
	v_mov_b32_e32 v139, v43
	v_pk_add_f32 v[154:155], v[146:147], v[150:151] neg_lo:[0,1] neg_hi:[0,1]
	v_pk_add_f32 v[160:161], v[146:147], v[150:151]
	v_sub_f32_e32 v43, v167, v170
	v_pk_add_f32 v[152:153], v[166:167], v[152:153]
	v_pk_add_f32 v[2:3], v[2:3], v[4:5] neg_lo:[0,1] neg_hi:[0,1]
	v_pk_add_f32 v[162:163], v[156:157], v[156:157] op_sel_hi:[0,1]
	v_mov_b32_e32 v160, v154
; #define FFT_HD __device__ __attribute__((always_inline))
; template <int R> FFT_HD inline void dft_inv_reg(cf2 (&v)[1 << R]) {
;     constexpr int n = 1 << R;
; #pragma unroll
;     for (int s = R - 1; s >= 0; --s) {
;         const int half = n >> (s + 1);
; #pragma unroll
;         for (int m = 0; m < n; ++m) {
;             if ((m & half) == 0) {
;                 const int ml = m & (half - 1), tk = ml * (16 / half);
;                 const cf2 a = v[m], bb = v[m + half]; cf2 b;
;                 if (tk == 0) b = bb;
;                 else if (tk == 8) { b.x = -bb.y; b.y = bb.x; }
;                 else { const cf2 w = {fc32(tk), -fs32(tk)}; b = cmulcf(bb, w); }
;                 v[m].x = a.x + b.x; v[m].y = a.y + b.y; v[m + half].x = a.x - b.x; v[m + half].y = a.y - b.y;
;             }
;         }
;     }
; }
; template <int R, int F, bool CONJ> FFT_HD inline void tw_apply(cf2 (&v)[1 << R], cf2 pf, cf2 th) {
;     constexpr int j = fbrev(F, R);
;     v[j] = CONJ ? cmulcf(v[j], pf) : cmulf(v[j], pf);
;     if constexpr (2 * F < (1 << R)) {
;         const cf2 p2 = cmulf(pf, pf);
;         tw_apply<R, 2 * F, CONJ>(v, p2, th);
;         const cf2 p3 = cmulf(p2, th);
;         tw_apply<R, 2 * F + 1, CONJ>(v, p3, th);
;     }
; }
	s_mov_b32 s81, s61
	v_mul_f32_e32 v155, 0xbec3ef15, v155
	v_mul_f32_e32 v157, 0x3f6c835e, v43
	v_mov_b32_e32 v154, v60
	v_pk_mul_f32 v[152:153], v[152:153], s[82:83]
	v_mov_b32_e32 v156, v2
	v_mov_b32_e32 v190, v60
	v_sub_f32_e32 v9, v11, v27
	v_pk_fma_f32 v[152:153], v[160:161], s[80:81], v[152:153]
	v_pk_add_f32 v[72:73], v[154:155], v[156:157] neg_lo:[0,1] neg_hi:[0,1]
	v_pk_add_f32 v[60:61], v[2:3], v[60:61]
	v_pk_mul_f32 v[2:3], v[2:3], v[190:191]
	v_pk_add_f32 v[50:51], v[80:81], v[80:81] op_sel_hi:[0,1]
	v_mov_b32_e32 v8, v6
	v_mul_f32_e32 v6, 0x3ec3ef15, v9
	v_mul_f32_e32 v64, 0x3f6c835e, v9
	v_sub_f32_e32 v9, v17, v31
	v_fma_f32 v69, v142, s80, -v69
	v_mov_b32_e32 v68, v148
	v_sub_f32_e32 v2, v72, v152
	v_mul_f32_e32 v57, 0x3f6c835e, v9
	v_mul_f32_e32 v50, 0xbec3ef15, v9
	v_mov_b32_e32 v9, v7
	v_mov_b32_e32 v147, v67
	v_pk_add_f32 v[66:67], v[148:149], v[144:145] neg_lo:[0,1] neg_hi:[0,1]
	v_pk_add_f32 v[70:71], v[68:69], v[144:145]
	v_mov_b32_e32 v61, v3
	v_pk_add_f32 v[2:3], v[2:3], v[72:73] op_sel_hi:[0,1]
	v_pk_add_f32 v[54:55], v[84:85], v[84:85] op_sel:[0,1] op_sel_hi:[1,0]
	v_pk_mul_f32 v[82:83], v[8:9], v[8:9]
	v_mul_f32_e32 v85, v8, v7
	v_mov_b32_e32 v151, v5
	v_mov_b32_e32 v67, v71
	v_mov_b32_e32 v141, v3
	v_mov_b32_e32 v84, v82
	v_mov_b32_e32 v82, v83
	v_mov_b32_e32 v83, v85
	v_pk_mov_b32 v[158:159], v[158:159], v[74:75] op_sel:[1,0]
	v_mov_b32_e32 v77, v75
	v_pk_add_f32 v[4:5], v[146:147], v[150:151]
	s_mov_b32 s83, s60
	v_pk_mul_f32 v[66:67], v[66:67], s[80:81]
	v_pk_add_f32 v[70:71], v[138:139], v[140:141]
	v_pk_add_f32 v[88:89], v[84:85], v[82:83] neg_lo:[0,1] neg_hi:[0,1]
	v_pk_add_f32 v[82:83], v[84:85], v[82:83]
	v_pk_add_f32 v[74:75], v[158:159], v[76:77]
	v_mov_b32_e32 v76, v52
	v_mov_b32_e32 v77, v80
	v_mov_b32_e32 v80, v53
	v_pk_fma_f32 v[4:5], v[4:5], s[82:83], v[66:67] neg_lo:[0,0,1] neg_hi:[0,0,1]
	v_mov_b32_e32 v66, v54
	v_mov_b32_e32 v67, v70
	v_mov_b32_e32 v162, v59
	v_mov_b32_e32 v86, v88
	v_mov_b32_e32 v87, v83
	v_mov_b32_e32 v134, v58
	v_pk_add_f32 v[76:77], v[76:77], v[80:81] neg_lo:[0,1] neg_hi:[0,1]
	v_add_f32_e32 v44, v72, v152
	v_pk_add_f32 v[66:67], v[66:67], v[74:75] neg_lo:[0,1] neg_hi:[0,1]
	v_pk_mul_f32 v[90:91], v[86:87], v[86:87]
	v_pk_mul_f32 v[92:93], v[86:87], v[82:83] op_sel:[0,1] op_sel_hi:[1,0]
	v_pk_add_f32 v[134:135], v[134:135], v[162:163] neg_lo:[0,1] neg_hi:[0,1]
	v_pk_mul_f32 v[2:3], v[138:139], v[140:141]
	v_sub_f32_e32 v43, v145, v69
	v_add_f32_e32 v46, v44, v153
	v_add_f32_e32 v44, v60, v4
	v_pk_add_f32 v[68:69], v[76:77], v[66:67] neg_lo:[0,1] neg_hi:[0,1]
	v_pk_add_f32 v[66:67], v[76:77], v[66:67]
	v_mov_b32_e32 v94, v90
	v_mov_b32_e32 v95, v92
	v_pk_mov_b32 v[90:91], v[90:91], v[92:93] op_sel:[1,0]
	v_mov_b32_e32 v71, v3
	v_pk_add_f32 v[72:73], v[44:45], v[4:5] op_sel_hi:[0,1]
	v_mul_f32_e32 v79, 0x3f3504f3, v68
	v_mov_b32_e32 v68, v66
	v_mul_f32_e32 v67, 0x3f3504f3, v67
	v_mov_b32_e32 v78, v134
	v_mov_b32_e32 v66, v135
	v_mul_f32_e32 v5, 0x3ec3ef15, v43
	v_mov_b32_e32 v192, v75
	v_pk_add_f32 v[92:93], v[94:95], v[90:91] neg_lo:[0,1] neg_hi:[0,1]
	v_pk_add_f32 v[122:123], v[94:95], v[90:91]
	v_pk_add_f32 v[66:67], v[78:79], v[66:67] neg_lo:[0,1] neg_hi:[0,1]
	s_mov_b32 s83, s80
	v_mul_f32_e32 v44, 0x3f3504f3, v69
	v_pk_add_f32 v[4:5], v[60:61], v[4:5] neg_lo:[0,1] neg_hi:[0,1]
	v_mul_f32_e32 v10, v10, v46
	v_pk_add_f32 v[70:71], v[70:71], v[192:193]
	v_pk_mul_f32 v[138:139], v[2:3], s[14:15]
	v_pk_add_f32 v[52:53], v[52:53], v[52:53] op_sel:[0,1] op_sel_hi:[1,0]
	v_pk_mov_b32 v[54:55], v[2:3], v[54:55] op_sel:[1,0]
	v_mov_b32_e32 v126, v92
	v_mov_b32_e32 v127, v123
	v_pk_add_f32 v[136:137], v[134:135], v[134:135] op_sel:[0,1] op_sel_hi:[1,0]
	v_add_f32_e32 v49, v66, v67
	v_pk_fma_f32 v[66:67], v[68:69], s[82:83], v[44:45] op_sel_hi:[1,1,0] neg_lo:[0,0,1] neg_hi:[0,0,1]
	v_pk_add_f32 v[76:77], v[4:5], v[4:5] op_sel_hi:[0,1]
	v_mul_f32_e32 v5, 0x3f6c835e, v10
	v_pk_add_f32 v[58:59], v[58:59], v[58:59] op_sel:[0,1] op_sel_hi:[1,0]
	v_pk_add_f32 v[60:61], v[62:63], v[62:63] op_sel:[0,1] op_sel_hi:[1,0]
	v_mov_b32_e32 v138, v70
	v_mov_b32_e32 v56, v52
	v_pk_add_f32 v[52:53], v[52:53], v[70:71]
	v_pk_mul_f32 v[70:71], v[54:55], s[26:27]
	v_pk_add_f32 v[54:55], v[54:55], v[74:75] op_sel_hi:[1,0]
	v_pk_mul_f32 v[90:91], v[126:127], v[122:123] op_sel:[0,1] op_sel_hi:[1,0]
	v_pk_add_f32 v[66:67], v[136:137], v[66:67]
	v_mov_b32_e32 v59, v6
	v_mov_b32_e32 v61, v5
	v_mul_f32_e32 v62, 0x3ec3ef15, v10
	v_mov_b32_e32 v65, v58
	v_mov_b32_e32 v63, v60
	v_mov_b32_e32 v76, v23
	v_pk_add_f32 v[56:57], v[56:57], v[138:139] neg_lo:[0,1] neg_hi:[0,1]
	v_mov_b32_e32 v71, v55
	v_pk_add_f32 v[120:121], v[90:91], v[90:91]
	v_pk_mul_f32 v[90:91], v[8:9], v[122:123] op_sel:[1,1] op_sel_hi:[0,1]
	v_pk_add_f32 v[68:69], v[58:59], v[60:61]
	v_pk_add_f32 v[60:61], v[64:65], v[62:63] neg_lo:[0,1] neg_hi:[0,1]
	v_pk_add_f32 v[64:65], v[20:21], v[76:77] neg_lo:[0,1] neg_hi:[0,1]
	v_pk_mul_f32 v[58:59], v[20:21], v[76:77]
	v_mov_b32_e32 v72, v25
	v_mov_b32_e32 v53, v57
	v_pk_add_f32 v[54:55], v[50:51], v[70:71] neg_lo:[0,1] neg_hi:[0,1]
	v_mov_b32_e32 v50, v33
	v_mov_b32_e32 v51, v66
	v_pk_fma_f32 v[94:95], v[8:9], v[92:93], v[90:91] op_sel_hi:[1,0,1] neg_lo:[0,0,1] neg_hi:[0,0,1]
	v_pk_fma_f32 v[114:115], v[8:9], v[92:93], v[90:91] op_sel_hi:[1,0,1]
	v_pk_mul_f32 v[90:91], v[8:9], v[82:83] op_sel:[1,1] op_sel_hi:[0,1]
	v_mov_b32_e32 v65, v59
	v_mul_f32_e32 v6, 0x3ec3ef15, v59
	v_pk_add_f32 v[136:137], v[14:15], v[72:73] neg_lo:[0,1] neg_hi:[0,1]
	v_pk_mul_f32 v[72:73], v[14:15], v[72:73]
	v_pk_add_f32 v[70:71], v[18:19], v[50:51] neg_lo:[0,1] neg_hi:[0,1]
	v_pk_mul_f32 v[74:75], v[18:19], v[50:51]
; #define FFT_HD __device__ __attribute__((always_inline))
; template <int R> FFT_HD inline void reg_fwd(cf2 (&v)[1 << R], cf2 th) { dft_fwd_reg<R>(v); tw_apply<R, 1, false>(v, th, th); }
; template <int R> FFT_HD inline void reg_inv(cf2 (&v)[1 << R], cf2 th) { tw_apply<R, 1, true>(v, th, th); dft_inv_reg<R>(v); }
; __device__ __forceinline__ cf2 tw_fresh(cf2 th) { asm volatile("" : "+v"(th.x), "+v"(th.y)); return th; }
; template <int R> FFT_HD inline void dft_fwd_reg(cf2 (&v)[1 << R]) {
;     constexpr int n = 1 << R;
; #pragma unroll
;     for (int s = 0; s < R; ++s) {
;         const int half = n >> (s + 1);
; #pragma unroll
;         for (int m = 0; m < n; ++m) {
;             if ((m & half) == 0) {
;                 const int ml = m & (half - 1), tk = ml * (16 / half);
;                 const cf2 a = v[m], b = v[m + half];
;                 v[m].x = a.x + b.x; v[m].y = a.y + b.y;
;                 const cf2 d = {a.x - b.x, a.y - b.y};
;                 if (tk == 0) v[m + half] = d;
;                 else if (tk == 8) { v[m + half].x = d.y; v[m + half].y = -d.x; }
;                 else { const cf2 w = {fc32(tk), -fs32(tk)}; v[m + half] = cmulf(d, w); }
;             }
;         }
;     }
; }
; __device__ __forceinline__ void hyena_conv_s2(const float* HYT, float* ZOUT, const float* FILT, const cf2* TW, LAS unsigned char* lds, int vb, int nb, int tid_in) {
;     ...
;             grp_load<4, 1024>(X, grp, v); reg_inv<4>(v, th);
; #pragma unroll
;             for (int m = 0; m < 16; ++m) { v[m].x = m < 8 ? v[m].x * g1[m] : 0.f; v[m].y = fl[m]; }
;             reg_fwd<4>(v, tw_fresh(th)); grp_store<4, 1024>(X, grp, v); }
	v_pk_add_f32 v[50:51], v[68:69], v[52:53]
	v_pk_add_f32 v[52:53], v[68:69], v[56:57] neg_lo:[0,1] neg_hi:[0,1]
	v_pk_mov_b32 v[124:125], v[122:123], v[92:93] op_sel:[1,0]
	v_pk_fma_f32 v[92:93], v[8:9], v[88:89], v[90:91] op_sel_hi:[1,0,1] neg_lo:[0,0,1] neg_hi:[0,0,1]
	v_pk_fma_f32 v[102:103], v[8:9], v[88:89], v[90:91] op_sel_hi:[1,0,1]
	v_mul_f32_e32 v4, v13, v49
	v_pk_fma_f32 v[76:77], v[64:65], s[84:85], v[6:7] op_sel_hi:[1,1,0] neg_lo:[0,0,1] neg_hi:[0,0,1]
	v_mul_f32_e32 v13, 0x3ec3ef15, v136
	v_mul_f32_e32 v81, 0x3f6c835e, v73
	v_mov_b32_e32 v80, v41
	v_mov_b32_e32 v52, v50
	v_mov_b32_e32 v43, v187
	v_pk_add_f32 v[68:69], v[60:61], v[54:55] neg_lo:[0,1] neg_hi:[0,1]
	v_mov_b32_e32 v44, v187
	v_mov_b32_e32 v110, v92
	v_mov_b32_e32 v111, v103
	v_mov_b32_e32 v78, v187
	v_mov_b32_e32 v79, v76
	v_pk_add_f32 v[80:81], v[12:13], v[80:81] neg_lo:[0,1] neg_hi:[0,1]
	v_pk_mul_f32 v[56:57], v[42:43], v[52:53]
	v_pk_mul_f32 v[142:143], v[44:45], v[68:69]
	v_sub_f32_e32 v47, v16, v29
	v_pk_mov_b32 v[84:85], v[82:83], v[88:89] op_sel:[1,0]
	v_pk_mul_f32 v[88:89], v[110:111], v[110:111]
	v_pk_mul_f32 v[90:91], v[110:111], v[102:103] op_sel:[0,1] op_sel_hi:[1,0]
	v_pk_mul_f32 v[134:135], v[80:81], v[78:79]
	v_mul_f32_e32 v2, 0x3f6c835e, v59
	v_pk_mov_b32 v[144:145], v[142:143], v[142:143] op_sel:[1,0]
	v_mov_b32_e32 v46, v57
	v_mov_b32_e32 v57, v16
	v_mov_b32_e32 v16, v3
	v_sub_f32_e32 v48, v199, v39
	v_mov_b32_e32 v22, v183
	v_pk_mov_b32 v[112:113], v[102:103], v[92:93] op_sel:[1,0]
	v_mov_b32_e32 v92, v88
	v_mov_b32_e32 v93, v90
	v_pk_mov_b32 v[88:89], v[88:89], v[90:91] op_sel:[1,0]
	v_mov_b32_e32 v67, v134
	v_pk_fma_f32 v[64:65], v[64:65], s[60:61], v[2:3] op_sel_hi:[1,1,0] neg_lo:[0,0,1] neg_hi:[0,0,1]
	v_mov_b32_e32 v49, v145
	v_mov_b32_e32 v5, v12
	v_mov_b32_e32 v12, v73
	v_mov_b32_e32 v13, v14
	v_mov_b32_e32 v145, v199
	v_pk_add_f32 v[2:3], v[16:17], v[30:31]
	v_mov_b32_e32 v16, v75
	v_mov_b32_e32 v17, v18
	v_mov_b32_e32 v18, v59
	v_mov_b32_e32 v19, v20
	v_pk_add_f32 v[98:99], v[92:93], v[88:89] neg_lo:[0,1] neg_hi:[0,1]
	v_pk_add_f32 v[88:89], v[92:93], v[88:89]
	v_mul_f32_e32 v62, 0x3f3504f3, v4
	v_pk_add_f32 v[78:79], v[80:81], v[78:79] neg_lo:[0,1] neg_hi:[0,1]
	v_fmac_f32_e32 v67, 0x3f3504f3, v4
	v_pk_fma_f32 v[146:147], v[42:43], v[52:53], v[48:49] neg_lo:[0,0,1] neg_hi:[0,0,1]
	v_pk_fma_f32 v[42:43], v[42:43], v[52:53], v[142:143] op_sel:[0,0,1] op_sel_hi:[1,1,0]
	v_pk_add_f32 v[28:29], v[56:57], v[28:29]
	v_pk_add_f32 v[10:11], v[10:11], v[26:27]
	v_pk_add_f32 v[4:5], v[4:5], v[40:41]
	v_pk_add_f32 v[12:13], v[12:13], v[24:25]
	v_pk_add_f32 v[14:15], v[144:145], v[38:39]
	v_pk_add_f32 v[16:17], v[16:17], v[32:33]
	v_pk_add_f32 v[18:19], v[18:19], v[22:23]
	v_mov_b32_e32 v92, v98
	v_mov_b32_e32 v93, v89
	v_mov_b32_e32 v137, v73
	v_mov_b32_e32 v135, v79
	v_mov_b32_e32 v147, v43
	v_pk_fma_f32 v[42:43], v[44:45], v[68:69], v[46:47] neg_lo:[0,0,1] neg_hi:[0,0,1]
	v_pk_fma_f32 v[44:45], v[44:45], v[68:69], v[46:47]
	v_mov_b32_e32 v63, v187
	v_pk_add_f32 v[20:21], v[28:29], v[14:15]
	v_pk_add_f32 v[22:23], v[10:11], v[2:3]
	v_pk_add_f32 v[24:25], v[4:5], v[16:17]
	v_pk_add_f32 v[26:27], v[12:13], v[18:19]
	v_pk_mul_f32 v[130:131], v[92:93], v[88:89] op_sel:[0,1] op_sel_hi:[1,0]
	v_pk_mul_f32 v[136:137], v[136:137], s[26:27]
	v_mov_b32_e32 v43, v45
	v_pk_add_f32 v[44:45], v[134:135], v[62:63] neg_lo:[0,1] neg_hi:[0,1]
	v_pk_mul_f32 v[52:53], v[78:79], s[2:3]
	v_mov_b32_e32 v61, v81
	v_mov_b32_e32 v55, v76
	v_pk_add_f32 v[30:31], v[20:21], v[24:25] neg_lo:[0,1] neg_hi:[0,1]
	v_pk_add_f32 v[38:39], v[22:23], v[26:27] neg_lo:[0,1] neg_hi:[0,1]
	v_mov_b32_e32 v45, v53
	v_pk_add_f32 v[52:53], v[60:61], v[54:55]
	v_pk_add_f32 v[32:33], v[22:23], v[26:27]
	v_mov_b32_e32 v60, v30
	v_mov_b32_e32 v61, v22
	v_pk_mov_b32 v[22:23], v[38:39], v[26:27] op_sel:[1,0]
	v_mov_b32_e32 v131, v136
	v_mov_b32_e32 v136, v130
	v_mov_b32_e32 v74, v70
	v_pk_add_f32 v[22:23], v[60:61], v[22:23] neg_lo:[0,1] neg_hi:[0,1]
	v_pk_add_f32 v[60:61], v[130:131], v[136:137]
	v_pk_mul_f32 v[138:139], v[74:75], s[80:81] op_sel_hi:[1,0]
	v_pk_mul_f32 v[70:71], v[70:71], s[82:83]
	v_pk_add_f32 v[72:73], v[60:61], v[64:65] op_sel_hi:[1,0] neg_lo:[0,1] neg_hi:[0,1]
	v_mov_b32_e32 v186, v139
	v_mov_b32_e32 v71, v73
	v_pk_add_f32 v[72:73], v[70:71], v[186:187] neg_lo:[0,1] neg_hi:[0,1]
	v_pk_mul_f32 v[70:71], v[70:71], v[186:187]
	v_pk_mul_f32 v[128:129], v[126:127], v[126:127]
	v_pk_mul_f32 v[132:133], v[92:93], v[92:93]
	v_pk_add_f32 v[12:13], v[12:13], v[18:19] neg_lo:[0,1] neg_hi:[0,1]
	v_pk_add_f32 v[18:19], v[20:21], v[24:25]
	v_mov_b32_e32 v73, v71
	v_mov_b32_e32 v49, v44
	v_mov_b32_e32 v57, v72
	v_pk_fma_f32 v[140:141], v[74:75], s[80:81], v[138:139] op_sel:[0,0,1] op_sel_hi:[1,0,0] neg_lo:[0,0,1] neg_hi:[0,0,1]
	v_pk_add_f32 v[40:41], v[18:19], v[32:33]
	v_pk_add_f32 v[58:59], v[18:19], v[32:33] neg_lo:[0,1] neg_hi:[0,1]
	v_mov_b32_e32 v18, v128
	v_mov_b32_e32 v32, v129
	v_mov_b32_e32 v20, v132
	v_mov_b32_e32 v24, v133
	v_pk_add_f32 v[76:77], v[44:45], v[72:73] neg_lo:[0,1] neg_hi:[0,1]
	v_pk_add_f32 v[44:45], v[48:49], v[56:57]
	v_add_f32_e32 v142, v67, v140
	v_pk_add_f32 v[18:19], v[18:19], v[32:33] neg_lo:[0,1] neg_hi:[0,1]
	v_pk_add_f32 v[20:21], v[20:21], v[24:25] neg_lo:[0,1] neg_hi:[0,1]
	v_mov_b32_e32 v74, v7
	v_mov_b32_e32 v75, v64
	v_mov_b32_e32 v46, v44
	v_mov_b32_e32 v32, v58
	v_mov_b32_e32 v33, v120
	v_mul_f32_e32 v6, v19, v120
	v_pk_add_f32 v[26:27], v[38:39], v[30:31] op_sel:[1,0] op_sel_hi:[0,1]
	v_pk_add_f32 v[30:31], v[20:21], v[22:23] neg_lo:[0,1] neg_hi:[0,1]
	v_pk_add_f32 v[74:75], v[74:75], v[60:61]
	v_pk_add_f32 v[46:47], v[46:47], v[142:143] neg_lo:[0,1] neg_hi:[0,1]
; #define FFT_HD __device__ __attribute__((always_inline))
; template <int R> FFT_HD inline void dft_fwd_reg(cf2 (&v)[1 << R]) {
;     constexpr int n = 1 << R;
; #pragma unroll
;     for (int s = 0; s < R; ++s) {
;         const int half = n >> (s + 1);
; #pragma unroll
;         for (int m = 0; m < n; ++m) {
;             if ((m & half) == 0) {
;                 const int ml = m & (half - 1), tk = ml * (16 / half);
;                 const cf2 a = v[m], b = v[m + half];
;                 v[m].x = a.x + b.x; v[m].y = a.y + b.y;
;                 const cf2 d = {a.x - b.x, a.y - b.y};
;                 if (tk == 0) v[m + half] = d;
;                 else if (tk == 8) { v[m + half].x = d.y; v[m + half].y = -d.x; }
;                 else { const cf2 w = {fc32(tk), -fs32(tk)}; v[m + half] = cmulf(d, w); }
;             }
;         }
;     }
; }
; template <int R, int F, bool CONJ> FFT_HD inline void tw_apply(cf2 (&v)[1 << R], cf2 pf, cf2 th) {
;     constexpr int j = fbrev(F, R);
;     v[j] = CONJ ? cmulcf(v[j], pf) : cmulf(v[j], pf);
;     if constexpr (2 * F < (1 << R)) {
;         const cf2 p2 = cmulf(pf, pf);
;         tw_apply<R, 2 * F, CONJ>(v, p2, th);
;         const cf2 p3 = cmulf(p2, th);
;         tw_apply<R, 2 * F + 1, CONJ>(v, p3, th);
;     }
; }
	v_pk_add_f32 v[54:55], v[52:53], v[52:53] op_sel:[0,1] op_sel_hi:[1,0] neg_lo:[0,1] neg_hi:[0,1]
	v_pk_fma_f32 v[32:33], v[18:19], v[32:33], v[6:7] op_sel_hi:[1,1,0] neg_lo:[0,0,1] neg_hi:[0,0,1]
	v_mov_b32_e32 v27, v31
	v_mul_f32_e32 v6, v123, v31
	v_mov_b32_e32 v25, v51
	v_mov_b32_e32 v143, v47
	v_pk_mov_b32 v[50:51], v[50:51], v[52:53] op_sel:[1,0]
	v_mov_b32_e32 v52, v75
	v_pk_fma_f32 v[30:31], v[126:127], v[26:27], v[6:7] op_sel_hi:[1,1,0] neg_lo:[0,0,1] neg_hi:[0,0,1]
	v_mul_f32_e32 v6, v123, v26
	v_pk_add_f32 v[48:49], v[142:143], v[44:45]
	v_pk_add_f32 v[50:51], v[50:51], v[52:53]
	v_pk_fma_f32 v[26:27], v[124:125], v[26:27], v[6:7] op_sel_hi:[1,1,0]
	v_mov_b32_e32 v6, v7
	v_pk_add_f32 v[52:53], v[48:49], v[50:51] neg_lo:[0,1] neg_hi:[0,1]
	v_pk_add_f32 v[48:49], v[48:49], v[50:51]
	v_pk_mul_f32 v[64:65], v[6:7], v[60:61]
	v_mul_f32_e32 v6, v7, v49
	v_pk_mul_f32 v[58:59], v[120:121], v[58:59]
	v_mov_b32_e32 v62, v7
	v_mov_b32_e32 v63, v8
	v_pk_mul_f32 v[120:121], v[8:9], v[120:121] op_sel:[1,0] op_sel_hi:[0,0]
	v_pk_fma_f32 v[50:51], v[8:9], v[48:49], v[6:7] op_sel_hi:[1,1,0] neg_lo:[0,0,1] neg_hi:[0,0,1]
	v_mul_f32_e32 v6, v7, v48
	v_pk_fma_f32 v[58:59], v[18:19], v[18:19], v[58:59] op_sel:[1,0,0] op_sel_hi:[0,1,1]
	v_pk_fma_f32 v[126:127], v[8:9], v[18:19], v[120:121] op_sel_hi:[1,0,1] neg_lo:[0,0,1] neg_hi:[0,0,1]
	v_pk_fma_f32 v[18:19], v[8:9], v[18:19], v[120:121] op_sel_hi:[1,0,1]
	v_pk_fma_f32 v[6:7], v[62:63], v[48:49], v[6:7] op_sel_hi:[1,1,0]
	v_mul_f32_e32 v66, 0xbf3504f3, v79
	v_mul_f32_e32 v24, v8, v20
	v_mov_b32_e32 v65, v75
	v_pk_mov_b32 v[70:71], v[70:71], v[140:141] op_sel:[1,0]
	v_mov_b32_e32 v120, v126
	v_mov_b32_e32 v121, v19
	v_mov_b32_e32 v44, v54
	v_mul_f32_e32 v6, v19, v53
	v_pk_add_f32 v[66:67], v[66:67], v[70:71] neg_lo:[0,1] neg_hi:[0,1]
	v_pk_add_f32 v[24:25], v[24:25], v[64:65] neg_lo:[0,1] neg_hi:[0,1]
	v_pk_add_f32 v[44:45], v[46:47], v[44:45] neg_lo:[0,1] neg_hi:[0,1]
	v_pk_fma_f32 v[48:49], v[120:121], v[52:53], v[6:7] op_sel_hi:[1,1,0] neg_lo:[0,0,1] neg_hi:[0,0,1]
	v_pk_mov_b32 v[56:57], v[18:19], v[126:127] op_sel:[1,0]
	v_mul_f32_e32 v6, v19, v52
	v_pk_add_f32 v[64:65], v[42:43], v[66:67] neg_lo:[0,1] neg_hi:[0,1]
	v_pk_add_f32 v[70:71], v[146:147], v[76:77]
	v_pk_add_f32 v[78:79], v[146:147], v[76:77] neg_lo:[0,1] neg_hi:[0,1]
	v_pk_fma_f32 v[18:19], v[56:57], v[52:53], v[6:7] op_sel_hi:[1,1,0]
	v_pk_add_f32 v[46:47], v[46:47], v[54:55]
	v_pk_add_f32 v[52:53], v[44:45], v[24:25] neg_lo:[0,1] neg_hi:[0,1]
	v_mov_b32_e32 v147, v42
	v_mov_b32_e32 v77, v66
	v_mov_b32_e32 v116, v94
	v_mov_b32_e32 v117, v115
	v_pk_add_f32 v[80:81], v[42:43], v[66:67]
	v_mov_b32_e32 v122, v64
	v_pk_add_f32 v[124:125], v[78:79], v[64:65] neg_lo:[0,1] neg_hi:[0,1]
	v_mov_b32_e32 v47, v53
	v_mul_f32_e32 v6, v115, v53
	v_pk_add_f32 v[42:43], v[146:147], v[76:77]
	v_mov_b32_e32 v64, v71
	v_pk_mov_b32 v[118:119], v[114:115], v[94:95] op_sel:[1,0]
	v_pk_add_f32 v[2:3], v[10:11], v[2:3] neg_lo:[0,1] neg_hi:[0,1]
	v_pk_fma_f32 v[52:53], v[116:117], v[46:47], v[6:7] op_sel_hi:[1,1,0] neg_lo:[0,0,1] neg_hi:[0,0,1]
	v_mul_f32_e32 v6, v115, v46
	v_pk_add_f32 v[54:55], v[42:43], v[64:65]
	v_mul_f32_e32 v11, 0x3f3504f3, v2
	v_pk_add_f32 v[38:39], v[20:21], v[22:23]
	v_mov_b32_e32 v68, v20
	v_mov_b32_e32 v69, v60
	v_mul_f32_e32 v10, v8, v60
	v_pk_fma_f32 v[46:47], v[118:119], v[46:47], v[6:7] op_sel_hi:[1,1,0]
	v_mul_f32_e32 v6, v103, v55
	v_pk_fma_f32 v[68:69], v[62:63], v[68:69], v[10:11] op_sel_hi:[1,1,0]
	v_pk_fma_f32 v[56:57], v[110:111], v[54:55], v[6:7] op_sel_hi:[1,1,0] neg_lo:[0,0,1] neg_hi:[0,0,1]
	v_mul_f32_e32 v6, v103, v54
	v_pk_mul_f32 v[62:63], v[60:61], v[38:39] op_sel:[0,1] op_sel_hi:[1,0]
	v_pk_fma_f32 v[54:55], v[112:113], v[54:55], v[6:7] op_sel_hi:[1,1,0]
	v_pk_fma_f32 v[62:63], v[20:21], v[22:23], v[62:63] neg_lo:[0,0,1] neg_hi:[0,0,1]
	v_mov_b32_e32 v61, v20
	v_mov_b32_e32 v23, v39
	v_mul_f32_e32 v6, v60, v22
	v_pk_fma_f32 v[20:21], v[60:61], v[22:23], v[6:7] op_sel_hi:[1,1,0]
	v_pk_add_f32 v[22:23], v[44:45], v[24:25]
	v_mul_f32_e32 v2, 0x3f3504f3, v12
	v_pk_mul_f32 v[38:39], v[68:69], v[22:23] op_sel:[0,1] op_sel_hi:[1,0]
	v_pk_add_f32 v[14:15], v[28:29], v[14:15] neg_lo:[0,1] neg_hi:[0,1]
	v_fma_f32 v28, v3, s80, -v11
	v_pk_mul_f32 v[100:101], v[8:9], v[88:89] op_sel:[1,1] op_sel_hi:[0,1]
	v_mov_b32_e32 v123, v81
	v_pk_fma_f32 v[38:39], v[44:45], v[24:25], v[38:39] neg_lo:[0,0,1] neg_hi:[0,0,1]
	v_mov_b32_e32 v69, v24
	v_mov_b32_e32 v45, v23
	v_mul_f32_e32 v6, v68, v44
	v_mov_b32_e32 v29, v28
	v_fmac_f32_e32 v11, 0x3f3504f3, v3
	v_mov_b32_e32 v10, v28
	v_pk_add_f32 v[4:5], v[4:5], v[16:17] neg_lo:[0,1] neg_hi:[0,1]
	v_pk_fma_f32 v[2:3], v[12:13], s[82:83], v[2:3] op_sel:[1,0,0] op_sel_hi:[1,1,0] neg_lo:[0,0,1] neg_hi:[0,0,1]
	v_pk_fma_f32 v[104:105], v[8:9], v[98:99], v[100:101] op_sel_hi:[1,0,1] neg_lo:[0,0,1] neg_hi:[0,0,1]
	v_pk_fma_f32 v[100:101], v[8:9], v[98:99], v[100:101] op_sel_hi:[1,0,1]
	v_pk_add_f32 v[122:123], v[78:79], v[122:123]
	v_pk_fma_f32 v[22:23], v[68:69], v[44:45], v[6:7] op_sel_hi:[1,1,0]
	v_pk_add_f32 v[24:25], v[80:81], v[78:79] neg_lo:[0,1] neg_hi:[0,1]
	v_pk_add_f32 v[12:13], v[14:15], v[4:5] op_sel:[0,1] op_sel_hi:[1,0] neg_lo:[0,1] neg_hi:[0,1]
	v_pk_add_f32 v[16:17], v[14:15], v[4:5] op_sel:[0,1] op_sel_hi:[1,0]
	v_pk_add_f32 v[68:69], v[10:11], v[2:3]
	v_pk_mov_b32 v[4:5], v[4:5], v[28:29] op_sel:[1,0]
	v_mov_b32_e32 v15, v2
	v_pk_mul_f32 v[96:97], v[116:117], v[116:117]
	v_pk_mul_f32 v[94:95], v[94:95], v[116:117] op_sel_hi:[0,1]
	v_mov_b32_e32 v106, v104
	v_mov_b32_e32 v107, v101
	v_mov_b32_e32 v24, v122
	v_mul_f32_e32 v6, v101, v25
	v_mov_b32_e32 v16, v12
; #define FFT_HD __device__ __attribute__((always_inline))
; template <int R> FFT_HD inline void reg_fwd(cf2 (&v)[1 << R], cf2 th) { dft_fwd_reg<R>(v); tw_apply<R, 1, false>(v, th, th); }
; __device__ __forceinline__ cf2 tw_fresh(cf2 th) { asm volatile("" : "+v"(th.x), "+v"(th.y)); return th; }
; template <int R, int F, bool CONJ> FFT_HD inline void tw_apply(cf2 (&v)[1 << R], cf2 pf, cf2 th) {
;     constexpr int j = fbrev(F, R);
;     v[j] = CONJ ? cmulcf(v[j], pf) : cmulf(v[j], pf);
;     if constexpr (2 * F < (1 << R)) {
;         const cf2 p2 = cmulf(pf, pf);
;         tw_apply<R, 2 * F, CONJ>(v, p2, th);
;         const cf2 p3 = cmulf(p2, th);
;         tw_apply<R, 2 * F + 1, CONJ>(v, p3, th);
;     }
; }
; template <int R, int S> FFT_HD inline int grp_base(int grp) { return (grp / S) * (S << R) + (grp & (S - 1)); }
; template <int R, int S, class P> FFT_HD inline void grp_load(P X, int grp, cf2 (&v)[1 << R]) {
;     P Xb = X + fpad(grp_base<R, S>(grp));
; #pragma unroll
;     for (int m = 0; m < (1 << R); ++m) v[m] = Xb[m * S + ((m * S) >> 3)];
; }
; template <int R, int S, class P> FFT_HD inline void grp_store(P X, int grp, const cf2 (&v)[1 << R]) {
;     P Xb = X + fpad(grp_base<R, S>(grp));
; #pragma unroll
;     for (int m = 0; m < (1 << R); ++m) Xb[m * S + ((m * S) >> 3)] = v[m];
; }
; __device__ __forceinline__ void hyena_conv_s2(const float* HYT, float* ZOUT, const float* FILT, const cf2* TW, LAS unsigned char* lds, int vb, int nb, int tid_in) {
;     ...
;             reg_fwd<4>(v, tw_fresh(th)); grp_store<4, 1024>(X, grp, v); }
	v_pk_add_f32 v[10:11], v[10:11], v[2:3] neg_lo:[0,1] neg_hi:[0,1]
	v_pk_add_f32 v[2:3], v[4:5], v[14:15]
	v_mov_b32_e32 v12, v69
	v_pk_mov_b32 v[108:109], v[100:101], v[104:105] op_sel:[1,0]
	v_pk_fma_f32 v[44:45], v[106:107], v[24:25], v[6:7] op_sel_hi:[1,1,0] neg_lo:[0,0,1] neg_hi:[0,0,1]
	v_mul_f32_e32 v6, v101, v122
	v_pk_add_f32 v[4:5], v[2:3], v[12:13]
	v_mov_b32_e32 v12, v96
	v_mov_b32_e32 v28, v97
	v_mov_b32_e32 v29, v3
	v_mov_b32_e32 v3, v95
	v_mov_b32_e32 v94, v69
	v_pk_fma_f32 v[24:25], v[108:109], v[24:25], v[6:7] op_sel_hi:[1,1,0]
	v_mul_f32_e32 v6, v83, v5
	v_pk_add_f32 v[12:13], v[12:13], v[28:29] neg_lo:[0,1] neg_hi:[0,1]
	v_pk_add_f32 v[28:29], v[2:3], v[94:95] neg_lo:[0,1] neg_hi:[0,1]
	v_pk_add_f32 v[2:3], v[2:3], v[94:95]
	v_mov_b32_e32 v64, v42
	v_mov_b32_e32 v42, v71
	v_pk_fma_f32 v[14:15], v[86:87], v[4:5], v[6:7] op_sel_hi:[1,1,0] neg_lo:[0,0,1] neg_hi:[0,0,1]
	v_mul_f32_e32 v6, v83, v4
	v_pk_mul_f32 v[68:69], v[8:9], v[2:3] op_sel:[1,1] op_sel_hi:[0,1]
	v_pk_add_f32 v[42:43], v[64:65], v[42:43] neg_lo:[0,1] neg_hi:[0,1]
	v_pk_fma_f32 v[4:5], v[84:85], v[4:5], v[6:7] op_sel_hi:[1,1,0]
	v_pk_fma_f32 v[72:73], v[8:9], v[12:13], v[68:69] op_sel_hi:[1,0,1] neg_lo:[0,0,1] neg_hi:[0,0,1]
	v_pk_fma_f32 v[68:69], v[8:9], v[12:13], v[68:69] op_sel_hi:[1,0,1]
	v_mov_b32_e32 v74, v72
	v_mov_b32_e32 v75, v69
	v_mul_f32_e32 v4, v69, v43
	v_pk_fma_f32 v[74:75], v[74:75], v[42:43], v[4:5] op_sel_hi:[1,1,0] neg_lo:[0,0,1] neg_hi:[0,0,1]
	v_pk_mov_b32 v[72:73], v[68:69], v[72:73] op_sel:[1,0]
	v_mul_f32_e32 v4, v69, v42
	v_mov_b32_e32 v29, v3
	v_pk_fma_f32 v[42:43], v[72:73], v[42:43], v[4:5] op_sel_hi:[1,1,0]
	v_mul_f32_e32 v4, v13, v3
	v_pk_fma_f32 v[68:69], v[12:13], v[28:29], v[4:5] op_sel_hi:[1,1,0] neg_lo:[0,0,1] neg_hi:[0,0,1]
	v_pk_mov_b32 v[72:73], v[2:3], v[12:13] op_sel:[1,0]
	v_mov_b32_e32 v29, v13
	v_mul_f32_e32 v2, v3, v28
	v_pk_mov_b32 v[90:91], v[88:89], v[98:99] op_sel:[1,0]
	v_pk_mul_f32 v[98:99], v[106:107], v[106:107]
	v_pk_mul_f32 v[104:105], v[106:107], v[100:101] op_sel:[0,1] op_sel_hi:[1,0]
	v_pk_add_f32 v[70:71], v[16:17], v[10:11] neg_lo:[0,1] neg_hi:[0,1]
	v_pk_add_f32 v[10:11], v[16:17], v[10:11]
	v_pk_fma_f32 v[2:3], v[72:73], v[28:29], v[2:3] op_sel_hi:[1,1,0]
	v_mov_b32_e32 v60, v98
	v_mov_b32_e32 v61, v104
	v_pk_mov_b32 v[64:65], v[98:99], v[104:105] op_sel:[1,0]
	v_mov_b32_e32 v12, v10
	v_mov_b32_e32 v13, v71
	v_mul_f32_e32 v2, v89, v71
	v_pk_add_f32 v[66:67], v[60:61], v[64:65] neg_lo:[0,1] neg_hi:[0,1]
	v_pk_add_f32 v[60:61], v[60:61], v[64:65]
	v_pk_fma_f32 v[28:29], v[92:93], v[12:13], v[2:3] op_sel_hi:[1,1,0] neg_lo:[0,0,1] neg_hi:[0,0,1]
	v_mul_f32_e32 v2, v89, v10
	v_mov_b32_e32 v64, v66
	v_mov_b32_e32 v65, v61
	v_mov_b32_e32 v16, v70
	v_mov_b32_e32 v17, v11
	v_pk_fma_f32 v[12:13], v[90:91], v[12:13], v[2:3] op_sel_hi:[1,1,0]
	v_mul_f32_e32 v2, v61, v11
	v_pk_fma_f32 v[10:11], v[64:65], v[16:17], v[2:3] op_sel_hi:[1,1,0] neg_lo:[0,0,1] neg_hi:[0,0,1]
	v_pk_mov_b32 v[64:65], v[60:61], v[66:67] op_sel:[1,0]
	v_mul_f32_e32 v2, v61, v70
	v_pk_mul_f32 v[60:61], v[8:9], v[60:61] op_sel:[1,1] op_sel_hi:[0,1]
	v_pk_fma_f32 v[16:17], v[64:65], v[16:17], v[2:3] op_sel_hi:[1,1,0]
	v_pk_fma_f32 v[64:65], v[8:9], v[66:67], v[60:61] op_sel_hi:[1,0,1] neg_lo:[0,0,1] neg_hi:[0,0,1]
	v_pk_fma_f32 v[8:9], v[8:9], v[66:67], v[60:61] op_sel_hi:[1,0,1]
	v_mov_b32_e32 v125, v123
	v_mov_b32_e32 v60, v64
	v_mov_b32_e32 v61, v9
	v_mul_f32_e32 v2, v9, v123
	v_pk_fma_f32 v[60:61], v[60:61], v[124:125], v[2:3] op_sel_hi:[1,1,0] neg_lo:[0,0,1] neg_hi:[0,0,1]
	v_pk_mov_b32 v[64:65], v[8:9], v[64:65] op_sel:[1,0]
	v_mul_f32_e32 v2, v9, v124
	v_pk_fma_f32 v[8:9], v[64:65], v[124:125], v[2:3] op_sel_hi:[1,1,0]
	v_mov_b32_e32 v33, v58
	v_mov_b32_e32 v31, v27
	v_mov_b32_e32 v63, v21
	v_mov_b32_e32 v15, v5
	v_mov_b32_e32 v69, v3
	v_mov_b32_e32 v29, v13
	v_mov_b32_e32 v11, v17
	v_mov_b32_e32 v51, v7
	v_mov_b32_e32 v49, v19
	v_mov_b32_e32 v53, v47
	v_mov_b32_e32 v39, v23
	v_mov_b32_e32 v57, v55
	v_mov_b32_e32 v75, v43
	v_mov_b32_e32 v45, v25
	v_mov_b32_e32 v61, v9
	s_movk_i32 s3, 0x200
	ds_write2st64_b64 v177, v[40:41], v[32:33] offset1:18
	ds_write2st64_b64 v177, v[30:31], v[62:63] offset0:36 offset1:54
	ds_write2st64_b64 v177, v[14:15], v[68:69] offset0:72 offset1:90
	ds_write2st64_b64 v177, v[28:29], v[10:11] offset0:108 offset1:126
	ds_write_b64 v178, v[50:51]
	ds_write_b64 v179, v[48:49]
	ds_write_b64 v180, v[52:53]
	ds_write_b64 v181, v[38:39]
	ds_write_b64 v182, v[56:57]
	ds_write_b64 v185, v[74:75]
	ds_write_b64 v189, v[44:45]
	ds_write_b64 v198, v[60:61]
	s_cbranch_vccz .LBB0_661
	s_waitcnt lgkmcnt(0)
	s_barrier
; #define FFT_HD __device__ __attribute__((always_inline))
; template <int R> FFT_HD inline void reg_fwd(cf2 (&v)[1 << R], cf2 th) { dft_fwd_reg<R>(v); tw_apply<R, 1, false>(v, th, th); }
; template <int R, int F, bool CONJ> FFT_HD inline void tw_apply(cf2 (&v)[1 << R], cf2 pf, cf2 th) {
;     constexpr int j = fbrev(F, R);
;     v[j] = CONJ ? cmulcf(v[j], pf) : cmulf(v[j], pf);
;     if constexpr (2 * F < (1 << R)) {
;         const cf2 p2 = cmulf(pf, pf);
;         tw_apply<R, 2 * F, CONJ>(v, p2, th);
;         const cf2 p3 = cmulf(p2, th);
;         tw_apply<R, 2 * F + 1, CONJ>(v, p3, th);
;     }
; }
; __device__ __forceinline__ void s_mid2(ldsc X, const cf2* TW, int tid) {
; #pragma unroll 1
;     for (int q = 0; q < 2; ++q) { const int grp = tid + 512 * q; cf2 v[16]; grp_load<4, 64>(X, grp, v); reg_fwd<4>(v, TW[(grp & 63) * 16]); grp_store<4, 64>(X, grp, v); }
	v_mov_b32_e32 v38, v202
	v_mov_b32_e32 v39, v203
	s_mov_b32 s3, 0
	s_mov_b64 s[4:5], -1
	v_pk_mul_f32 v[2:3], v[38:39], v[38:39] op_sel:[1,1] op_sel_hi:[0,1]
	v_pk_fma_f32 v[4:5], v[38:39], v[38:39], v[2:3] op_sel_hi:[0,1,1] neg_lo:[0,0,1] neg_hi:[0,0,1]
	v_pk_fma_f32 v[2:3], v[38:39], v[38:39], v[2:3] op_sel_hi:[0,1,1]
	v_pk_mov_b32 v[44:45], v[2:3], v[4:5] op_sel:[1,0]
	v_pk_mul_f32 v[6:7], v[38:39], v[2:3] op_sel:[1,1] op_sel_hi:[0,1]
	v_mov_b32_e32 v42, v4
	v_mov_b32_e32 v43, v3
	v_pk_mul_f32 v[2:3], v[2:3], v[44:45] op_sel:[1,0]
	v_pk_fma_f32 v[8:9], v[38:39], v[4:5], v[6:7] op_sel_hi:[1,0,1] neg_lo:[0,0,1] neg_hi:[0,0,1]
	v_pk_fma_f32 v[6:7], v[38:39], v[4:5], v[6:7] op_sel_hi:[1,0,1]
	v_pk_fma_f32 v[10:11], v[4:5], v[42:43], v[2:3] op_sel_hi:[0,1,1] neg_lo:[0,0,1] neg_hi:[0,0,1]
	v_pk_fma_f32 v[2:3], v[4:5], v[42:43], v[2:3] op_sel_hi:[0,1,1]
	v_pk_mov_b32 v[48:49], v[6:7], v[8:9] op_sel:[1,0]
	v_mov_b32_e32 v46, v8
	v_mov_b32_e32 v47, v7
	v_pk_mov_b32 v[52:53], v[2:3], v[10:11] op_sel:[1,0]
	v_pk_mul_f32 v[4:5], v[38:39], v[10:11] op_sel_hi:[1,0]
	v_pk_mul_f32 v[6:7], v[6:7], v[48:49] op_sel:[1,0]
	v_mov_b32_e32 v50, v10
	v_mov_b32_e32 v51, v3
	v_pk_mul_f32 v[12:13], v[2:3], v[52:53] op_sel:[1,0]
	v_pk_fma_f32 v[14:15], v[38:39], v[2:3], v[4:5] op_sel:[0,1,1] op_sel_hi:[1,1,0] neg_lo:[1,0,0] neg_hi:[1,0,0]
	v_pk_fma_f32 v[2:3], v[38:39], v[2:3], v[4:5] op_sel:[0,1,1] op_sel_hi:[1,1,0]
	v_pk_fma_f32 v[4:5], v[8:9], v[46:47], v[6:7] op_sel_hi:[0,1,1] neg_lo:[0,0,1] neg_hi:[0,0,1]
	v_pk_fma_f32 v[6:7], v[8:9], v[46:47], v[6:7] op_sel_hi:[0,1,1]
	v_pk_fma_f32 v[8:9], v[10:11], v[50:51], v[12:13] op_sel_hi:[0,1,1] neg_lo:[0,0,1] neg_hi:[0,0,1]
	v_pk_fma_f32 v[10:11], v[10:11], v[50:51], v[12:13] op_sel_hi:[0,1,1]
	v_pk_mov_b32 v[12:13], v[14:15], v[2:3] op_sel:[1,0]
	v_pk_mov_b32 v[58:59], v[6:7], v[4:5] op_sel:[1,0]
	v_pk_mul_f32 v[16:17], v[38:39], v[6:7] op_sel:[1,1] op_sel_hi:[0,1]
	v_mov_b32_e32 v54, v2
	v_mov_b32_e32 v55, v15
	v_mov_b32_e32 v56, v4
	v_mov_b32_e32 v57, v7
	v_mov_b32_e32 v61, v11
	v_pk_mov_b32 v[62:63], v[10:11], v[8:9] op_sel:[1,0]
	v_pk_mul_f32 v[10:11], v[38:39], v[10:11] op_sel:[1,1] op_sel_hi:[0,1]
	v_pk_mul_f32 v[2:3], v[2:3], v[12:13] op_sel_hi:[0,1]
	v_pk_mul_f32 v[6:7], v[6:7], v[58:59] op_sel:[1,0]
	v_pk_fma_f32 v[12:13], v[38:39], v[4:5], v[16:17] op_sel_hi:[1,0,1] neg_lo:[0,0,1] neg_hi:[0,0,1]
	v_pk_fma_f32 v[16:17], v[38:39], v[4:5], v[16:17] op_sel_hi:[1,0,1]
	v_mov_b32_e32 v60, v8
	v_pk_fma_f32 v[18:19], v[38:39], v[8:9], v[10:11] op_sel_hi:[1,0,1] neg_lo:[0,0,1] neg_hi:[0,0,1]
	v_pk_fma_f32 v[8:9], v[38:39], v[8:9], v[10:11] op_sel_hi:[1,0,1]
	v_pk_fma_f32 v[10:11], v[14:15], v[54:55], v[2:3] op_sel:[1,0,0] neg_lo:[0,0,1] neg_hi:[0,0,1]
	v_pk_fma_f32 v[2:3], v[14:15], v[54:55], v[2:3] op_sel:[1,0,0]
	v_pk_fma_f32 v[14:15], v[4:5], v[56:57], v[6:7] op_sel_hi:[0,1,1] neg_lo:[0,0,1] neg_hi:[0,0,1]
	v_pk_fma_f32 v[4:5], v[4:5], v[56:57], v[6:7] op_sel_hi:[0,1,1]
	v_pk_mov_b32 v[66:67], v[16:17], v[12:13] op_sel:[1,0]
	v_mov_b32_e32 v64, v12
	v_mov_b32_e32 v65, v17
	v_mov_b32_e32 v70, v2
	v_pk_mul_f32 v[2:3], v[38:39], v[2:3] op_sel:[1,0] op_sel_hi:[0,0]
	v_mov_b32_e32 v73, v5
	v_pk_mov_b32 v[74:75], v[4:5], v[14:15] op_sel:[1,0]
	v_pk_mul_f32 v[4:5], v[38:39], v[4:5] op_sel:[1,1] op_sel_hi:[0,1]
	v_pk_mul_f32 v[6:7], v[16:17], v[66:67] op_sel:[1,0]
	v_mov_b32_e32 v69, v9
	v_mov_b32_e32 v71, v11
	v_mov_b32_e32 v72, v14
	v_pk_mov_b32 v[76:77], v[8:9], v[18:19] op_sel:[1,0]
	v_pk_fma_f32 v[8:9], v[38:39], v[10:11], v[2:3] op_sel:[0,1,0] neg_lo:[0,0,1] neg_hi:[0,0,1]
	v_pk_fma_f32 v[2:3], v[38:39], v[10:11], v[2:3] op_sel:[0,1,0]
	v_pk_fma_f32 v[10:11], v[38:39], v[14:15], v[4:5] op_sel_hi:[1,0,1] neg_lo:[0,0,1] neg_hi:[0,0,1]
	v_pk_fma_f32 v[4:5], v[38:39], v[14:15], v[4:5] op_sel_hi:[1,0,1]
	v_pk_fma_f32 v[14:15], v[12:13], v[64:65], v[6:7] op_sel_hi:[0,1,1] neg_lo:[0,0,1] neg_hi:[0,0,1]
	v_pk_fma_f32 v[6:7], v[12:13], v[64:65], v[6:7] op_sel_hi:[0,1,1]
	v_mov_b32_e32 v83, v7
	v_pk_mov_b32 v[84:85], v[6:7], v[14:15] op_sel:[1,0]
	v_pk_mul_f32 v[6:7], v[38:39], v[6:7] op_sel:[1,1] op_sel_hi:[0,1]
	v_mov_b32_e32 v79, v3
	v_mov_b32_e32 v81, v5
	v_pk_mov_b32 v[86:87], v[4:5], v[10:11] op_sel:[1,0]
	v_pk_mov_b32 v[88:89], v[2:3], v[8:9] op_sel:[1,0]
	v_pk_fma_f32 v[2:3], v[38:39], v[14:15], v[6:7] op_sel_hi:[1,0,1] neg_lo:[0,0,1] neg_hi:[0,0,1]
	v_pk_fma_f32 v[4:5], v[38:39], v[14:15], v[6:7] op_sel_hi:[1,0,1]
	v_pk_mov_b32 v[40:41], v[38:39], v[38:39] op_sel:[1,0]
	v_mov_b32_e32 v68, v18
	v_mov_b32_e32 v78, v8
	v_mov_b32_e32 v80, v10
	v_mov_b32_e32 v82, v14
	v_mov_b32_e32 v90, v2
	v_mov_b32_e32 v91, v5
	v_pk_mov_b32 v[92:93], v[4:5], v[2:3] op_sel:[1,0]
; #define FFT_HD __device__ __attribute__((always_inline))
; template <int R> FFT_HD inline void reg_fwd(cf2 (&v)[1 << R], cf2 th) { dft_fwd_reg<R>(v); tw_apply<R, 1, false>(v, th, th); }
; template <int R> FFT_HD inline void dft_fwd_reg(cf2 (&v)[1 << R]) {
;     constexpr int n = 1 << R;
; #pragma unroll
;     for (int s = 0; s < R; ++s) {
;         const int half = n >> (s + 1);
; #pragma unroll
;         for (int m = 0; m < n; ++m) {
;             if ((m & half) == 0) {
;                 const int ml = m & (half - 1), tk = ml * (16 / half);
;                 const cf2 a = v[m], b = v[m + half];
;                 v[m].x = a.x + b.x; v[m].y = a.y + b.y;
;                 const cf2 d = {a.x - b.x, a.y - b.y};
;                 if (tk == 0) v[m + half] = d;
;                 else if (tk == 8) { v[m + half].x = d.y; v[m + half].y = -d.x; }
;                 else { const cf2 w = {fc32(tk), -fs32(tk)}; v[m + half] = cmulf(d, w); }
;             }
;         }
;     }
; }
; __device__ __forceinline__ void s_mid2(ldsc X, const cf2* TW, int tid) {
; #pragma unroll 1
;     for (int q = 0; q < 2; ++q) { const int grp = tid + 512 * q; cf2 v[16]; grp_load<4, 64>(X, grp, v); reg_fwd<4>(v, TW[(grp & 63) * 16]); grp_store<4, 64>(X, grp, v); }
.LBB0_663:
	v_cndmask_b32_e64 v2, 0, 1, s[4:5]
	v_cmp_ne_u32_e32 vcc, 1, v2
	v_add_u32_e32 v2, s3, v172
	v_ashrrev_i32_e32 v3, 31, v2
	v_lshrrev_b32_e32 v3, 26, v3
	v_add_lshl_u32 v2, v2, v3, 4
	v_and_b32_e32 v2, 0xfffffc00, v2
	v_or_b32_e32 v3, v2, v173
	v_bitop3_b32 v2, v2, s24, v173 bitop3:0xc8
	v_lshlrev_b32_e32 v3, 3, v3
	v_add3_u32 v129, 0, v2, v3
	v_add_u32_e32 v127, 0x800, v129
	v_add_u32_e32 v126, 0x1400, v129
	ds_read2_b64 v[18:21], v129 offset1:72
	ds_read2_b64 v[2:5], v129 offset0:144 offset1:216
	ds_read2_b64 v[14:17], v127 offset0:32 offset1:104
	ds_read2_b64 v[10:13], v127 offset0:176 offset1:248
	ds_read2_b64 v[6:9], v126 offset0:80 offset1:152
	v_add_u32_e32 v128, 0x1000, v129
	v_add_u32_e32 v125, 0x1800, v129
	ds_read2_b64 v[22:25], v128 offset0:64 offset1:136
	ds_read2_b64 v[26:29], v125 offset0:96 offset1:168
	s_waitcnt lgkmcnt(2)
	v_pk_add_f32 v[94:95], v[4:5], v[8:9] neg_lo:[0,1] neg_hi:[0,1]
	v_add_u32_e32 v124, 0x1c00, v129
	v_mul_f32_e32 v96, 0x3f6c835e, v95
	ds_read2_b64 v[30:33], v124 offset0:112 offset1:184
	v_pk_fma_f32 v[98:99], v[94:95], s[60:61], v[96:97] op_sel_hi:[1,1,0]
	v_mul_f32_e32 v101, 0x3ec3ef15, v95
	v_mul_f32_e32 v130, 0x3f6c835e, v94
	v_pk_mov_b32 v[94:95], v[18:19], v[14:15] op_sel:[1,0]
	s_waitcnt lgkmcnt(1)
	v_pk_mov_b32 v[96:97], v[22:23], v[26:27] op_sel:[1,0]
	v_mov_b32_e32 v102, v22
	v_pk_add_f32 v[94:95], v[94:95], v[96:97] neg_lo:[0,1] neg_hi:[0,1]
	v_mov_b32_e32 v96, v18
	v_mov_b32_e32 v97, v15
	v_mov_b32_e32 v103, v27
	v_pk_add_f32 v[96:97], v[96:97], v[102:103] neg_lo:[0,1] neg_hi:[0,1]
	v_mov_b32_e32 v102, v21
	v_mov_b32_e32 v103, v17
	v_mov_b32_e32 v104, v25
	v_mov_b32_e32 v105, v29
	v_pk_add_f32 v[106:107], v[102:103], v[104:105] neg_lo:[0,1] neg_hi:[0,1]
	v_mov_b32_e32 v102, v20
	v_mov_b32_e32 v103, v16
	v_mov_b32_e32 v104, v24
	v_mov_b32_e32 v105, v28
	v_pk_add_f32 v[108:109], v[102:103], v[104:105] neg_lo:[0,1] neg_hi:[0,1]
	s_mov_b32 s4, s61
	s_mov_b32 s5, s60
	v_pk_mul_f32 v[102:103], v[108:109], s[4:5]
	s_waitcnt lgkmcnt(0)
	v_pk_add_f32 v[114:115], v[10:11], v[30:31] neg_lo:[0,1] neg_hi:[0,1]
	v_pk_add_f32 v[120:121], v[18:19], v[22:23]
	v_pk_add_f32 v[18:19], v[20:21], v[24:25]
	v_pk_add_f32 v[132:133], v[2:3], v[6:7]
	v_pk_add_f32 v[4:5], v[4:5], v[8:9]
	v_pk_add_f32 v[26:27], v[14:15], v[26:27]
	v_pk_add_f32 v[8:9], v[16:17], v[28:29]
	v_pk_add_f32 v[28:29], v[10:11], v[30:31]
	v_pk_add_f32 v[10:11], v[12:13], v[32:33]
	v_mul_f32_e32 v116, 0x3f6c835e, v106
	v_mul_f32_e32 v118, 0x3ec3ef15, v108
	v_pk_fma_f32 v[104:105], v[106:107], s[60:61], v[102:103]
	v_pk_fma_f32 v[102:103], v[106:107], s[60:61], v[102:103] neg_lo:[0,0,1] neg_hi:[0,0,1]
	v_mov_b32_e32 v108, v107
	v_pk_add_f32 v[106:107], v[12:13], v[32:33] neg_lo:[0,1] neg_hi:[0,1]
	v_pk_add_f32 v[12:13], v[120:121], v[26:27]
	v_pk_add_f32 v[14:15], v[18:19], v[8:9]
	v_pk_add_f32 v[24:25], v[18:19], v[8:9] neg_lo:[0,1] neg_hi:[0,1]
	v_pk_add_f32 v[16:17], v[132:133], v[28:29]
	v_pk_add_f32 v[18:19], v[4:5], v[10:11]
	v_pk_add_f32 v[22:23], v[4:5], v[10:11] neg_lo:[0,1] neg_hi:[0,1]
	v_pk_add_f32 v[8:9], v[12:13], v[16:17]
	v_pk_add_f32 v[10:11], v[14:15], v[18:19]
	v_mul_f32_e32 v21, 0x3f3504f3, v24
	v_pk_add_f32 v[4:5], v[8:9], v[10:11]
	v_pk_add_f32 v[10:11], v[8:9], v[10:11] neg_lo:[0,1] neg_hi:[0,1]
	v_pk_add_f32 v[12:13], v[12:13], v[16:17] neg_lo:[0,1] neg_hi:[0,1]
	v_mul_f32_e32 v8, v11, v61
	v_mul_f32_e32 v20, v10, v62
	v_pk_add_f32 v[14:15], v[14:15], v[18:19] neg_lo:[0,1] neg_hi:[0,1]
	v_pk_fma_f32 v[8:9], v[10:11], v[60:61], v[8:9] op_sel_hi:[1,1,0] neg_lo:[0,0,1] neg_hi:[0,0,1]
	v_pk_fma_f32 v[10:11], v[10:11], v[62:63], v[20:21] op_sel_hi:[1,1,0]
	v_pk_add_f32 v[18:19], v[12:13], v[14:15] op_sel:[0,1] op_sel_hi:[1,0] neg_lo:[0,1] neg_hi:[0,1]
	v_pk_add_f32 v[16:17], v[12:13], v[14:15] op_sel:[0,1] op_sel_hi:[1,0]
	v_mov_b32_e32 v15, v19
	v_mov_b32_e32 v14, v16
	v_mul_f32_e32 v10, v19, v51
	v_pk_fma_f32 v[12:13], v[14:15], v[50:51], v[10:11] op_sel_hi:[1,1,0] neg_lo:[0,0,1] neg_hi:[0,0,1]
	v_mul_f32_e32 v10, v16, v52
	v_mul_f32_e32 v32, 0x3f3504f3, v25
	v_mul_f32_e32 v24, 0x3f3504f3, v22
	v_mov_b32_e32 v30, v18
	v_mov_b32_e32 v31, v17
	v_pk_fma_f32 v[14:15], v[14:15], v[52:53], v[10:11] op_sel_hi:[1,1,0]
	v_mul_f32_e32 v10, v17, v73
	v_pk_add_f32 v[26:27], v[120:121], v[26:27] neg_lo:[0,1] neg_hi:[0,1]
	v_pk_add_f32 v[28:29], v[132:133], v[28:29] neg_lo:[0,1] neg_hi:[0,1]
	s_mov_b32 s83, s80
	v_pk_fma_f32 v[16:17], v[30:31], v[72:73], v[10:11] op_sel_hi:[1,1,0] neg_lo:[0,0,1] neg_hi:[0,0,1]
	v_mul_f32_e32 v10, v18, v74
	v_sub_f32_e32 v20, v32, v21
	v_fmac_f32_e32 v21, 0x3f3504f3, v25
	v_pk_fma_f32 v[22:23], v[22:23], s[82:83], v[24:25] op_sel:[1,0,0] op_sel_hi:[1,1,0] neg_lo:[0,0,1] neg_hi:[0,0,1]
	v_pk_add_f32 v[24:25], v[26:27], v[28:29] op_sel:[0,1] op_sel_hi:[1,0] neg_lo:[0,1] neg_hi:[0,1]
	v_pk_add_f32 v[26:27], v[26:27], v[28:29] op_sel:[0,1] op_sel_hi:[1,0]
	v_pk_fma_f32 v[18:19], v[30:31], v[74:75], v[10:11] op_sel_hi:[1,1,0]
	v_mov_b32_e32 v28, v24
	v_pk_add_f32 v[30:31], v[20:21], v[22:23] neg_lo:[0,1] neg_hi:[0,1]
	v_pk_mov_b32 v[24:25], v[24:25], v[26:27] op_sel:[1,0]
	v_pk_add_f32 v[20:21], v[20:21], v[22:23]
	v_mov_b32_e32 v29, v27
	v_pk_add_f32 v[22:23], v[24:25], v[20:21]
	v_pk_add_f32 v[26:27], v[24:25], v[20:21] neg_lo:[0,1] neg_hi:[0,1]
	v_mul_f32_e32 v10, v45, v23
	v_pk_fma_f32 v[20:21], v[44:45], v[22:23], v[10:11] op_sel_hi:[1,1,0] neg_lo:[1,0,0] neg_hi:[1,0,0]
	v_mul_f32_e32 v10, v42, v22
	s_mov_b32 s79, s61
	v_mul_f32_e32 v100, 0x3f6c835e, v109
	v_pk_fma_f32 v[22:23], v[42:43], v[22:23], v[10:11] op_sel_hi:[1,1,0]
	v_mul_f32_e32 v10, v27, v71
	v_pk_mov_b32 v[2:3], v[2:3], v[2:3] op_sel:[1,0]
; #define FFT_HD __device__ __attribute__((always_inline))
; template <int R> FFT_HD inline void dft_fwd_reg(cf2 (&v)[1 << R]) {
;     constexpr int n = 1 << R;
; #pragma unroll
;     for (int s = 0; s < R; ++s) {
;         const int half = n >> (s + 1);
; #pragma unroll
;         for (int m = 0; m < n; ++m) {
;             if ((m & half) == 0) {
;                 const int ml = m & (half - 1), tk = ml * (16 / half);
;                 const cf2 a = v[m], b = v[m + half];
;                 v[m].x = a.x + b.x; v[m].y = a.y + b.y;
;                 const cf2 d = {a.x - b.x, a.y - b.y};
;                 if (tk == 0) v[m + half] = d;
;                 else if (tk == 8) { v[m + half].x = d.y; v[m + half].y = -d.x; }
;                 else { const cf2 w = {fc32(tk), -fs32(tk)}; v[m + half] = cmulf(d, w); }
;             }
;         }
;     }
; }
	v_pk_mov_b32 v[6:7], v[6:7], v[6:7] op_sel:[1,0]
	v_pk_fma_f32 v[122:123], v[108:109], s[78:79], v[100:101] op_sel_hi:[1,1,0] neg_lo:[0,0,1] neg_hi:[0,0,1]
	v_mul_f32_e32 v100, 0xbf6c835e, v107
	v_pk_add_f32 v[120:121], v[28:29], v[30:31] neg_lo:[0,1] neg_hi:[0,1]
	v_pk_add_f32 v[32:33], v[28:29], v[30:31]
	v_pk_fma_f32 v[24:25], v[26:27], v[70:71], v[10:11] op_sel_hi:[1,1,0] neg_lo:[1,0,0] neg_hi:[1,0,0]
	v_mul_f32_e32 v10, v27, v70
	v_mov_b32_e32 v117, v3
	v_mov_b32_e32 v119, v7
	v_pk_fma_f32 v[108:109], v[106:107], s[78:79], v[100:101] op_sel_hi:[1,1,0]
	v_pk_fma_f32 v[26:27], v[26:27], v[70:71], v[10:11] op_sel:[1,0,0] op_sel_hi:[0,1,0]
	v_mov_b32_e32 v30, v32
	v_mov_b32_e32 v31, v121
	v_mul_f32_e32 v10, v121, v57
	v_pk_add_f32 v[116:117], v[116:117], v[118:119] neg_lo:[0,1] neg_hi:[0,1]
	v_mov_b32_e32 v3, v101
	v_mov_b32_e32 v7, v130
	v_pk_fma_f32 v[28:29], v[30:31], v[56:57], v[10:11] op_sel_hi:[1,1,0] neg_lo:[0,0,1] neg_hi:[0,0,1]
	v_mul_f32_e32 v10, v32, v58
	v_pk_add_f32 v[6:7], v[2:3], v[6:7] neg_lo:[0,1] neg_hi:[0,1]
	v_pk_add_f32 v[2:3], v[116:117], v[122:123]
	v_mov_b32_e32 v186, v122
	v_pk_add_f32 v[118:119], v[116:117], v[122:123] neg_lo:[0,1] neg_hi:[0,1]
	v_mov_b32_e32 v122, v187
	v_mov_b32_e32 v123, v108
	v_mov_b32_e32 v132, v120
	v_mov_b32_e32 v133, v33
	v_pk_fma_f32 v[30:31], v[30:31], v[58:59], v[10:11] op_sel_hi:[1,1,0]
	v_mul_f32_e32 v10, v33, v83
	v_pk_mul_f32 v[116:117], v[116:117], v[186:187]
	v_pk_mul_f32 v[130:131], v[6:7], v[122:123]
	v_pk_add_f32 v[122:123], v[6:7], v[122:123] neg_lo:[0,1] neg_hi:[0,1]
	v_pk_mul_f32 v[110:111], v[114:115], s[80:81] op_sel_hi:[1,0]
	v_pk_mul_f32 v[112:113], v[106:107], s[4:5]
	v_pk_fma_f32 v[32:33], v[132:133], v[82:83], v[10:11] op_sel_hi:[1,1,0] neg_lo:[0,0,1] neg_hi:[0,0,1]
	v_mul_f32_e32 v10, v120, v84
	v_mov_b32_e32 v119, v117
	v_mov_b32_e32 v131, v123
	s_mov_b32 s3, s80
	v_mov_b32_e32 v116, v117
	v_mov_b32_e32 v117, v187
	v_pk_fma_f32 v[120:121], v[132:133], v[84:85], v[10:11] op_sel_hi:[1,1,0]
	v_mov_b32_e32 v133, v130
	v_pk_add_f32 v[116:117], v[130:131], v[116:117] neg_lo:[0,1] neg_hi:[0,1]
	v_pk_mul_f32 v[130:131], v[122:123], s[2:3]
	v_mul_f32_e32 v105, 0xbf3504f3, v123
	v_mov_b32_e32 v122, v111
	v_mov_b32_e32 v123, v113
	v_mov_b32_e32 v111, v112
	v_mov_b32_e32 v186, v110
	v_pk_add_f32 v[110:111], v[122:123], v[110:111] neg_lo:[0,1] neg_hi:[0,1]
	v_pk_mov_b32 v[114:115], v[114:115], v[98:99] op_sel:[1,0]
	v_mov_b32_e32 v112, v96
	v_mov_b32_e32 v113, v104
	v_mov_b32_e32 v102, v97
	v_mov_b32_e32 v189, v111
	v_sub_f32_e32 v100, v104, v103
	v_pk_add_f32 v[102:103], v[112:113], v[102:103]
	v_pk_mul_f32 v[112:113], v[114:115], v[188:189]
	v_pk_add_f32 v[114:115], v[114:115], v[110:111] neg_lo:[0,1] neg_hi:[0,1]
	v_mov_b32_e32 v132, v187
	v_mov_b32_e32 v113, v115
	v_pk_mul_f32 v[134:135], v[118:119], v[132:133]
	v_pk_add_f32 v[118:119], v[118:119], v[132:133]
	v_pk_add_f32 v[114:115], v[112:113], v[186:187] neg_lo:[0,1] neg_hi:[0,1]
	v_pk_add_f32 v[106:107], v[94:95], v[94:95] op_sel:[0,1] op_sel_hi:[1,0] neg_lo:[0,1] neg_hi:[0,1]
	v_pk_mov_b32 v[98:99], v[118:119], v[98:99] op_sel:[1,0]
	v_pk_mul_f32 v[112:113], v[112:113], v[186:187]
	v_pk_mov_b32 v[6:7], v[6:7], v[116:117] op_sel:[1,0]
	v_mov_b32_e32 v109, v114
	v_mov_b32_e32 v130, v116
	v_pk_add_f32 v[98:99], v[98:99], v[110:111]
	v_mov_b32_e32 v115, v113
	v_pk_add_f32 v[6:7], v[6:7], v[108:109]
	v_mov_b32_e32 v116, v2
	v_mov_b32_e32 v117, v106
	v_pk_add_f32 v[108:109], v[130:131], v[114:115] neg_lo:[0,1] neg_hi:[0,1]
	v_pk_add_f32 v[116:117], v[116:117], v[6:7] neg_lo:[0,1] neg_hi:[0,1]
	v_mov_b32_e32 v130, v102
	v_mov_b32_e32 v131, v106
	v_mov_b32_e32 v106, v98
	v_mov_b32_e32 v107, v7
	v_pk_mov_b32 v[2:3], v[102:103], v[2:3] op_sel:[1,0]
	v_pk_mov_b32 v[6:7], v[98:99], v[6:7] op_sel:[1,0]
	v_pk_add_f32 v[106:107], v[130:131], v[106:107]
	v_pk_add_f32 v[2:3], v[2:3], v[6:7]
	v_mul_f32_e32 v100, 0x3f3504f3, v100
	v_pk_add_f32 v[6:7], v[106:107], v[2:3] neg_lo:[0,1] neg_hi:[0,1]
	v_pk_add_f32 v[2:3], v[106:107], v[2:3]
	v_mov_b32_e32 v135, v119
	v_mov_b32_e32 v101, v110
	v_mul_f32_e32 v10, v39, v3
	v_pk_add_f32 v[110:111], v[134:135], v[100:101] neg_lo:[0,1] neg_hi:[0,1]
	v_pk_add_f32 v[114:115], v[102:103], v[98:99] neg_lo:[0,1] neg_hi:[0,1]
	v_pk_fma_f32 v[98:99], v[38:39], v[2:3], v[10:11] op_sel_hi:[1,1,0] neg_lo:[0,0,1] neg_hi:[0,0,1]
	v_mul_f32_e32 v10, v40, v2
	v_mov_b32_e32 v101, v94
	v_mov_b32_e32 v135, v95
	v_mov_b32_e32 v104, v96
	v_mov_b32_e32 v112, v97
	v_pk_fma_f32 v[2:3], v[40:41], v[2:3], v[10:11] op_sel_hi:[1,1,0]
	v_pk_add_f32 v[94:95], v[100:101], v[134:135]
	v_pk_add_f32 v[96:97], v[104:105], v[112:113] neg_lo:[0,1] neg_hi:[0,1]
	v_mov_b32_e32 v104, v109
	v_mov_b32_e32 v105, v111
	v_pk_add_f32 v[118:119], v[114:115], v[116:117] neg_lo:[0,1] neg_hi:[0,1]
	v_pk_add_f32 v[122:123], v[114:115], v[116:117]
	v_mul_f32_e32 v2, v7, v69
	v_pk_add_f32 v[106:107], v[116:117], v[114:115] neg_lo:[0,1] neg_hi:[0,1]
	v_pk_add_f32 v[112:113], v[94:95], v[104:105]
	v_pk_add_f32 v[104:105], v[94:95], v[104:105] neg_lo:[0,1] neg_hi:[0,1]
	v_mov_b32_e32 v116, v108
	v_mov_b32_e32 v117, v110
	v_pk_fma_f32 v[102:103], v[6:7], v[68:69], v[2:3] op_sel_hi:[1,1,0] neg_lo:[0,0,1] neg_hi:[0,0,1]
	v_mul_f32_e32 v2, v6, v76
	v_mov_b32_e32 v101, v94
; #define FFT_HD __device__ __attribute__((always_inline))
; template <int R> FFT_HD inline void reg_fwd(cf2 (&v)[1 << R], cf2 th) { dft_fwd_reg<R>(v); tw_apply<R, 1, false>(v, th, th); }
; template <int R, int F, bool CONJ> FFT_HD inline void tw_apply(cf2 (&v)[1 << R], cf2 pf, cf2 th) {
;     constexpr int j = fbrev(F, R);
;     v[j] = CONJ ? cmulcf(v[j], pf) : cmulf(v[j], pf);
;     if constexpr (2 * F < (1 << R)) {
;         const cf2 p2 = cmulf(pf, pf);
;         tw_apply<R, 2 * F, CONJ>(v, p2, th);
;         const cf2 p3 = cmulf(p2, th);
;         tw_apply<R, 2 * F + 1, CONJ>(v, p3, th);
;     }
; }
; __device__ __forceinline__ void s_mid2(ldsc X, const cf2* TW, int tid) {
;     ...
;     for (int q = 0; q < 2; ++q) { const int grp = tid + 512 * q; cf2 v[16]; grp_load<4, 64>(X, grp, v); reg_fwd<4>(v, TW[(grp & 63) * 16]); grp_store<4, 64>(X, grp, v); }
;     __syncthreads();
; #pragma unroll 1
;     for (int q = 0; q < 4; ++q) { const int grp = tid + 512 * q; cf2 v[8]; grp_load<3, 8>(X, grp, v); reg_fwd<3>(v, TW[(grp & 7) * 256]); grp_store<3, 8>(X, grp, v); }
	v_mov_b32_e32 v113, v105
	v_pk_add_f32 v[116:117], v[96:97], v[116:117]
	v_mov_b32_e32 v94, v97
	v_pk_fma_f32 v[6:7], v[6:7], v[76:77], v[2:3] op_sel_hi:[1,1,0]
	v_pk_mov_b32 v[114:115], v[106:107], v[122:123] op_sel:[1,0]
	v_mul_f32_e32 v2, v122, v55
	v_mov_b32_e32 v100, v96
	v_pk_add_f32 v[96:97], v[110:111], v[94:95] neg_lo:[0,1] neg_hi:[0,1]
	v_pk_add_f32 v[94:95], v[110:111], v[94:95]
	v_pk_add_f32 v[110:111], v[116:117], v[112:113]
	v_mov_b32_e32 v104, v116
	v_mov_b32_e32 v113, v117
	v_pk_fma_f32 v[114:115], v[114:115], v[54:55], v[2:3] op_sel_hi:[1,1,0] neg_lo:[1,0,0] neg_hi:[1,0,0]
	v_mov_b32_e32 v106, v122
	v_mul_f32_e32 v2, v122, v54
	v_pk_add_f32 v[104:105], v[104:105], v[112:113] neg_lo:[0,1] neg_hi:[0,1]
	v_pk_fma_f32 v[106:107], v[106:107], v[54:55], v[2:3] op_sel_hi:[1,1,0]
	v_mul_f32_e32 v2, v105, v79
	v_pk_fma_f32 v[112:113], v[104:105], v[78:79], v[2:3] op_sel_hi:[1,1,0] neg_lo:[0,0,1] neg_hi:[0,0,1]
	v_mul_f32_e32 v2, v104, v88
	v_pk_fma_f32 v[104:105], v[104:105], v[88:89], v[2:3] op_sel_hi:[1,1,0]
	v_mul_f32_e32 v2, v47, v111
	v_pk_fma_f32 v[116:117], v[46:47], v[110:111], v[2:3] op_sel_hi:[1,1,0] neg_lo:[0,0,1] neg_hi:[0,0,1]
	v_mul_f32_e32 v2, v48, v110
	v_mov_b32_e32 v119, v123
	v_pk_add_f32 v[100:101], v[100:101], v[108:109] neg_lo:[0,1] neg_hi:[0,1]
	v_mov_b32_e32 v108, v96
	v_mov_b32_e32 v109, v95
	v_pk_fma_f32 v[110:111], v[48:49], v[110:111], v[2:3] op_sel_hi:[1,1,0]
	v_mul_f32_e32 v2, v123, v81
	v_pk_add_f32 v[108:109], v[100:101], v[108:109]
	v_pk_fma_f32 v[122:123], v[118:119], v[80:81], v[2:3] op_sel_hi:[1,1,0] neg_lo:[0,0,1] neg_hi:[0,0,1]
	v_mul_f32_e32 v2, v118, v86
	v_pk_add_f32 v[94:95], v[94:95], v[100:101] neg_lo:[0,1] neg_hi:[0,1]
	v_pk_fma_f32 v[118:119], v[118:119], v[86:87], v[2:3] op_sel_hi:[1,1,0]
	v_mov_b32_e32 v94, v108
	v_mul_f32_e32 v2, v95, v65
	v_pk_add_f32 v[96:97], v[100:101], v[96:97] neg_lo:[0,1] neg_hi:[0,1]
	v_pk_fma_f32 v[100:101], v[94:95], v[64:65], v[2:3] op_sel_hi:[1,1,0] neg_lo:[0,0,1] neg_hi:[0,0,1]
	v_mul_f32_e32 v2, v108, v66
	v_mov_b32_e32 v97, v109
	v_pk_fma_f32 v[94:95], v[94:95], v[66:67], v[2:3] op_sel_hi:[1,1,0]
	v_mul_f32_e32 v2, v109, v91
	v_pk_fma_f32 v[108:109], v[96:97], v[90:91], v[2:3] op_sel_hi:[1,1,0] neg_lo:[0,0,1] neg_hi:[0,0,1]
	v_mul_f32_e32 v2, v96, v92
	v_pk_fma_f32 v[96:97], v[96:97], v[92:93], v[2:3] op_sel_hi:[1,1,0]
	v_mov_b32_e32 v9, v11
	v_mov_b32_e32 v13, v15
	v_mov_b32_e32 v17, v19
	v_mov_b32_e32 v21, v23
	v_mov_b32_e32 v25, v27
	v_mov_b32_e32 v29, v31
	v_mov_b32_e32 v33, v121
	v_mov_b32_e32 v99, v3
	v_mov_b32_e32 v103, v7
	v_mov_b32_e32 v115, v107
	v_mov_b32_e32 v123, v119
	v_mov_b32_e32 v117, v111
	v_mov_b32_e32 v113, v105
	v_mov_b32_e32 v101, v95
	v_mov_b32_e32 v109, v97
	s_movk_i32 s3, 0x200
	s_mov_b64 s[4:5], 0
	s_and_b64 vcc, exec, vcc
	ds_write2_b64 v129, v[4:5], v[8:9] offset1:72
	ds_write2_b64 v129, v[12:13], v[16:17] offset0:144 offset1:216
	ds_write2_b64 v127, v[20:21], v[24:25] offset0:32 offset1:104
	ds_write2_b64 v127, v[28:29], v[32:33] offset0:176 offset1:248
	ds_write2_b64 v128, v[98:99], v[102:103] offset0:64 offset1:136
	ds_write2_b64 v126, v[114:115], v[122:123] offset0:80 offset1:152
	ds_write2_b64 v125, v[116:117], v[112:113] offset0:96 offset1:168
	ds_write2_b64 v124, v[100:101], v[108:109] offset0:112 offset1:184
	s_cbranch_vccz .LBB0_663
	s_waitcnt lgkmcnt(0)
	s_barrier
	v_mov_b32_e32 v2, v204
	v_mov_b32_e32 v3, v205
	s_mov_b32 s3, 0
	v_pk_mul_f32 v[6:7], v[2:3], v[2:3] op_sel:[1,1] op_sel_hi:[0,1]
	v_pk_fma_f32 v[14:15], v[2:3], v[2:3], v[6:7] op_sel_hi:[0,1,1] neg_lo:[0,0,1] neg_hi:[0,0,1]
	v_pk_fma_f32 v[16:17], v[2:3], v[2:3], v[6:7] op_sel_hi:[0,1,1]
	v_mov_b32_e32 v6, v14
	v_mov_b32_e32 v7, v17
	v_mul_f32_e32 v8, v17, v17
	v_pk_mul_f32 v[10:11], v[6:7], v[16:17] op_sel:[0,1] op_sel_hi:[1,0]
	v_pk_mov_b32 v[12:13], v[16:17], v[14:15] op_sel:[1,0]
	v_pk_mul_f32 v[16:17], v[2:3], v[16:17] op_sel:[1,1] op_sel_hi:[0,1]
	v_pk_fma_f32 v[18:19], v[2:3], v[14:15], v[16:17] op_sel_hi:[1,0,1] neg_lo:[0,0,1] neg_hi:[0,0,1]
	v_pk_fma_f32 v[20:21], v[2:3], v[14:15], v[16:17] op_sel_hi:[1,0,1]
	v_mov_b32_e32 v14, v18
	v_pk_mov_b32 v[16:17], v[20:21], v[18:19] op_sel:[1,0]
	v_mov_b32_e32 v15, v21
	v_pk_mul_f32 v[20:21], v[20:21], v[16:17] op_sel:[1,0]
	v_pk_fma_f32 v[8:9], v[6:7], v[6:7], v[8:9] op_sel_hi:[1,1,0] neg_lo:[0,0,1] neg_hi:[0,0,1]
	v_pk_fma_f32 v[22:23], v[18:19], v[14:15], v[20:21] op_sel_hi:[0,1,1] neg_lo:[0,0,1] neg_hi:[0,0,1]
	v_pk_fma_f32 v[24:25], v[18:19], v[14:15], v[20:21] op_sel_hi:[0,1,1]
	v_mov_b32_e32 v19, v25
	v_pk_mov_b32 v[20:21], v[24:25], v[22:23] op_sel:[1,0]
	v_pk_mul_f32 v[24:25], v[2:3], v[24:25] op_sel:[1,1] op_sel_hi:[0,1]
	v_pk_add_f32 v[10:11], v[10:11], v[10:11]
	v_pk_fma_f32 v[26:27], v[2:3], v[22:23], v[24:25] op_sel_hi:[1,0,1] neg_lo:[0,0,1] neg_hi:[0,0,1]
	v_pk_fma_f32 v[24:25], v[2:3], v[22:23], v[24:25] op_sel_hi:[1,0,1]
	v_mul_f32_e32 v9, v2, v8
	v_mul_f32_e32 v28, v3, v8
	v_mov_b32_e32 v18, v22
	v_mov_b32_e32 v22, v26
	v_mov_b32_e32 v23, v25
	v_pk_mov_b32 v[24:25], v[24:25], v[26:27] op_sel:[1,0]
	v_fma_f32 v26, -v3, v10, v9
	v_fmac_f32_e32 v28, v2, v10
	v_pk_mov_b32 v[4:5], v[2:3], v[2:3] op_sel:[1,0]
	v_mov_b32_e32 v27, v26
	v_mov_b32_e32 v9, v8
	v_mov_b32_e32 v11, v10
	v_mov_b32_e32 v29, v28

; #define FFT_HD __device__ __attribute__((always_inline))
; template <int R> FFT_HD inline void reg_inv(cf2 (&v)[1 << R], cf2 th) { tw_apply<R, 1, true>(v, th, th); dft_inv_reg<R>(v); }
; template <int R> FFT_HD inline void dft_inv_reg(cf2 (&v)[1 << R]) {
;     constexpr int n = 1 << R;
; #pragma unroll
;     for (int s = R - 1; s >= 0; --s) {
;         const int half = n >> (s + 1);
; #pragma unroll
;         for (int m = 0; m < n; ++m) {
;             if ((m & half) == 0) {
;                 const int ml = m & (half - 1), tk = ml * (16 / half);
;                 const cf2 a = v[m], bb = v[m + half]; cf2 b;
;                 if (tk == 0) b = bb;
;                 else if (tk == 8) { b.x = -bb.y; b.y = bb.x; }
;                 else { const cf2 w = {fc32(tk), -fs32(tk)}; b = cmulcf(bb, w); }
;                 v[m].x = a.x + b.x; v[m].y = a.y + b.y; v[m + half].x = a.x - b.x; v[m + half].y = a.y - b.y;
;             }
;         }
;     }
; }
; template <int R, int F, bool CONJ> FFT_HD inline void tw_apply(cf2 (&v)[1 << R], cf2 pf, cf2 th) {
;     constexpr int j = fbrev(F, R);
;     v[j] = CONJ ? cmulcf(v[j], pf) : cmulf(v[j], pf);
;     if constexpr (2 * F < (1 << R)) {
;         const cf2 p2 = cmulf(pf, pf);
;         tw_apply<R, 2 * F, CONJ>(v, p2, th);
;         const cf2 p3 = cmulf(p2, th);
;         tw_apply<R, 2 * F + 1, CONJ>(v, p3, th);
;     }
; }
; __device__ __forceinline__ void s_mid2(ldsc X, const cf2* TW, int tid) {
;     ...
; #pragma unroll 1
;     for (int q = 0; q < 4; ++q) { const int grp = tid + 512 * q; cf2 v[8]; grp_load<3, 8>(X, grp, v); reg_inv<3>(v, TW[(grp & 7) * 256]); grp_store<3, 8>(X, grp, v); }
.LBB0_681:
	v_add_u32_e32 v30, s3, v172
	v_ashrrev_i32_e32 v31, 31, v30
	v_lshrrev_b32_e32 v31, 29, v31
	v_add_u32_e32 v30, v30, v31
	v_ashrrev_i32_e32 v30, 3, v30
	v_lshl_add_u32 v31, v30, 6, 0
	v_lshlrev_b32_e32 v30, 9, v30
	v_add3_u32 v66, v31, v30, v174
	ds_read2_b64 v[36:39], v66 offset1:9
	ds_read2_b64 v[30:33], v66 offset0:18 offset1:27
	ds_read2_b64 v[40:43], v66 offset0:36 offset1:45
	ds_read2_b64 v[44:47], v66 offset0:54 offset1:63
	s_mov_b32 s83, s80
	s_addk_i32 s3, 0x200
	s_waitcnt lgkmcnt(2)
	v_pk_mul_f32 v[48:49], v[30:31], v[8:9]
	s_cmpk_eq_i32 s3, 0x800
	v_pk_fma_f32 v[50:51], v[30:31], v[6:7], v[48:49] op_sel:[1,0,0] op_sel_hi:[0,1,1] neg_lo:[0,0,1] neg_hi:[0,0,1]
	v_pk_fma_f32 v[30:31], v[30:31], v[6:7], v[48:49] op_sel:[1,0,0] op_sel_hi:[0,1,1]
	v_mov_b32_e32 v51, v31
	v_pk_mul_f32 v[30:31], v[38:39], v[12:13] op_sel:[1,0] op_sel_hi:[0,1]
	v_pk_fma_f32 v[48:49], v[38:39], v[10:11], v[30:31]
	v_pk_fma_f32 v[30:31], v[38:39], v[10:11], v[30:31] neg_lo:[0,0,1] neg_hi:[0,0,1]
	s_nop 0
	v_mov_b32_e32 v49, v31
	v_pk_mul_f32 v[30:31], v[32:33], v[22:23]
	s_nop 0
	v_pk_fma_f32 v[38:39], v[32:33], v[20:21], v[30:31] op_sel:[1,0,0] op_sel_hi:[0,1,1] neg_lo:[0,0,1] neg_hi:[0,0,1]
	v_pk_fma_f32 v[30:31], v[32:33], v[20:21], v[30:31] op_sel:[1,0,0] op_sel_hi:[0,1,1]
	v_mov_b32_e32 v39, v31
	v_pk_add_f32 v[30:31], v[36:37], v[48:49] neg_lo:[0,1] neg_hi:[0,1]
	v_pk_add_f32 v[32:33], v[50:51], v[38:39] neg_lo:[0,1] neg_hi:[0,1]
	v_pk_add_f32 v[36:37], v[36:37], v[48:49]
	v_pk_add_f32 v[52:53], v[30:31], v[32:33]
	v_pk_add_f32 v[54:55], v[30:31], v[32:33] neg_lo:[0,1] neg_hi:[0,1]
	s_waitcnt lgkmcnt(1)
	v_pk_mul_f32 v[32:33], v[40:41], v[4:5] op_sel_hi:[0,1]
	v_pk_fma_f32 v[56:57], v[40:41], v[2:3], v[32:33] op_sel:[1,0,0] neg_lo:[0,0,1] neg_hi:[0,0,1]
	v_pk_fma_f32 v[32:33], v[40:41], v[2:3], v[32:33] op_sel:[1,0,0]
	v_pk_mul_f32 v[40:41], v[42:43], v[18:19]
	v_mov_b32_e32 v57, v33
	v_pk_fma_f32 v[58:59], v[42:43], v[24:25], v[40:41] op_sel:[1,0,0] op_sel_hi:[0,1,1] neg_lo:[0,0,1] neg_hi:[0,0,1]
	v_pk_fma_f32 v[40:41], v[42:43], v[24:25], v[40:41] op_sel:[1,0,0] op_sel_hi:[0,1,1]
	s_waitcnt lgkmcnt(0)
	v_pk_mul_f32 v[42:43], v[44:45], v[16:17]
	v_mov_b32_e32 v59, v41
	v_pk_fma_f32 v[60:61], v[44:45], v[14:15], v[42:43] op_sel:[1,0,0] op_sel_hi:[0,1,1] neg_lo:[0,0,1] neg_hi:[0,0,1]
	v_pk_fma_f32 v[42:43], v[44:45], v[14:15], v[42:43] op_sel:[1,0,0] op_sel_hi:[0,1,1]
	v_pk_mul_f32 v[44:45], v[46:47], v[26:27]
	v_mov_b32_e32 v42, v60
	v_pk_fma_f32 v[62:63], v[46:47], v[28:29], v[44:45] op_sel:[1,0,0] op_sel_hi:[0,1,1] neg_lo:[0,0,1] neg_hi:[0,0,1]
	v_pk_fma_f32 v[44:45], v[46:47], v[28:29], v[44:45] op_sel:[1,0,0] op_sel_hi:[0,1,1]
	v_mov_b32_e32 v44, v62
	v_pk_add_f32 v[46:47], v[56:57], v[58:59]
	v_mov_b32_e32 v57, v43
	v_mov_b32_e32 v59, v45
	v_pk_mov_b32 v[32:33], v[32:33], v[60:61] op_sel:[1,0]
	v_pk_mov_b32 v[40:41], v[40:41], v[62:63] op_sel:[1,0]
	v_pk_add_f32 v[64:65], v[42:43], v[44:45]
	v_pk_add_f32 v[42:43], v[56:57], v[58:59] neg_lo:[0,1] neg_hi:[0,1]
	v_pk_add_f32 v[56:57], v[32:33], v[40:41] neg_lo:[0,1] neg_hi:[0,1]
	v_add_f32_e32 v32, v42, v43
	v_sub_f32_e32 v33, v56, v57
	v_pk_add_f32 v[38:39], v[50:51], v[38:39]
	v_mov_b32_e32 v30, v52
	v_pk_add_f32 v[44:45], v[46:47], v[64:65] neg_lo:[0,1] neg_hi:[0,1]
	v_sub_f32_e32 v40, v42, v43
	v_mul_f32_e32 v52, 0x3f3504f3, v33
	v_mul_f32_e32 v41, 0x3f3504f3, v32
	v_pk_add_f32 v[48:49], v[36:37], v[38:39] op_sel:[0,1] op_sel_hi:[1,0] neg_lo:[0,1] neg_hi:[0,1]
	v_mov_b32_e32 v31, v55
	v_mul_f32_e32 v32, 0x3f3504f3, v40
	v_pk_add_f32 v[42:43], v[46:47], v[64:65]
	v_pk_add_f32 v[36:37], v[36:37], v[38:39] op_sel:[0,1] op_sel_hi:[1,0]
	v_mov_b32_e32 v55, v53
	v_sub_f32_e32 v40, v52, v41
	v_fmac_f32_e32 v41, 0x3f3504f3, v33
	v_pk_add_f32 v[50:51], v[48:49], v[44:45] neg_lo:[0,1] neg_hi:[0,1]
	v_pk_add_f32 v[44:45], v[48:49], v[44:45]
	v_pk_add_f32 v[48:49], v[56:57], v[56:57] op_sel:[0,1] op_sel_hi:[0,1]
	v_pk_add_f32 v[38:39], v[36:37], v[42:43] op_sel:[0,1] op_sel_hi:[1,0]
	v_pk_add_f32 v[36:37], v[36:37], v[42:43] op_sel:[0,1] op_sel_hi:[1,0] neg_lo:[0,1] neg_hi:[0,1]
	v_pk_add_f32 v[42:43], v[54:55], v[40:41]
	v_pk_fma_f32 v[32:33], v[48:49], s[82:83], v[32:33] op_sel_hi:[1,1,0] neg_lo:[0,0,1] neg_hi:[0,0,1]
	v_pk_add_f32 v[40:41], v[54:55], v[40:41] neg_lo:[0,1] neg_hi:[0,1]
	v_mov_b32_e32 v46, v50
	v_mov_b32_e32 v47, v45
	v_mov_b32_e32 v45, v51
	v_pk_add_f32 v[48:49], v[30:31], v[32:33]
	v_pk_add_f32 v[30:31], v[30:31], v[32:33] neg_lo:[0,1] neg_hi:[0,1]
	ds_write2_b64 v66, v[38:39], v[42:43] offset1:9
	ds_write2_b64 v66, v[46:47], v[48:49] offset0:18 offset1:27
	ds_write2_b64 v66, v[36:37], v[40:41] offset0:36 offset1:45
	ds_write2_b64 v66, v[44:45], v[30:31] offset0:54 offset1:63
	s_cbranch_scc0 .LBB0_681
; #define FFT_HD __device__ __attribute__((always_inline))
; template <int R> FFT_HD inline void reg_inv(cf2 (&v)[1 << R], cf2 th) { tw_apply<R, 1, true>(v, th, th); dft_inv_reg<R>(v); }
; template <int R, int F, bool CONJ> FFT_HD inline void tw_apply(cf2 (&v)[1 << R], cf2 pf, cf2 th) {
;     constexpr int j = fbrev(F, R);
;     v[j] = CONJ ? cmulcf(v[j], pf) : cmulf(v[j], pf);
;     if constexpr (2 * F < (1 << R)) {
;         const cf2 p2 = cmulf(pf, pf);
;         tw_apply<R, 2 * F, CONJ>(v, p2, th);
;         const cf2 p3 = cmulf(p2, th);
;         tw_apply<R, 2 * F + 1, CONJ>(v, p3, th);
;     }
; }
; __device__ __forceinline__ void s_mid2(ldsc X, const cf2* TW, int tid) {
;     ...
; #pragma unroll 1
;     for (int q = 0; q < 2; ++q) { const int grp = tid + 512 * q; cf2 v[16]; grp_load<4, 64>(X, grp, v); reg_inv<4>(v, TW[(grp & 63) * 16]); grp_store<4, 64>(X, grp, v); }
	s_waitcnt lgkmcnt(0)
	s_barrier
	v_mov_b32_e32 v18, v202
	v_mov_b32_e32 v19, v203
	s_mov_b32 s3, 0
	s_mov_b64 s[4:5], -1
	v_pk_mul_f32 v[4:5], v[18:19], v[18:19] op_sel:[0,1] op_sel_hi:[1,0]
	v_mul_f32_e32 v2, v19, v19
	v_pk_add_f32 v[24:25], v[4:5], v[4:5]
	v_pk_fma_f32 v[22:23], v[18:19], v[18:19], v[2:3] op_sel_hi:[1,1,0] neg_lo:[0,0,1] neg_hi:[0,0,1]
	v_pk_mul_f32 v[6:7], v[18:19], v[24:25] op_sel:[1,0] op_sel_hi:[0,1]
	v_pk_mul_f32 v[8:9], v[18:19], v[24:25]
	v_pk_mul_f32 v[4:5], v[22:23], v[24:25]
	v_pk_fma_f32 v[30:31], v[18:19], v[22:23], v[6:7] neg_lo:[0,0,1] neg_hi:[0,0,1]
	v_pk_fma_f32 v[32:33], v[18:19], v[22:23], v[8:9] op_sel:[1,0,0] op_sel_hi:[0,1,1]
	v_pk_mul_f32 v[2:3], v[24:25], v[24:25]
	v_pk_add_f32 v[28:29], v[4:5], v[4:5]
	v_pk_mul_f32 v[12:13], v[30:31], v[32:33]
	v_pk_fma_f32 v[26:27], v[22:23], v[22:23], v[2:3] neg_lo:[0,0,1] neg_hi:[0,0,1]
	v_pk_mul_f32 v[8:9], v[18:19], v[28:29]
	v_pk_mul_f32 v[10:11], v[32:33], v[32:33]
	v_pk_add_f32 v[44:45], v[12:13], v[12:13]
	v_pk_mul_f32 v[2:3], v[28:29], v[28:29]
	v_pk_mul_f32 v[6:7], v[18:19], v[28:29] op_sel:[1,0] op_sel_hi:[0,1]
	v_pk_fma_f32 v[40:41], v[18:19], v[26:27], v[8:9] op_sel:[1,0,0] op_sel_hi:[0,1,1]
	v_pk_fma_f32 v[42:43], v[30:31], v[30:31], v[10:11] neg_lo:[0,0,1] neg_hi:[0,0,1]
	v_pk_mul_f32 v[12:13], v[18:19], v[44:45]
	v_pk_mul_f32 v[4:5], v[26:27], v[28:29]
	v_pk_fma_f32 v[34:35], v[26:27], v[26:27], v[2:3] neg_lo:[0,0,1] neg_hi:[0,0,1]
	v_pk_fma_f32 v[38:39], v[18:19], v[26:27], v[6:7] neg_lo:[0,0,1] neg_hi:[0,0,1]
	v_pk_mul_f32 v[2:3], v[40:41], v[40:41]
	v_pk_mul_f32 v[10:11], v[18:19], v[44:45] op_sel:[1,0] op_sel_hi:[0,1]
	v_pk_fma_f32 v[58:59], v[18:19], v[42:43], v[12:13] op_sel:[1,0,0] op_sel_hi:[0,1,1]
	v_pk_add_f32 v[36:37], v[4:5], v[4:5]
	v_pk_mul_f32 v[4:5], v[38:39], v[40:41]
	v_pk_mul_f32 v[6:7], v[44:45], v[44:45]
	v_pk_fma_f32 v[48:49], v[38:39], v[38:39], v[2:3] neg_lo:[0,0,1] neg_hi:[0,0,1]
	v_pk_fma_f32 v[56:57], v[18:19], v[42:43], v[10:11] neg_lo:[0,0,1] neg_hi:[0,0,1]
	v_pk_mul_f32 v[2:3], v[58:59], v[58:59]
	v_pk_mul_f32 v[8:9], v[42:43], v[44:45]
	v_pk_add_f32 v[50:51], v[4:5], v[4:5]
	v_pk_fma_f32 v[52:53], v[42:43], v[42:43], v[6:7] neg_lo:[0,0,1] neg_hi:[0,0,1]
	v_pk_mul_f32 v[4:5], v[56:57], v[58:59]
	v_pk_fma_f32 v[66:67], v[56:57], v[56:57], v[2:3] neg_lo:[0,0,1] neg_hi:[0,0,1]
	v_mul_f32_e32 v46, v19, v34
	v_mul_f32_e32 v14, v18, v34
	v_pk_add_f32 v[54:55], v[8:9], v[8:9]
	v_mul_f32_e32 v62, v19, v52
	v_mul_f32_e32 v64, v19, v48
	v_mul_f32_e32 v6, v18, v48
	v_mul_f32_e32 v7, v18, v52
	v_pk_add_f32 v[68:69], v[4:5], v[4:5]
	v_mul_f32_e32 v74, v19, v66
	v_mul_f32_e32 v2, v18, v66
	v_fmac_f32_e32 v46, v18, v36
	v_fma_f32 v60, -v19, v36, v14
	v_fmac_f32_e32 v62, v18, v54
	v_fmac_f32_e32 v64, v18, v50
	v_fma_f32 v70, -v19, v50, v6
	v_fma_f32 v72, -v19, v54, v7
	v_fmac_f32_e32 v74, v18, v68
	v_fma_f32 v76, -v19, v68, v2
	v_pk_mov_b32 v[20:21], v[18:19], v[18:19] op_sel:[1,0]
	v_mov_b32_e32 v25, v24
	v_mov_b32_e32 v23, v22
	v_mov_b32_e32 v29, v28
	v_mov_b32_e32 v33, v32
	v_mov_b32_e32 v27, v26
	v_mov_b32_e32 v31, v30
	v_mov_b32_e32 v35, v34
	v_mov_b32_e32 v45, v44
	v_mov_b32_e32 v41, v40
	v_mov_b32_e32 v37, v36
	v_mov_b32_e32 v43, v42
	v_mov_b32_e32 v39, v38
	v_mov_b32_e32 v55, v54
	v_mov_b32_e32 v51, v50
	v_mov_b32_e32 v47, v46
	v_mov_b32_e32 v59, v58
	v_mov_b32_e32 v53, v52
	v_mov_b32_e32 v49, v48
	v_mov_b32_e32 v61, v60
	v_mov_b32_e32 v57, v56
	v_mov_b32_e32 v69, v68
	v_mov_b32_e32 v63, v62
	v_mov_b32_e32 v65, v64
	v_mov_b32_e32 v67, v66
	v_mov_b32_e32 v71, v70
	v_mov_b32_e32 v73, v72
	v_mov_b32_e32 v75, v74
	v_mov_b32_e32 v77, v76
